# K-loop 64-deep full-line LDS-DMA (A double-buffered, B pulled to regs) in moe_up and moe_down phases; inproj tail loads skipped
# speedup vs baseline: 1.2412x; 1.2412x over previous
.LBB0_191:
	s_mul_i32 s0, s13, 0x6000
	s_min_u32 s16, s12, 29
	v_add_u32_e32 v150, s0, v154
	s_lshl_b32 s0, s16, 6
	s_add_u32 s16, s4, s0
	v_readfirstlane_b32 s34, v150
	v_add_u32_e32 v151, 0x1000, v150
	v_add_u32_e32 v152, 0x2000, v150
	v_add_u32_e32 v153, 0x3000, v150
	v_add_u32_e32 v160, 0x4000, v150
	v_add_u32_e32 v150, 0x5000, v150
	s_addc_u32 s17, s5, 0
	v_lshl_add_u64 v[146:147], v[134:135], 0, s[0:1]
	v_lshl_add_u64 v[148:149], v[144:145], 0, s[0:1]
	v_readfirstlane_b32 s0, v151
	v_readfirstlane_b32 s63, v150
	v_lshl_add_u64 v[150:151], s[16:17], 0, v[138:139]
	s_waitcnt vmcnt(6)
	s_cmp_lt_u32 s12, 31
	s_cbranch_scc1 .Ltw0
	s_waitcnt vmcnt(0)
.Ltw0:
	v_readfirstlane_b32 s35, v152
	v_readfirstlane_b32 s61, v153
	v_lshl_add_u64 v[152:153], s[16:17], 0, v[128:129]
	v_lshl_add_u64 v[150:151], v[150:151], 0, s[38:39]
	s_mov_b32 m0, s34
	s_waitcnt lgkmcnt(0)
	s_barrier
	v_lshl_add_u64 v[178:179], s[16:17], 0, v[130:131]
	v_lshl_add_u64 v[152:153], v[152:153], 0, s[38:39]
	s_cmp_ge_u32 s12, 30
	s_cbranch_scc1 .Ltd0_0
	global_load_lds_dwordx4 v[150:151], off
.Ltd0_0:
	s_mov_b32 m0, s0
	v_lshl_add_u64 v[182:183], s[16:17], 0, v[132:133]
	v_lshl_add_u64 v[178:179], v[178:179], 0, s[38:39]
	s_cbranch_scc1 .Ltd0_1
	global_load_lds_dwordx4 v[152:153], off
.Ltd0_1:
	s_mov_b32 m0, s35
	v_readfirstlane_b32 s62, v160
	v_lshl_add_u64 v[182:183], v[182:183], 0, s[38:39]
	s_cbranch_scc1 .Ltd0_2
	global_load_lds_dwordx4 v[178:179], off
.Ltd0_2:
	s_mov_b32 m0, s61
	v_lshl_add_u64 v[146:147], v[146:147], 0, s[38:39]
	s_cbranch_scc1 .Ltd0_3
	global_load_lds_dwordx4 v[182:183], off
.Ltd0_3:
	s_mov_b32 m0, s62
	v_lshl_add_u64 v[148:149], v[148:149], 0, s[38:39]
	s_cbranch_scc1 .Ltd0_4
	global_load_lds_dwordx4 v[146:147], off
.Ltd0_4:
	s_mov_b32 m0, s63
	s_mul_i32 s15, s14, 0x6000
	s_cbranch_scc1 .Ltd0_5
	global_load_lds_dwordx4 v[148:149], off
.Ltd0_5:
	s_add_i32 s15, s15, 0
	v_add_u32_e32 v160, s15, v157
	v_add_u32_e32 v162, v160, v155
	ds_read_b128 v[146:149], v162
	ds_read_b128 v[182:185], v162 offset:2048
	ds_read_b128 v[186:189], v162 offset:4096
	ds_read_b128 v[190:193], v162 offset:6144
	v_add_u32_e32 v161, s15, v158
	v_add_u32_e32 v163, v161, v155
	ds_read_b128 v[150:153], v163 offset:16384
	ds_read_b128 v[194:197], v163 offset:18432
	v_add_u32_e32 v160, v160, v156
	s_waitcnt lgkmcnt(0)
	v_mfma_f32_32x32x16_bf16 v[0:15], v[146:149], v[150:153], v[0:15]
	ds_read_b128 v[198:201], v160
	s_add_i32 s0, s14, 1
	s_cmp_lg_u32 s14, 2
	s_cselect_b32 s14, s0, 0
	s_add_i32 s0, s13, 1
	s_cmp_lg_u32 s13, 2
	s_cselect_b32 s13, s0, 0
	v_mfma_f32_32x32x16_bf16 v[16:31], v[146:149], v[194:197], v[16:31]
	ds_read_b128 v[146:149], v160 offset:2048
	s_add_i32 s12, s12, 1
	s_cmp_eq_u32 s12, 32
	v_mfma_f32_32x32x16_bf16 v[32:47], v[182:185], v[150:153], v[32:47]
	ds_read_b128 v[202:205], v160 offset:4096
	v_mfma_f32_32x32x16_bf16 v[48:63], v[182:185], v[194:197], v[48:63]
	ds_read_b128 v[182:185], v160 offset:6144
	v_add_u32_e32 v160, v161, v156
	v_mfma_f32_32x32x16_bf16 v[64:79], v[186:189], v[150:153], v[64:79]
	ds_read_b128 v[206:209], v160 offset:16384
	v_mfma_f32_32x32x16_bf16 v[80:95], v[186:189], v[194:197], v[80:95]
	ds_read_b128 v[186:189], v160 offset:18432
	v_mfma_f32_32x32x16_bf16 v[96:111], v[190:193], v[150:153], v[96:111]
	v_mfma_f32_32x32x16_bf16 v[112:127], v[190:193], v[194:197], v[112:127]
	s_waitcnt lgkmcnt(0)
	v_mfma_f32_32x32x16_bf16 v[0:15], v[198:201], v[206:209], v[0:15]
	v_mfma_f32_32x32x16_bf16 v[16:31], v[198:201], v[186:189], v[16:31]
	v_mfma_f32_32x32x16_bf16 v[32:47], v[146:149], v[206:209], v[32:47]
	v_mfma_f32_32x32x16_bf16 v[48:63], v[146:149], v[186:189], v[48:63]
	v_mfma_f32_32x32x16_bf16 v[64:79], v[202:205], v[206:209], v[64:79]
	v_mfma_f32_32x32x16_bf16 v[80:95], v[202:205], v[186:189], v[80:95]
	v_mfma_f32_32x32x16_bf16 v[96:111], v[182:185], v[206:209], v[96:111]
	v_mfma_f32_32x32x16_bf16 v[112:127], v[182:185], v[186:189], v[112:127]
	s_cbranch_scc0 .LBB0_191
	s_waitcnt vmcnt(0)
	v_mov_b32_e32 v190, v180
	v_add_u32_e32 v231, 0x400, v159
	v_add_u32_e32 v230, 0x1000, v159
	v_add_u32_e32 v228, 0x1400, v159
	v_add_u32_e32 v227, 0x2000, v159
	v_add_u32_e32 v220, 0x2400, v159
	v_add_u32_e32 v221, 0x3000, v159
	v_add_u32_e32 v222, 0x3200, v159
	v_add_u32_e32 v223, 0x3400, v159
	v_add_u32_e32 v224, 0x3600, v159
	v_add_u32_e32 v225, 0x4000, v159
	v_add_u32_e32 v217, 0x4400, v159
	v_add_u32_e32 v218, 0x4800, v159
	v_add_u32_e32 v219, 0x5000, v159
	v_add_u32_e32 v214, 0x5400, v159
	v_add_u32_e32 v215, 0x5800, v159
	v_add_u32_e32 v216, 0x6000, v159
	v_add_u32_e32 v207, 0x6400, v159
	v_add_u32_e32 v208, 0x6800, v159
	v_add_u32_e32 v209, 0x7200, v159
	v_add_u32_e32 v210, 0x7400, v159
	v_add_u32_e32 v211, 0x7600, v159
	v_add_u32_e32 v212, 0x7800, v159
	v_add_u32_e32 v206, 0x8400, v159
	v_add_u32_e32 v205, 0x8800, v159
	v_add_u32_e32 v204, 0x9400, v159
	v_add_u32_e32 v202, 0x9800, v159
	v_add_u32_e32 v201, 0xa400, v159
	v_add_u32_e32 v196, 0xa800, v159
	v_add_u32_e32 v197, 0xb400, v159
	v_add_u32_e32 v198, 0xb600, v159
	v_add_u32_e32 v199, 0xb800, v159
	v_add_u32_e32 v200, 0xba00, v159
	s_waitcnt vmcnt(0)
	s_barrier
	s_and_saveexec_b64 s[4:5], s[6:7]
	s_cbranch_execz .LBB0_194
	v_add_u32_e32 v128, 0xc400, v159
	ds_write2_b32 v159, v0, v16 offset1:32
	ds_write2_b32 v159, v1, v17 offset0:132 offset1:164
	ds_write2_b32 v231, v2, v18 offset0:8 offset1:40
	ds_write2_b32 v231, v3, v19 offset0:140 offset1:172
	ds_write2_b32 v230, v4, v20 offset0:32 offset1:64
	ds_write2_b32 v230, v5, v21 offset0:164 offset1:196
	ds_write2_b32 v228, v6, v22 offset0:40 offset1:72
	ds_write2_b32 v228, v7, v23 offset0:172 offset1:204
	ds_write2_b32 v227, v8, v24 offset0:64 offset1:96
	ds_write2_b32 v227, v9, v25 offset0:196 offset1:228
	ds_write2_b32 v220, v10, v26 offset0:72 offset1:104
	ds_write2_b32 v220, v11, v27 offset0:204 offset1:236
	ds_write2_b32 v221, v12, v28 offset0:96 offset1:128
	ds_write2_b32 v222, v13, v29 offset0:100 offset1:132
	ds_write2_b32 v223, v14, v30 offset0:104 offset1:136
	ds_write2_b32 v224, v15, v31 offset0:108 offset1:140
	ds_write2_b32 v225, v32, v48 offset0:128 offset1:160
	ds_write2_b32 v217, v33, v49 offset0:4 offset1:36
	ds_write2_b32 v217, v34, v50 offset0:136 offset1:168
	ds_write2_b32 v218, v35, v51 offset0:12 offset1:44
	ds_write2_b32 v219, v36, v52 offset0:160 offset1:192
	ds_write2_b32 v214, v37, v53 offset0:36 offset1:68
	ds_write2_b32 v214, v38, v54 offset0:168 offset1:200
	ds_write2_b32 v215, v39, v55 offset0:44 offset1:76
	ds_write2_b32 v216, v40, v56 offset0:192 offset1:224
	ds_write2_b32 v207, v41, v57 offset0:68 offset1:100
	ds_write2_b32 v207, v42, v58 offset0:200 offset1:232
	ds_write2_b32 v208, v43, v59 offset0:76 offset1:108
	ds_write2_b32 v209, v44, v60 offset0:96 offset1:128
	ds_write2_b32 v210, v45, v61 offset0:100 offset1:132
	ds_write2_b32 v211, v46, v62 offset0:104 offset1:136
	ds_write2_b32 v212, v47, v63 offset0:108 offset1:140
	ds_write2_b32 v206, v64, v80 offset1:32
	ds_write2_b32 v206, v65, v81 offset0:132 offset1:164
	ds_write2_b32 v205, v66, v82 offset0:8 offset1:40
	ds_write2_b32 v205, v67, v83 offset0:140 offset1:172
	ds_write2_b32 v204, v68, v84 offset0:32 offset1:64
	ds_write2_b32 v204, v69, v85 offset0:164 offset1:196
	ds_write2_b32 v202, v70, v86 offset0:40 offset1:72
	ds_write2_b32 v202, v71, v87 offset0:172 offset1:204
	ds_write2_b32 v201, v72, v88 offset0:64 offset1:96
	ds_write2_b32 v201, v73, v89 offset0:196 offset1:228
	ds_write2_b32 v196, v74, v90 offset0:72 offset1:104
	ds_write2_b32 v196, v75, v91 offset0:204 offset1:236
	ds_write2_b32 v197, v76, v92 offset0:96 offset1:128
	ds_write2_b32 v198, v77, v93 offset0:100 offset1:132
	ds_write2_b32 v199, v78, v94 offset0:104 offset1:136
	ds_write2_b32 v200, v79, v95 offset0:108 offset1:140
	ds_write2_b32 v128, v96, v112 offset0:128 offset1:160
	v_add_u32_e32 v128, 0xc800, v159
	ds_write2_b32 v128, v97, v113 offset0:4 offset1:36
	ds_write2_b32 v128, v98, v114 offset0:136 offset1:168
	v_add_u32_e32 v128, 0xcc00, v159
	ds_write2_b32 v128, v99, v115 offset0:12 offset1:44
	v_add_u32_e32 v128, 0xd400, v159
	ds_write2_b32 v128, v100, v116 offset0:160 offset1:192
	v_add_u32_e32 v128, 0xd800, v159
	ds_write2_b32 v128, v101, v117 offset0:36 offset1:68
	ds_write2_b32 v128, v102, v118 offset0:168 offset1:200
	v_add_u32_e32 v128, 0xdc00, v159
	ds_write2_b32 v128, v103, v119 offset0:44 offset1:76
	v_add_u32_e32 v128, 0xe400, v159
	ds_write2_b32 v128, v104, v120 offset0:192 offset1:224
	v_add_u32_e32 v128, 0xe800, v159
	ds_write2_b32 v128, v105, v121 offset0:68 offset1:100
	ds_write2_b32 v128, v106, v122 offset0:200 offset1:232
	v_add_u32_e32 v128, 0xec00, v159
	ds_write2_b32 v128, v107, v123 offset0:76 offset1:108
	v_add_u32_e32 v128, 0xf600, v159
	ds_write2_b32 v128, v108, v124 offset0:96 offset1:128
	v_add_u32_e32 v128, 0xf800, v159
	ds_write2_b32 v128, v109, v125 offset0:100 offset1:132
	v_add_u32_e32 v128, 0xfa00, v159
	ds_write2_b32 v128, v110, v126 offset0:104 offset1:136
	v_add_u32_e32 v128, 0xfc00, v159
	ds_write2_b32 v128, v111, v127 offset0:108 offset1:140

.LBB0_602:
	s_mul_i32 s30, s15, 0x6000
	s_min_i32 s34, s14, 29
	s_mul_i32 s2, s29, 0x6000
	v_add_u32_e32 v130, s30, v148
	s_lshl_b32 s30, s34, 6
	s_mov_b32 s31, s3
	s_add_i32 s34, s2, 0
	s_add_i32 s2, s30, 0x80
	v_readfirstlane_b32 s35, v130
	v_add_u32_e32 v169, 0x1000, v130
	s_waitcnt vmcnt(6)
	s_cmp_lt_u32 s14, 31
	s_cbranch_scc1 .Ltw1
	s_waitcnt vmcnt(0)
.Ltw1:
	v_add_u32_e32 v181, 0x2000, v130
	v_lshl_add_u64 v[170:171], v[136:137], 0, s[30:31]
	v_lshl_add_u64 v[172:173], v[146:147], 0, s[30:31]
	v_lshl_add_u64 v[174:175], v[138:139], 0, s[2:3]
	v_readfirstlane_b32 s30, v169
	s_mov_b32 m0, s35
	s_waitcnt lgkmcnt(0)
	s_barrier
	v_add_u32_e32 v184, 0x3000, v130
	v_lshl_add_u64 v[176:177], v[140:141], 0, s[2:3]
	v_readfirstlane_b32 s31, v181
	s_cmp_ge_u32 s14, 30
	s_cbranch_scc1 .Ltd1_0
	global_load_lds_dwordx4 v[174:175], off
.Ltd1_0:
	s_mov_b32 m0, s30
	v_add_u32_e32 v185, 0x4000, v130
	v_lshl_add_u64 v[178:179], v[142:143], 0, s[2:3]
	v_lshl_add_u64 v[182:183], v[144:145], 0, s[2:3]
	v_readfirstlane_b32 s2, v184
	s_cbranch_scc1 .Ltd1_1
	global_load_lds_dwordx4 v[176:177], off
.Ltd1_1:
	s_mov_b32 m0, s31
	v_add_u32_e32 v130, 0x5000, v130
	v_add_u32_e32 v198, s34, v151
	v_add_u32_e32 v206, s34, v152
	v_readfirstlane_b32 s34, v185
	s_cbranch_scc1 .Ltd1_2
	global_load_lds_dwordx4 v[178:179], off
.Ltd1_2:
	s_mov_b32 m0, s2
	v_lshl_add_u64 v[170:171], v[170:171], 0, s[12:13]
	v_readfirstlane_b32 s36, v130
	s_cbranch_scc1 .Ltd1_3
	global_load_lds_dwordx4 v[182:183], off
.Ltd1_3:
	s_mov_b32 m0, s34
	v_lshl_add_u64 v[172:173], v[172:173], 0, s[12:13]
	s_cbranch_scc1 .Ltd1_4
	global_load_lds_dwordx4 v[170:171], off
.Ltd1_4:
	s_mov_b32 m0, s36
	v_add_u32_e32 v130, v198, v149
	s_cbranch_scc1 .Ltd1_5
	global_load_lds_dwordx4 v[172:173], off
.Ltd1_5:
	ds_read_b128 v[170:173], v130
	ds_read_b128 v[182:185], v130 offset:2048
	ds_read_b128 v[186:189], v130 offset:4096
	ds_read_b128 v[190:193], v130 offset:6144
	v_add_u32_e32 v169, v206, v149
	ds_read_b128 v[174:177], v169 offset:16384
	ds_read_b128 v[194:197], v169 offset:18432
	v_add_u32_e32 v130, v198, v150
	s_waitcnt lgkmcnt(0)
	v_mfma_f32_32x32x16_bf16 v[0:15], v[170:173], v[174:177], v[0:15]
	ds_read_b128 v[198:201], v130
	s_add_i32 s2, s29, 1
	s_cmp_lg_u32 s29, 2
	s_cselect_b32 s29, s2, 0
	s_add_i32 s2, s15, 1
	s_cmp_lg_u32 s15, 2
	s_cselect_b32 s15, s2, 0
	v_mfma_f32_32x32x16_bf16 v[16:31], v[170:173], v[194:197], v[16:31]
	ds_read_b128 v[170:173], v130 offset:2048
	s_add_i32 s14, s14, 1
	s_cmp_eq_u32 s14, 32
	v_mfma_f32_32x32x16_bf16 v[32:47], v[182:185], v[174:177], v[32:47]
	ds_read_b128 v[202:205], v130 offset:4096
	v_mfma_f32_32x32x16_bf16 v[48:63], v[182:185], v[194:197], v[48:63]
	ds_read_b128 v[182:185], v130 offset:6144
	v_add_u32_e32 v130, v206, v150
	v_mfma_f32_32x32x16_bf16 v[64:79], v[186:189], v[174:177], v[64:79]
	ds_read_b128 v[206:209], v130 offset:16384
	v_mfma_f32_32x32x16_bf16 v[80:95], v[186:189], v[194:197], v[80:95]
	ds_read_b128 v[186:189], v130 offset:18432
	v_mfma_f32_32x32x16_bf16 v[96:111], v[190:193], v[174:177], v[96:111]
	v_mfma_f32_32x32x16_bf16 v[112:127], v[190:193], v[194:197], v[112:127]
	s_waitcnt lgkmcnt(0)
	v_mfma_f32_32x32x16_bf16 v[0:15], v[198:201], v[206:209], v[0:15]
	v_mfma_f32_32x32x16_bf16 v[16:31], v[198:201], v[186:189], v[16:31]
	v_mfma_f32_32x32x16_bf16 v[32:47], v[170:173], v[206:209], v[32:47]
	v_mfma_f32_32x32x16_bf16 v[48:63], v[170:173], v[186:189], v[48:63]
	v_mfma_f32_32x32x16_bf16 v[64:79], v[202:205], v[206:209], v[64:79]
	v_mfma_f32_32x32x16_bf16 v[80:95], v[202:205], v[186:189], v[80:95]
	v_mfma_f32_32x32x16_bf16 v[96:111], v[182:185], v[206:209], v[96:111]
	v_mfma_f32_32x32x16_bf16 v[112:127], v[182:185], v[186:189], v[112:127]
	s_cbranch_scc0 .LBB0_602
	s_waitcnt vmcnt(0)
	v_mov_b32_e32 v130, v180
	v_add_u32_e32 v201, 0x400, v153
	v_add_u32_e32 v200, 0x1000, v153
	v_add_u32_e32 v199, 0x1400, v153
	v_add_u32_e32 v198, 0x2000, v153
	v_add_u32_e32 v192, 0x2400, v153
	v_add_u32_e32 v193, 0x3000, v153
	v_add_u32_e32 v194, 0x3200, v153
	v_add_u32_e32 v195, 0x3400, v153
	v_add_u32_e32 v196, 0x3600, v153
	v_add_u32_e32 v197, 0x4000, v153
	v_add_u32_e32 v189, 0x4400, v153
	v_add_u32_e32 v190, 0x4800, v153
	v_add_u32_e32 v191, 0x5000, v153
	v_add_u32_e32 v186, 0x5400, v153
	v_add_u32_e32 v187, 0x5800, v153
	v_add_u32_e32 v188, 0x6000, v153
	v_add_u32_e32 v179, 0x6400, v153
	v_add_u32_e32 v181, 0x6800, v153
	v_add_u32_e32 v182, 0x7200, v153
	v_add_u32_e32 v183, 0x7400, v153
	v_add_u32_e32 v184, 0x7600, v153
	v_add_u32_e32 v185, 0x7800, v153
	v_add_u32_e32 v178, 0x8400, v153
	v_add_u32_e32 v177, 0x8800, v153
	v_add_u32_e32 v176, 0x9400, v153
	v_add_u32_e32 v175, 0x9800, v153
	v_add_u32_e32 v174, 0xa400, v153
	v_add_u32_e32 v147, 0xa800, v153
	v_add_u32_e32 v169, 0xb400, v153
	v_add_u32_e32 v170, 0xb600, v153
	v_add_u32_e32 v171, 0xb800, v153
	v_add_u32_e32 v172, 0xba00, v153
	s_waitcnt vmcnt(0)
	s_barrier
	s_and_saveexec_b64 s[14:15], s[6:7]
	s_cbranch_execz .LBB0_605
	v_add_u32_e32 v136, 0xc400, v153
	ds_write2_b32 v153, v0, v16 offset1:32
	ds_write2_b32 v153, v1, v17 offset0:132 offset1:164
	ds_write2_b32 v201, v2, v18 offset0:8 offset1:40
	ds_write2_b32 v201, v3, v19 offset0:140 offset1:172
	ds_write2_b32 v200, v4, v20 offset0:32 offset1:64
	ds_write2_b32 v200, v5, v21 offset0:164 offset1:196
	ds_write2_b32 v199, v6, v22 offset0:40 offset1:72
	ds_write2_b32 v199, v7, v23 offset0:172 offset1:204
	ds_write2_b32 v198, v8, v24 offset0:64 offset1:96
	ds_write2_b32 v198, v9, v25 offset0:196 offset1:228
	ds_write2_b32 v192, v10, v26 offset0:72 offset1:104
	ds_write2_b32 v192, v11, v27 offset0:204 offset1:236
	ds_write2_b32 v193, v12, v28 offset0:96 offset1:128
	ds_write2_b32 v194, v13, v29 offset0:100 offset1:132
	ds_write2_b32 v195, v14, v30 offset0:104 offset1:136
	ds_write2_b32 v196, v15, v31 offset0:108 offset1:140
	ds_write2_b32 v197, v32, v48 offset0:128 offset1:160
	ds_write2_b32 v189, v33, v49 offset0:4 offset1:36
	ds_write2_b32 v189, v34, v50 offset0:136 offset1:168
	ds_write2_b32 v190, v35, v51 offset0:12 offset1:44
	ds_write2_b32 v191, v36, v52 offset0:160 offset1:192
	ds_write2_b32 v186, v37, v53 offset0:36 offset1:68
	ds_write2_b32 v186, v38, v54 offset0:168 offset1:200
	ds_write2_b32 v187, v39, v55 offset0:44 offset1:76
	ds_write2_b32 v188, v40, v56 offset0:192 offset1:224
	ds_write2_b32 v179, v41, v57 offset0:68 offset1:100
	ds_write2_b32 v179, v42, v58 offset0:200 offset1:232
	ds_write2_b32 v181, v43, v59 offset0:76 offset1:108
	ds_write2_b32 v182, v44, v60 offset0:96 offset1:128
	ds_write2_b32 v183, v45, v61 offset0:100 offset1:132
	ds_write2_b32 v184, v46, v62 offset0:104 offset1:136
	ds_write2_b32 v185, v47, v63 offset0:108 offset1:140
	ds_write2_b32 v178, v64, v80 offset1:32
	ds_write2_b32 v178, v65, v81 offset0:132 offset1:164
	ds_write2_b32 v177, v66, v82 offset0:8 offset1:40
	ds_write2_b32 v177, v67, v83 offset0:140 offset1:172
	ds_write2_b32 v176, v68, v84 offset0:32 offset1:64
	ds_write2_b32 v176, v69, v85 offset0:164 offset1:196
	ds_write2_b32 v175, v70, v86 offset0:40 offset1:72
	ds_write2_b32 v175, v71, v87 offset0:172 offset1:204
	ds_write2_b32 v174, v72, v88 offset0:64 offset1:96
	ds_write2_b32 v174, v73, v89 offset0:196 offset1:228
	ds_write2_b32 v147, v74, v90 offset0:72 offset1:104
	ds_write2_b32 v147, v75, v91 offset0:204 offset1:236
	ds_write2_b32 v169, v76, v92 offset0:96 offset1:128
	ds_write2_b32 v170, v77, v93 offset0:100 offset1:132
	ds_write2_b32 v171, v78, v94 offset0:104 offset1:136
	ds_write2_b32 v172, v79, v95 offset0:108 offset1:140
	ds_write2_b32 v136, v96, v112 offset0:128 offset1:160
	v_add_u32_e32 v136, 0xc800, v153
	ds_write2_b32 v136, v97, v113 offset0:4 offset1:36
	ds_write2_b32 v136, v98, v114 offset0:136 offset1:168
	v_add_u32_e32 v136, 0xcc00, v153
	ds_write2_b32 v136, v99, v115 offset0:12 offset1:44
	v_add_u32_e32 v136, 0xd400, v153
	ds_write2_b32 v136, v100, v116 offset0:160 offset1:192
	v_add_u32_e32 v136, 0xd800, v153
	ds_write2_b32 v136, v101, v117 offset0:36 offset1:68
	ds_write2_b32 v136, v102, v118 offset0:168 offset1:200
	v_add_u32_e32 v136, 0xdc00, v153
	ds_write2_b32 v136, v103, v119 offset0:44 offset1:76
	v_add_u32_e32 v136, 0xe400, v153
	ds_write2_b32 v136, v104, v120 offset0:192 offset1:224
	v_add_u32_e32 v136, 0xe800, v153
	ds_write2_b32 v136, v105, v121 offset0:68 offset1:100
	ds_write2_b32 v136, v106, v122 offset0:200 offset1:232
	v_add_u32_e32 v136, 0xec00, v153
	ds_write2_b32 v136, v107, v123 offset0:76 offset1:108
	v_add_u32_e32 v136, 0xf600, v153
	ds_write2_b32 v136, v108, v124 offset0:96 offset1:128
	v_add_u32_e32 v136, 0xf800, v153
	ds_write2_b32 v136, v109, v125 offset0:100 offset1:132
	v_add_u32_e32 v136, 0xfa00, v153
	ds_write2_b32 v136, v110, v126 offset0:104 offset1:136
	v_add_u32_e32 v136, 0xfc00, v153
	ds_write2_b32 v136, v111, v127 offset0:108 offset1:140

.LBB0_955:
	s_lshr_b32 s10, s19, 4
	s_and_b32 s10, s10, 12
	s_bfe_u32 s28, s19, 0x20001
	s_or_b32 s10, s10, s20
	s_lshl_b32 s14, s28, 4
	s_and_b32 s26, s19, 1
	s_or_b32 s27, s14, s10
	s_lshl_b32 s14, s27, 9
	s_lshl_b32 s15, s26, 8
	s_or_b32 s14, s14, s15
	v_or_b32_e32 v0, s14, v146
	v_lshlrev_b32_e32 v0, 2, v0
	global_load_dword v2, v0, s[2:3]
	global_load_dword v4, v0, s[2:3] offset:256
	global_load_dword v10, v0, s[2:3] offset:512
	global_load_dword v11, v0, s[2:3] offset:768
	s_lshl_b32 s44, s28, 22
	v_readfirstlane_b32 s30, v148
	s_bfe_u32 s29, s19, 0x30003
	v_readfirstlane_b32 s31, v154
	s_mov_b32 m0, s30
	v_readfirstlane_b32 s34, v155
	s_or_b32 s28, s29, s21
	s_waitcnt vmcnt(0)
	s_barrier
	v_readfirstlane_b32 s35, v156
	s_lshl_b32 s29, s28, 17
	s_lshl_b32 s10, s10, 21
	v_readfirstlane_b32 s36, v157
	s_or_b32 s10, s10, s29
	v_readfirstlane_b32 s37, v158
	v_lshl_add_u64 v[134:135], v[130:131], 0, s[10:11]
	v_mov_b32_e32 v1, v129
	v_readfirstlane_b32 s38, v159
	v_lshl_add_u64 v[136:137], v[132:133], 0, s[10:11]
	v_mov_b32_e32 v3, v129
	v_readfirstlane_b32 s39, v160
	v_mov_b32_e32 v5, v129
	v_readfirstlane_b32 s40, v161
	v_readfirstlane_b32 s41, v162
	v_readfirstlane_b32 s42, v163
	v_readfirstlane_b32 s43, v164
	v_lshl_add_u64 v[6:7], v[134:135], 0, 64
	v_lshl_add_u64 v[8:9], v[136:137], 0, 64
	s_mov_b32 s14, s11
	s_mov_b32 s15, 2
	s_mov_b32 s29, s11
	v_mov_b32_e32 v16, 0
	v_mov_b32_e32 v17, v129
	v_mov_b32_e32 v18, v129
	v_mov_b32_e32 v19, v129
	v_mov_b32_e32 v20, v129
	v_mov_b32_e32 v21, v129
	v_mov_b32_e32 v22, v129
	v_mov_b32_e32 v23, v129
	v_mov_b32_e32 v24, v129
	v_mov_b32_e32 v25, v129
	v_mov_b32_e32 v26, v129
	v_mov_b32_e32 v27, v129
	v_mov_b32_e32 v28, v129
	v_mov_b32_e32 v29, v129
	v_mov_b32_e32 v30, v129
	v_mov_b32_e32 v31, v129
	v_mov_b32_e32 v32, 0
	v_mov_b32_e32 v33, v129
	v_mov_b32_e32 v34, v129
	v_mov_b32_e32 v35, v129
	v_mov_b32_e32 v36, v129
	v_mov_b32_e32 v37, v129
	v_mov_b32_e32 v38, v129
	v_mov_b32_e32 v39, v129
	v_mov_b32_e32 v40, v129
	v_mov_b32_e32 v41, v129
	v_mov_b32_e32 v42, v129
	v_mov_b32_e32 v43, v129
	v_mov_b32_e32 v44, v129
	v_mov_b32_e32 v45, v129
	v_mov_b32_e32 v46, v129
	v_mov_b32_e32 v47, v129
	v_mov_b32_e32 v48, 0
	v_mov_b32_e32 v49, v129
	v_mov_b32_e32 v50, v129
	v_mov_b32_e32 v51, v129
	v_mov_b32_e32 v52, v129
	v_mov_b32_e32 v53, v129
	v_mov_b32_e32 v54, v129
	v_mov_b32_e32 v55, v129
	v_mov_b32_e32 v56, v129
	v_mov_b32_e32 v57, v129
	v_mov_b32_e32 v58, v129
	s_waitcnt vmcnt(3)
	v_lshl_add_u32 v0, v2, 10, s44
	s_waitcnt vmcnt(2)
	v_lshl_add_u32 v2, v4, 10, s44
	v_or_b32_e32 v0, v0, v147
	s_waitcnt vmcnt(1)
	v_lshl_add_u32 v4, v10, 10, s44
	v_or_b32_e32 v2, v2, v147
	v_lshlrev_b32_e32 v128, 1, v0
	s_waitcnt vmcnt(0)
	v_lshl_add_u32 v10, v11, 10, s44
	v_or_b32_e32 v4, v4, v147
	v_lshlrev_b32_e32 v0, 1, v2
	s_nop 0
	s_mov_b32 m0, s31
	v_or_b32_e32 v10, v10, v147
	v_lshlrev_b32_e32 v2, 1, v4
	s_nop 0
	s_mov_b32 m0, s34
	v_lshlrev_b32_e32 v4, 1, v10
	s_nop 0
	s_mov_b32 m0, s35
	v_lshl_add_u64 v[138:139], s[4:5], 0, v[128:129]
	s_nop 0
	s_mov_b32 m0, s36
	v_lshl_add_u64 v[140:141], s[4:5], 0, v[0:1]
	s_nop 0
	s_mov_b32 m0, s37
	v_lshl_add_u64 v[0:1], v[138:139], 0, 64
	s_nop 0
	s_mov_b32 m0, s38
	v_lshl_add_u64 v[142:143], s[4:5], 0, v[2:3]
	v_lshl_add_u64 v[10:11], v[140:141], 0, 64
	s_nop 0
	s_mov_b32 m0, s39
	v_lshl_add_u64 v[144:145], s[4:5], 0, v[4:5]
	v_lshl_add_u64 v[12:13], v[142:143], 0, 64
	s_nop 0
	s_mov_b32 m0, s40
	v_lshl_add_u64 v[14:15], v[144:145], 0, 64
	s_nop 0
	s_mov_b32 m0, s41
	v_mov_b32_e32 v0, 0
	s_nop 0
	s_mov_b32 m0, s42
	v_mov_b32_e32 v1, v129
	s_nop 0
	s_mov_b32 m0, s43
	v_mov_b32_e32 v2, v129
	s_nop 0
	v_mov_b32_e32 v4, v129
	v_mov_b32_e32 v6, v129
	v_mov_b32_e32 v7, v129
	v_mov_b32_e32 v8, v129
	v_mov_b32_e32 v9, v129
	v_mov_b32_e32 v10, v129
	v_mov_b32_e32 v11, v129
	v_mov_b32_e32 v12, v129
	v_mov_b32_e32 v13, v129
	v_mov_b32_e32 v14, v129
	v_mov_b32_e32 v15, v129
	v_mov_b32_e32 v59, v129
	v_mov_b32_e32 v60, v129
	v_mov_b32_e32 v61, v129
	v_mov_b32_e32 v62, v129
	v_mov_b32_e32 v63, v129
	v_mov_b32_e32 v64, 0
	v_mov_b32_e32 v65, v129
	v_mov_b32_e32 v66, v129
	v_mov_b32_e32 v67, v129
	v_mov_b32_e32 v68, v129
	v_mov_b32_e32 v69, v129
	v_mov_b32_e32 v70, v129
	v_mov_b32_e32 v71, v129
	v_mov_b32_e32 v72, v129
	v_mov_b32_e32 v73, v129
	v_mov_b32_e32 v74, v129
	v_mov_b32_e32 v75, v129
	v_mov_b32_e32 v76, v129
	v_mov_b32_e32 v77, v129
	v_mov_b32_e32 v78, v129
	v_mov_b32_e32 v79, v129
	v_mov_b32_e32 v80, 0
	v_mov_b32_e32 v81, v129
	v_mov_b32_e32 v82, v129
	v_mov_b32_e32 v83, v129
	v_mov_b32_e32 v84, v129
	v_mov_b32_e32 v85, v129
	v_mov_b32_e32 v86, v129
	v_mov_b32_e32 v87, v129
	v_mov_b32_e32 v88, v129
	v_mov_b32_e32 v89, v129
	v_mov_b32_e32 v90, v129
	v_mov_b32_e32 v91, v129
	v_mov_b32_e32 v92, v129
	v_mov_b32_e32 v93, v129
	v_mov_b32_e32 v94, v129
	v_mov_b32_e32 v95, v129
	v_mov_b32_e32 v96, 0
	v_mov_b32_e32 v97, v129
	v_mov_b32_e32 v98, v129
	v_mov_b32_e32 v99, v129
	v_mov_b32_e32 v100, v129
	v_mov_b32_e32 v101, v129
	v_mov_b32_e32 v102, v129
	v_mov_b32_e32 v103, v129
	v_mov_b32_e32 v104, v129
	v_mov_b32_e32 v105, v129
	v_mov_b32_e32 v106, v129
	v_mov_b32_e32 v107, v129
	v_mov_b32_e32 v108, v129
	v_mov_b32_e32 v109, v129
	v_mov_b32_e32 v110, v129
	v_mov_b32_e32 v111, v129
	v_mov_b32_e32 v112, 0
	v_mov_b32_e32 v113, v129
	v_mov_b32_e32 v114, v129
	v_mov_b32_e32 v115, v129
	v_mov_b32_e32 v116, v129
	v_mov_b32_e32 v117, v129
	v_mov_b32_e32 v118, v129
	v_mov_b32_e32 v119, v129
	v_mov_b32_e32 v120, v129
	v_mov_b32_e32 v121, v129
	v_mov_b32_e32 v122, v129
	v_mov_b32_e32 v123, v129
	v_mov_b32_e32 v124, v129
	v_mov_b32_e32 v125, v129
	v_mov_b32_e32 v126, v129
	v_mov_b32_e32 v127, v129
	s_mov_b64 s[54:55], 0x80
	v_lshrrev_b32_e32 v170, 6, v180
	v_lshlrev_b32_e32 v176, 11, v170
	v_mov_b32_e32 v171, 0x12000
	ds_read_b64 v[172:173], v171
	v_and_b32_e32 v166, 63, v180
	v_readfirstlane_b32 s53, v176
	v_lshrrev_b32_e32 v167, 5, v166
	v_bfe_u32 v168, v166, 1, 3
	v_xor_b32_e32 v168, v167, v168
	v_and_b32_e32 v169, 31, v166
	v_lshlrev_b32_e32 v169, 7, v169
	v_lshrrev_b32_e32 v169, 3, v166
	v_lshlrev_b32_e32 v176, 4, v169
	v_add_u32_e32 v177, 0x80, v176
	v_and_b32_e32 v169, 7, v166
	v_lshrrev_b32_e32 v167, 4, v166
	v_xor_b32_e32 v167, v169, v167
	v_lshrrev_b32_e32 v169, 5, v166
	v_sub_u32_e32 v182, v167, v169
	v_xor_b32_e32 v167, 4, v167
	v_add_u32_e32 v169, 2, v169
	v_sub_u32_e32 v184, v167, v169
	v_lshlrev_b32_e32 v182, 4, v182
	v_ashrrev_i32_e32 v183, 31, v182
	v_lshlrev_b32_e32 v184, 4, v184
	v_ashrrev_i32_e32 v185, 31, v184
	ds_bpermute_b32 v242, v176, v134
	ds_bpermute_b32 v243, v176, v135
	ds_bpermute_b32 v244, v177, v134
	ds_bpermute_b32 v245, v177, v135
	ds_bpermute_b32 v246, v176, v136
	ds_bpermute_b32 v247, v176, v137
	ds_bpermute_b32 v248, v177, v136
	ds_bpermute_b32 v249, v177, v137
	s_waitcnt lgkmcnt(0)
	ds_bpermute_b32 v178, v176, v138
	ds_bpermute_b32 v179, v176, v139
	ds_bpermute_b32 v232, v177, v138
	ds_bpermute_b32 v233, v177, v139
	ds_bpermute_b32 v234, v176, v140
	ds_bpermute_b32 v235, v176, v141
	ds_bpermute_b32 v236, v177, v140
	ds_bpermute_b32 v237, v177, v141
	ds_bpermute_b32 v238, v176, v142
	ds_bpermute_b32 v239, v176, v143
	ds_bpermute_b32 v240, v177, v142
	ds_bpermute_b32 v241, v177, v143
	ds_bpermute_b32 v134, v176, v144
	ds_bpermute_b32 v135, v176, v145
	ds_bpermute_b32 v136, v177, v144
	ds_bpermute_b32 v137, v177, v145
	s_waitcnt lgkmcnt(0)
	v_readfirstlane_b32 s56, v172
	v_readfirstlane_b32 s57, v173
	v_and_b32_e32 v169, 31, v166
	v_lshlrev_b32_e32 v169, 7, v169
	v_lshrrev_b32_e32 v167, 1, v170
	v_lshl_add_u32 v138, v167, 14, v169
	v_and_b32_e32 v167, 1, v170
	v_lshl_add_u32 v142, v167, 13, v169
	v_add_u32_e32 v142, 0x10000, v142
	v_xor_b32_e32 v169, 6, v168
	v_lshl_add_u32 v141, v169, 4, v138
	v_lshl_add_u32 v145, v169, 4, v142
	v_xor_b32_e32 v169, 4, v168
	v_lshl_add_u32 v140, v169, 4, v138
	v_lshl_add_u32 v144, v169, 4, v142
	v_xor_b32_e32 v169, 2, v168
	v_lshl_add_u32 v139, v169, 4, v138
	v_lshl_add_u32 v143, v169, 4, v142
	v_xor_b32_e32 v169, 0, v168
	v_lshl_add_u32 v138, v169, 4, v138
	v_lshl_add_u32 v142, v169, 4, v142
	v_lshl_add_u64 v[178:179], v[178:179], 0, v[182:183]
	v_lshl_add_u64 v[232:233], v[232:233], 0, v[184:185]
	v_lshl_add_u64 v[234:235], v[234:235], 0, v[182:183]
	v_lshl_add_u64 v[236:237], v[236:237], 0, v[184:185]
	v_lshl_add_u64 v[238:239], v[238:239], 0, v[182:183]
	v_lshl_add_u64 v[240:241], v[240:241], 0, v[184:185]
	v_lshl_add_u64 v[134:135], v[134:135], 0, v[182:183]
	v_lshl_add_u64 v[136:137], v[136:137], 0, v[184:185]
	v_lshl_add_u64 v[242:243], v[242:243], 0, v[182:183]
	v_lshl_add_u64 v[244:245], v[244:245], 0, v[184:185]
	v_lshl_add_u64 v[246:247], v[246:247], 0, v[182:183]
	v_lshl_add_u64 v[248:249], v[248:249], 0, v[184:185]
	s_mov_b32 s58, s53
	s_add_i32 m0, s58, 0x0
	s_nop 0
	global_load_lds_dwordx4 v[178:179], off
	s_add_i32 m0, s58, 0x400
	v_lshl_add_u64 v[178:179], v[178:179], 0, s[54:55]
	global_load_lds_dwordx4 v[232:233], off
	s_add_i32 m0, s58, 0x2000
	v_lshl_add_u64 v[232:233], v[232:233], 0, s[54:55]
	global_load_lds_dwordx4 v[234:235], off
	s_add_i32 m0, s58, 0x2400
	v_lshl_add_u64 v[234:235], v[234:235], 0, s[54:55]
	global_load_lds_dwordx4 v[236:237], off
	s_add_i32 m0, s58, 0x4000
	v_lshl_add_u64 v[236:237], v[236:237], 0, s[54:55]
	global_load_lds_dwordx4 v[238:239], off
	s_add_i32 m0, s58, 0x4400
	v_lshl_add_u64 v[238:239], v[238:239], 0, s[54:55]
	global_load_lds_dwordx4 v[240:241], off
	s_add_i32 m0, s58, 0x6000
	v_lshl_add_u64 v[240:241], v[240:241], 0, s[54:55]
	global_load_lds_dwordx4 v[134:135], off
	s_add_i32 m0, s58, 0x6400
	v_lshl_add_u64 v[134:135], v[134:135], 0, s[54:55]
	global_load_lds_dwordx4 v[136:137], off
	v_lshl_add_u64 v[136:137], v[136:137], 0, s[54:55]
	s_add_i32 s58, s53, 0x10000
	s_add_i32 m0, s58, 0x0
	s_nop 0
	global_load_lds_dwordx4 v[242:243], off
	s_add_i32 m0, s58, 0x400
	v_lshl_add_u64 v[242:243], v[242:243], 0, s[54:55]
	global_load_lds_dwordx4 v[244:245], off
	s_add_i32 m0, s58, 0x2000
	v_lshl_add_u64 v[244:245], v[244:245], 0, s[54:55]
	global_load_lds_dwordx4 v[246:247], off
	s_add_i32 m0, s58, 0x2400
	v_lshl_add_u64 v[246:247], v[246:247], 0, s[54:55]
	global_load_lds_dwordx4 v[248:249], off
	v_lshl_add_u64 v[248:249], v[248:249], 0, s[54:55]
	s_mov_b32 s14, 0
	s_mov_b32 s15, 0
.Lg_ph8_top:
	s_waitcnt vmcnt(0)
	s_waitcnt lgkmcnt(0)
	s_barrier
	s_cmp_eq_u32 s14, 15
	s_cbranch_scc1 .Lg_ph8_noA
	s_xor_b32 s58, s15, 0x8000
	s_add_i32 s58, s58, s53
	s_add_i32 m0, s58, 0x0
	s_nop 0
	global_load_lds_dwordx4 v[178:179], off
	s_add_i32 m0, s58, 0x400
	v_lshl_add_u64 v[178:179], v[178:179], 0, s[54:55]
	global_load_lds_dwordx4 v[232:233], off
	s_add_i32 m0, s58, 0x2000
	v_lshl_add_u64 v[232:233], v[232:233], 0, s[54:55]
	global_load_lds_dwordx4 v[234:235], off
	s_add_i32 m0, s58, 0x2400
	v_lshl_add_u64 v[234:235], v[234:235], 0, s[54:55]
	global_load_lds_dwordx4 v[236:237], off
	s_add_i32 m0, s58, 0x4000
	v_lshl_add_u64 v[236:237], v[236:237], 0, s[54:55]
	global_load_lds_dwordx4 v[238:239], off
	s_add_i32 m0, s58, 0x4400
	v_lshl_add_u64 v[238:239], v[238:239], 0, s[54:55]
	global_load_lds_dwordx4 v[240:241], off
	s_add_i32 m0, s58, 0x6000
	v_lshl_add_u64 v[240:241], v[240:241], 0, s[54:55]
	global_load_lds_dwordx4 v[134:135], off
	s_add_i32 m0, s58, 0x6400
	v_lshl_add_u64 v[134:135], v[134:135], 0, s[54:55]
	global_load_lds_dwordx4 v[136:137], off
	v_lshl_add_u64 v[136:137], v[136:137], 0, s[54:55]
.Lg_ph8_noA:
	ds_read_b128 v[190:193], v142
	ds_read_b128 v[194:197], v142 offset:4096
	ds_read_b128 v[198:201], v143
	ds_read_b128 v[202:205], v143 offset:4096
	ds_read_b128 v[206:209], v144
	ds_read_b128 v[220:223], v144 offset:4096
	ds_read_b128 v[224:227], v145
	ds_read_b128 v[228:231], v145 offset:4096
	ds_read_b128 v[166:169], v138
	ds_read_b128 v[170:173], v138 offset:4096
	ds_read_b128 v[174:177], v138 offset:8192
	ds_read_b128 v[182:185], v138 offset:12288
	s_waitcnt lgkmcnt(4)
	s_barrier
	s_cmp_eq_u32 s14, 15
	s_cbranch_scc1 .Lg_ph8_noB
	s_add_i32 s58, s53, 0x10000
	s_add_i32 m0, s58, 0x0
	s_nop 0
	global_load_lds_dwordx4 v[242:243], off
	s_add_i32 m0, s58, 0x400
	v_lshl_add_u64 v[242:243], v[242:243], 0, s[54:55]
	global_load_lds_dwordx4 v[244:245], off
	s_add_i32 m0, s58, 0x2000
	v_lshl_add_u64 v[244:245], v[244:245], 0, s[54:55]
	global_load_lds_dwordx4 v[246:247], off
	s_add_i32 m0, s58, 0x2400
	v_lshl_add_u64 v[246:247], v[246:247], 0, s[54:55]
	global_load_lds_dwordx4 v[248:249], off
	v_lshl_add_u64 v[248:249], v[248:249], 0, s[54:55]
.Lg_ph8_noB:
	s_waitcnt lgkmcnt(3)
	v_mfma_f32_32x32x16_bf16 v[0:15], v[166:169], v[190:193], v[0:15]
	v_mfma_f32_32x32x16_bf16 v[16:31], v[166:169], v[194:197], v[16:31]
	ds_read_b128 v[166:169], v139
	s_waitcnt lgkmcnt(3)
	v_mfma_f32_32x32x16_bf16 v[32:47], v[170:173], v[190:193], v[32:47]
	v_mfma_f32_32x32x16_bf16 v[48:63], v[170:173], v[194:197], v[48:63]
	ds_read_b128 v[170:173], v139 offset:4096
	s_waitcnt lgkmcnt(3)
	v_mfma_f32_32x32x16_bf16 v[64:79], v[174:177], v[190:193], v[64:79]
	v_mfma_f32_32x32x16_bf16 v[80:95], v[174:177], v[194:197], v[80:95]
	ds_read_b128 v[174:177], v139 offset:8192
	s_waitcnt lgkmcnt(3)
	v_mfma_f32_32x32x16_bf16 v[96:111], v[182:185], v[190:193], v[96:111]
	v_mfma_f32_32x32x16_bf16 v[112:127], v[182:185], v[194:197], v[112:127]
	ds_read_b128 v[182:185], v139 offset:12288
	s_waitcnt lgkmcnt(3)
	v_mfma_f32_32x32x16_bf16 v[0:15], v[166:169], v[198:201], v[0:15]
	v_mfma_f32_32x32x16_bf16 v[16:31], v[166:169], v[202:205], v[16:31]
	ds_read_b128 v[166:169], v140
	s_waitcnt lgkmcnt(3)
	v_mfma_f32_32x32x16_bf16 v[32:47], v[170:173], v[198:201], v[32:47]
	v_mfma_f32_32x32x16_bf16 v[48:63], v[170:173], v[202:205], v[48:63]
	ds_read_b128 v[170:173], v140 offset:4096
	s_waitcnt lgkmcnt(3)
	v_mfma_f32_32x32x16_bf16 v[64:79], v[174:177], v[198:201], v[64:79]
	v_mfma_f32_32x32x16_bf16 v[80:95], v[174:177], v[202:205], v[80:95]
	ds_read_b128 v[174:177], v140 offset:8192
	s_waitcnt lgkmcnt(3)
	v_mfma_f32_32x32x16_bf16 v[96:111], v[182:185], v[198:201], v[96:111]
	v_mfma_f32_32x32x16_bf16 v[112:127], v[182:185], v[202:205], v[112:127]
	ds_read_b128 v[182:185], v140 offset:12288
	s_waitcnt lgkmcnt(3)
	v_mfma_f32_32x32x16_bf16 v[0:15], v[166:169], v[206:209], v[0:15]
	v_mfma_f32_32x32x16_bf16 v[16:31], v[166:169], v[220:223], v[16:31]
	ds_read_b128 v[166:169], v141
	s_waitcnt lgkmcnt(3)
	v_mfma_f32_32x32x16_bf16 v[32:47], v[170:173], v[206:209], v[32:47]
	v_mfma_f32_32x32x16_bf16 v[48:63], v[170:173], v[220:223], v[48:63]
	ds_read_b128 v[170:173], v141 offset:4096
	s_waitcnt lgkmcnt(3)
	v_mfma_f32_32x32x16_bf16 v[64:79], v[174:177], v[206:209], v[64:79]
	v_mfma_f32_32x32x16_bf16 v[80:95], v[174:177], v[220:223], v[80:95]
	ds_read_b128 v[174:177], v141 offset:8192
	s_waitcnt lgkmcnt(3)
	v_mfma_f32_32x32x16_bf16 v[96:111], v[182:185], v[206:209], v[96:111]
	v_mfma_f32_32x32x16_bf16 v[112:127], v[182:185], v[220:223], v[112:127]
	ds_read_b128 v[182:185], v141 offset:12288
	s_waitcnt lgkmcnt(3)
	v_mfma_f32_32x32x16_bf16 v[0:15], v[166:169], v[224:227], v[0:15]
	v_mfma_f32_32x32x16_bf16 v[16:31], v[166:169], v[228:231], v[16:31]
	s_waitcnt lgkmcnt(2)
	v_mfma_f32_32x32x16_bf16 v[32:47], v[170:173], v[224:227], v[32:47]
	v_mfma_f32_32x32x16_bf16 v[48:63], v[170:173], v[228:231], v[48:63]
	s_waitcnt lgkmcnt(1)
	v_mfma_f32_32x32x16_bf16 v[64:79], v[174:177], v[224:227], v[64:79]
	v_mfma_f32_32x32x16_bf16 v[80:95], v[174:177], v[228:231], v[80:95]
	s_waitcnt lgkmcnt(0)
	v_mfma_f32_32x32x16_bf16 v[96:111], v[182:185], v[224:227], v[96:111]
	v_mfma_f32_32x32x16_bf16 v[112:127], v[182:185], v[228:231], v[112:127]
	v_xor_b32_e32 v138, 0x8000, v138
	v_xor_b32_e32 v139, 0x8000, v139
	v_xor_b32_e32 v140, 0x8000, v140
	v_xor_b32_e32 v141, 0x8000, v141
	s_xor_b32 s15, s15, 0x8000
	s_add_i32 s14, s14, 1
	s_cmp_eq_u32 s14, 16
	s_cbranch_scc0 .Lg_ph8_top
	v_mov_b32_e32 v171, 0x12000
	v_mov_b32_e32 v172, s56
	v_mov_b32_e32 v173, s57
	ds_write_b64 v171, v[172:173]
	s_waitcnt vmcnt(0)
	v_mov_b32_e32 v128, v180
	v_add_u32_e32 v193, 0x400, v153
	v_add_u32_e32 v192, 0x1000, v153
	v_add_u32_e32 v191, 0x1400, v153
	v_add_u32_e32 v190, 0x2000, v153
	v_add_u32_e32 v183, 0x2400, v153
	v_add_u32_e32 v184, 0x3000, v153
	v_add_u32_e32 v185, 0x3200, v153
	v_add_u32_e32 v186, 0x3400, v153
	v_add_u32_e32 v187, 0x3600, v153
	v_add_u32_e32 v189, 0x4000, v153
	v_add_u32_e32 v179, 0x4400, v153
	v_add_u32_e32 v181, 0x4800, v153
	v_add_u32_e32 v182, 0x5000, v153
	v_add_u32_e32 v176, 0x5400, v153
	v_add_u32_e32 v177, 0x5800, v153
	v_add_u32_e32 v178, 0x6000, v153
	v_add_u32_e32 v170, 0x6400, v153
	v_add_u32_e32 v171, 0x6800, v153
	v_add_u32_e32 v172, 0x7200, v153
	v_add_u32_e32 v173, 0x7400, v153
	v_add_u32_e32 v174, 0x7600, v153
	v_add_u32_e32 v175, 0x7800, v153
	v_add_u32_e32 v169, 0x8400, v153
	v_add_u32_e32 v168, 0x8800, v153
	v_add_u32_e32 v167, 0x9400, v153
	v_add_u32_e32 v166, 0x9800, v153
	v_add_u32_e32 v145, 0xa400, v153
	v_add_u32_e32 v140, 0xa800, v153
	v_add_u32_e32 v141, 0xb400, v153
	v_add_u32_e32 v142, 0xb600, v153
	v_add_u32_e32 v143, 0xb800, v153
	v_add_u32_e32 v144, 0xba00, v153
	s_waitcnt vmcnt(0)
	s_barrier
	s_and_saveexec_b64 s[14:15], s[6:7]
	s_cbranch_execz .LBB0_959
	v_add_u32_e32 v134, 0xc400, v153
	ds_write2_b32 v153, v0, v16 offset1:32
	ds_write2_b32 v153, v1, v17 offset0:132 offset1:164
	ds_write2_b32 v193, v2, v18 offset0:8 offset1:40
	ds_write2_b32 v193, v3, v19 offset0:140 offset1:172
	ds_write2_b32 v192, v4, v20 offset0:32 offset1:64
	ds_write2_b32 v192, v5, v21 offset0:164 offset1:196
	ds_write2_b32 v191, v6, v22 offset0:40 offset1:72
	ds_write2_b32 v191, v7, v23 offset0:172 offset1:204
	ds_write2_b32 v190, v8, v24 offset0:64 offset1:96
	ds_write2_b32 v190, v9, v25 offset0:196 offset1:228
	ds_write2_b32 v183, v10, v26 offset0:72 offset1:104
	ds_write2_b32 v183, v11, v27 offset0:204 offset1:236
	ds_write2_b32 v184, v12, v28 offset0:96 offset1:128
	ds_write2_b32 v185, v13, v29 offset0:100 offset1:132
	ds_write2_b32 v186, v14, v30 offset0:104 offset1:136
	ds_write2_b32 v187, v15, v31 offset0:108 offset1:140
	ds_write2_b32 v189, v32, v48 offset0:128 offset1:160
	ds_write2_b32 v179, v33, v49 offset0:4 offset1:36
	ds_write2_b32 v179, v34, v50 offset0:136 offset1:168
	ds_write2_b32 v181, v35, v51 offset0:12 offset1:44
	ds_write2_b32 v182, v36, v52 offset0:160 offset1:192
	ds_write2_b32 v176, v37, v53 offset0:36 offset1:68
	ds_write2_b32 v176, v38, v54 offset0:168 offset1:200
	ds_write2_b32 v177, v39, v55 offset0:44 offset1:76
	ds_write2_b32 v178, v40, v56 offset0:192 offset1:224
	ds_write2_b32 v170, v41, v57 offset0:68 offset1:100
	ds_write2_b32 v170, v42, v58 offset0:200 offset1:232
	ds_write2_b32 v171, v43, v59 offset0:76 offset1:108
	ds_write2_b32 v172, v44, v60 offset0:96 offset1:128
	ds_write2_b32 v173, v45, v61 offset0:100 offset1:132
	ds_write2_b32 v174, v46, v62 offset0:104 offset1:136
	ds_write2_b32 v175, v47, v63 offset0:108 offset1:140
	ds_write2_b32 v169, v64, v80 offset1:32
	ds_write2_b32 v169, v65, v81 offset0:132 offset1:164
	ds_write2_b32 v168, v66, v82 offset0:8 offset1:40
	ds_write2_b32 v168, v67, v83 offset0:140 offset1:172
	ds_write2_b32 v167, v68, v84 offset0:32 offset1:64
	ds_write2_b32 v167, v69, v85 offset0:164 offset1:196
	ds_write2_b32 v166, v70, v86 offset0:40 offset1:72
	ds_write2_b32 v166, v71, v87 offset0:172 offset1:204
	ds_write2_b32 v145, v72, v88 offset0:64 offset1:96
	ds_write2_b32 v145, v73, v89 offset0:196 offset1:228
	ds_write2_b32 v140, v74, v90 offset0:72 offset1:104
	ds_write2_b32 v140, v75, v91 offset0:204 offset1:236
	ds_write2_b32 v141, v76, v92 offset0:96 offset1:128
	ds_write2_b32 v142, v77, v93 offset0:100 offset1:132
	ds_write2_b32 v143, v78, v94 offset0:104 offset1:136
	ds_write2_b32 v144, v79, v95 offset0:108 offset1:140
	ds_write2_b32 v134, v96, v112 offset0:128 offset1:160
	v_add_u32_e32 v134, 0xc800, v153
	ds_write2_b32 v134, v97, v113 offset0:4 offset1:36
	ds_write2_b32 v134, v98, v114 offset0:136 offset1:168
	v_add_u32_e32 v134, 0xcc00, v153
	ds_write2_b32 v134, v99, v115 offset0:12 offset1:44
	v_add_u32_e32 v134, 0xd400, v153
	ds_write2_b32 v134, v100, v116 offset0:160 offset1:192
	v_add_u32_e32 v134, 0xd800, v153
	ds_write2_b32 v134, v101, v117 offset0:36 offset1:68
	ds_write2_b32 v134, v102, v118 offset0:168 offset1:200
	v_add_u32_e32 v134, 0xdc00, v153
	ds_write2_b32 v134, v103, v119 offset0:44 offset1:76
	v_add_u32_e32 v134, 0xe400, v153
	ds_write2_b32 v134, v104, v120 offset0:192 offset1:224
	v_add_u32_e32 v134, 0xe800, v153
	ds_write2_b32 v134, v105, v121 offset0:68 offset1:100
	ds_write2_b32 v134, v106, v122 offset0:200 offset1:232
	v_add_u32_e32 v134, 0xec00, v153
	ds_write2_b32 v134, v107, v123 offset0:76 offset1:108
	v_add_u32_e32 v134, 0xf600, v153
	ds_write2_b32 v134, v108, v124 offset0:96 offset1:128
	v_add_u32_e32 v134, 0xf800, v153
	ds_write2_b32 v134, v109, v125 offset0:100 offset1:132
	v_add_u32_e32 v134, 0xfa00, v153
	ds_write2_b32 v134, v110, v126 offset0:104 offset1:136
	v_add_u32_e32 v134, 0xfc00, v153
	ds_write2_b32 v134, v111, v127 offset0:108 offset1:140

.LBB0_1021:
	s_lshr_b32 s4, s26, 3
	s_and_b32 s4, s4, 8
	s_lshl_b32 s16, s26, 3
	s_or_b32 s4, s4, s24
	s_and_b32 s35, s26, 1
	s_and_b32 s16, s16, 48
	s_or_b32 s36, s4, s16
	s_lshl_b32 s18, s35, 8
	s_lshl_b32 s16, s26, 4
	s_lshl_b32 s19, s36, 9
	v_or_b32_e32 v0, s18, v129
	s_and_b32 s37, s16, 0x380
	v_or_b32_e32 v0, s19, v0
	s_lshl_b32 s16, s37, 11
	s_lshl_b32 s4, s4, 21
	v_lshlrev_b32_e32 v1, 10, v0
	s_or_b32 s4, s4, s16
	s_add_u32 s16, s28, s4
	v_or_b32_e32 v0, v1, v128
	v_readfirstlane_b32 s4, v152
	v_lshlrev_b32_e32 v130, 1, v0
	s_mov_b32 m0, s4
	v_readfirstlane_b32 s4, v161
	v_add_lshl_u32 v0, v1, v158, 1
	s_waitcnt vmcnt(0)
	s_barrier
	s_nop 0
	s_mov_b32 m0, s4
	v_readfirstlane_b32 s4, v162
	s_addc_u32 s17, s29, 0
	v_add_lshl_u32 v2, v1, v159, 1
	s_nop 0
	s_mov_b32 m0, s4
	v_readfirstlane_b32 s4, v163
	v_add_lshl_u32 v4, v1, v160, 1
	v_lshl_add_u64 v[6:7], s[16:17], 0, v[132:133]
	s_nop 0
	s_mov_b32 m0, s4
	v_readfirstlane_b32 s4, v164
	v_lshl_add_u64 v[136:137], v[6:7], 0, v[134:135]
	s_nop 0
	s_mov_b32 m0, s4
	v_readfirstlane_b32 s4, v165
	v_lshl_add_u64 v[138:139], s[2:3], 0, v[130:131]
	v_mov_b32_e32 v1, v131
	v_lshl_add_u64 v[146:147], v[136:137], 0, s[10:11]
	s_nop 0
	s_mov_b32 m0, s4
	v_readfirstlane_b32 s4, v166
	v_lshl_add_u64 v[140:141], s[2:3], 0, v[0:1]
	v_mov_b32_e32 v3, v131
	s_nop 0
	v_lshl_add_u64 v[0:1], v[138:139], 0, 64
	s_mov_b32 m0, s4
	v_readfirstlane_b32 s4, v167
	v_lshl_add_u64 v[142:143], s[2:3], 0, v[2:3]
	v_mov_b32_e32 v5, v131
	s_nop 0
	v_lshl_add_u64 v[0:1], v[140:141], 0, 64
	s_mov_b32 m0, s4
	v_readfirstlane_b32 s4, v168
	v_lshl_add_u64 v[144:145], s[2:3], 0, v[4:5]
	s_nop 0
	v_lshl_add_u64 v[0:1], v[142:143], 0, 64
	s_mov_b32 m0, s4
	v_readfirstlane_b32 s4, v169
	s_nop 0
	v_lshl_add_u64 v[0:1], v[144:145], 0, 64
	s_mov_b32 m0, s4
	v_readfirstlane_b32 s4, v170
	s_nop 0
	v_lshl_add_u64 v[0:1], v[136:137], 0, 64
	s_mov_b32 m0, s4
	v_readfirstlane_b32 s4, v171
	s_nop 0
	v_lshl_add_u64 v[0:1], v[136:137], 0, s[12:13]
	s_mov_b32 m0, s4
	s_mov_b32 s16, s5
	s_nop 0
	s_mov_b32 s17, 2
	s_mov_b32 s38, s5
	v_mov_b32_e32 v0, 0
	v_mov_b32_e32 v1, v131
	v_mov_b32_e32 v2, v131
	v_mov_b32_e32 v4, v131
	v_mov_b32_e32 v6, v131
	v_mov_b32_e32 v7, v131
	v_mov_b32_e32 v8, v131
	v_mov_b32_e32 v9, v131
	v_mov_b32_e32 v10, v131
	v_mov_b32_e32 v11, v131
	v_mov_b32_e32 v12, v131
	v_mov_b32_e32 v13, v131
	v_mov_b32_e32 v14, v131
	v_mov_b32_e32 v15, v131
	v_mov_b32_e32 v16, 0
	v_mov_b32_e32 v17, v131
	v_mov_b32_e32 v18, v131
	v_mov_b32_e32 v19, v131
	v_mov_b32_e32 v20, v131
	v_mov_b32_e32 v21, v131
	v_mov_b32_e32 v22, v131
	v_mov_b32_e32 v23, v131
	v_mov_b32_e32 v24, v131
	v_mov_b32_e32 v25, v131
	v_mov_b32_e32 v26, v131
	v_mov_b32_e32 v27, v131
	v_mov_b32_e32 v28, v131
	v_mov_b32_e32 v29, v131
	v_mov_b32_e32 v30, v131
	v_mov_b32_e32 v31, v131
	v_mov_b32_e32 v32, 0
	v_mov_b32_e32 v33, v131
	v_mov_b32_e32 v34, v131
	v_mov_b32_e32 v35, v131
	v_mov_b32_e32 v36, v131
	v_mov_b32_e32 v37, v131
	v_mov_b32_e32 v38, v131
	v_mov_b32_e32 v39, v131
	v_mov_b32_e32 v40, v131
	v_mov_b32_e32 v41, v131
	v_mov_b32_e32 v42, v131
	v_mov_b32_e32 v43, v131
	v_mov_b32_e32 v44, v131
	v_mov_b32_e32 v45, v131
	v_mov_b32_e32 v46, v131
	v_mov_b32_e32 v47, v131
	v_mov_b32_e32 v48, 0
	v_mov_b32_e32 v49, v131
	v_mov_b32_e32 v50, v131
	v_mov_b32_e32 v51, v131
	v_mov_b32_e32 v52, v131
	v_mov_b32_e32 v53, v131
	v_mov_b32_e32 v54, v131
	v_mov_b32_e32 v55, v131
	v_mov_b32_e32 v56, v131
	v_mov_b32_e32 v57, v131
	v_mov_b32_e32 v58, v131
	v_mov_b32_e32 v59, v131
	v_mov_b32_e32 v60, v131
	v_mov_b32_e32 v61, v131
	v_mov_b32_e32 v62, v131
	v_mov_b32_e32 v63, v131
	v_mov_b32_e32 v64, 0
	v_mov_b32_e32 v65, v131
	v_mov_b32_e32 v66, v131
	v_mov_b32_e32 v67, v131
	v_mov_b32_e32 v68, v131
	v_mov_b32_e32 v69, v131
	v_mov_b32_e32 v70, v131
	v_mov_b32_e32 v71, v131
	v_mov_b32_e32 v72, v131
	v_mov_b32_e32 v73, v131
	v_mov_b32_e32 v74, v131
	v_mov_b32_e32 v75, v131
	v_mov_b32_e32 v76, v131
	v_mov_b32_e32 v77, v131
	v_mov_b32_e32 v78, v131
	v_mov_b32_e32 v79, v131
	v_mov_b32_e32 v80, 0
	v_mov_b32_e32 v81, v131
	v_mov_b32_e32 v82, v131
	v_mov_b32_e32 v83, v131
	v_mov_b32_e32 v84, v131
	v_mov_b32_e32 v85, v131
	v_mov_b32_e32 v86, v131
	v_mov_b32_e32 v87, v131
	v_mov_b32_e32 v88, v131
	v_mov_b32_e32 v89, v131
	v_mov_b32_e32 v90, v131
	v_mov_b32_e32 v91, v131
	v_mov_b32_e32 v92, v131
	v_mov_b32_e32 v93, v131
	v_mov_b32_e32 v94, v131
	v_mov_b32_e32 v95, v131
	v_mov_b32_e32 v96, 0
	v_mov_b32_e32 v97, v131
	v_mov_b32_e32 v98, v131
	v_mov_b32_e32 v99, v131
	v_mov_b32_e32 v100, v131
	v_mov_b32_e32 v101, v131
	v_mov_b32_e32 v102, v131
	v_mov_b32_e32 v103, v131
	v_mov_b32_e32 v104, v131
	v_mov_b32_e32 v105, v131
	v_mov_b32_e32 v106, v131
	v_mov_b32_e32 v107, v131
	v_mov_b32_e32 v108, v131
	v_mov_b32_e32 v109, v131
	v_mov_b32_e32 v110, v131
	v_mov_b32_e32 v111, v131
	v_mov_b32_e32 v112, 0
	v_mov_b32_e32 v113, v131
	v_mov_b32_e32 v114, v131
	v_mov_b32_e32 v115, v131
	v_mov_b32_e32 v116, v131
	v_mov_b32_e32 v117, v131
	v_mov_b32_e32 v118, v131
	v_mov_b32_e32 v119, v131
	v_mov_b32_e32 v120, v131
	v_mov_b32_e32 v121, v131
	v_mov_b32_e32 v122, v131
	v_mov_b32_e32 v123, v131
	v_mov_b32_e32 v124, v131
	v_mov_b32_e32 v125, v131
	v_mov_b32_e32 v126, v131
	v_mov_b32_e32 v127, v131
	s_mov_b64 s[54:55], 0x80
	v_lshrrev_b32_e32 v174, 6, v180
	v_lshlrev_b32_e32 v184, 11, v174
	v_mov_b32_e32 v175, 0x12000
	ds_read_b64 v[176:177], v175
	v_and_b32_e32 v148, 63, v180
	v_readfirstlane_b32 s53, v184
	v_lshrrev_b32_e32 v149, 5, v148
	v_bfe_u32 v150, v148, 1, 3
	v_xor_b32_e32 v150, v149, v150
	v_and_b32_e32 v151, 31, v148
	v_lshlrev_b32_e32 v151, 7, v151
	v_lshrrev_b32_e32 v151, 3, v148
	v_lshlrev_b32_e32 v184, 4, v151
	v_add_u32_e32 v185, 0x80, v184
	v_and_b32_e32 v151, 7, v148
	v_lshrrev_b32_e32 v149, 4, v148
	v_xor_b32_e32 v149, v151, v149
	v_lshrrev_b32_e32 v151, 5, v148
	v_sub_u32_e32 v190, v149, v151
	v_xor_b32_e32 v149, 4, v149
	v_add_u32_e32 v151, 2, v151
	v_sub_u32_e32 v192, v149, v151
	v_lshlrev_b32_e32 v190, 4, v190
	v_ashrrev_i32_e32 v191, 31, v190
	v_lshlrev_b32_e32 v192, 4, v192
	v_ashrrev_i32_e32 v193, 31, v192
	ds_bpermute_b32 v246, v184, v136
	ds_bpermute_b32 v247, v184, v137
	ds_bpermute_b32 v248, v185, v136
	ds_bpermute_b32 v249, v185, v137
	ds_bpermute_b32 v250, v184, v146
	ds_bpermute_b32 v251, v184, v147
	ds_bpermute_b32 v252, v185, v146
	ds_bpermute_b32 v253, v185, v147
	s_waitcnt lgkmcnt(0)
	ds_bpermute_b32 v178, v184, v138
	ds_bpermute_b32 v179, v184, v139
	ds_bpermute_b32 v186, v185, v138
	ds_bpermute_b32 v187, v185, v139
	ds_bpermute_b32 v238, v184, v140
	ds_bpermute_b32 v239, v184, v141
	ds_bpermute_b32 v240, v185, v140
	ds_bpermute_b32 v241, v185, v141
	ds_bpermute_b32 v242, v184, v142
	ds_bpermute_b32 v243, v184, v143
	ds_bpermute_b32 v244, v185, v142
	ds_bpermute_b32 v245, v185, v143
	ds_bpermute_b32 v136, v184, v144
	ds_bpermute_b32 v137, v184, v145
	ds_bpermute_b32 v146, v185, v144
	ds_bpermute_b32 v147, v185, v145
	s_waitcnt lgkmcnt(0)
	v_readfirstlane_b32 s56, v176
	v_readfirstlane_b32 s57, v177
	v_and_b32_e32 v151, 31, v148
	v_lshlrev_b32_e32 v151, 7, v151
	v_lshrrev_b32_e32 v149, 1, v174
	v_lshl_add_u32 v138, v149, 14, v151
	v_and_b32_e32 v149, 1, v174
	v_lshl_add_u32 v142, v149, 13, v151
	v_add_u32_e32 v142, 0x10000, v142
	v_xor_b32_e32 v151, 6, v150
	v_lshl_add_u32 v141, v151, 4, v138
	v_lshl_add_u32 v145, v151, 4, v142
	v_xor_b32_e32 v151, 4, v150
	v_lshl_add_u32 v140, v151, 4, v138
	v_lshl_add_u32 v144, v151, 4, v142
	v_xor_b32_e32 v151, 2, v150
	v_lshl_add_u32 v139, v151, 4, v138
	v_lshl_add_u32 v143, v151, 4, v142
	v_xor_b32_e32 v151, 0, v150
	v_lshl_add_u32 v138, v151, 4, v138
	v_lshl_add_u32 v142, v151, 4, v142
	v_lshl_add_u64 v[178:179], v[178:179], 0, v[190:191]
	v_lshl_add_u64 v[186:187], v[186:187], 0, v[192:193]
	v_lshl_add_u64 v[238:239], v[238:239], 0, v[190:191]
	v_lshl_add_u64 v[240:241], v[240:241], 0, v[192:193]
	v_lshl_add_u64 v[242:243], v[242:243], 0, v[190:191]
	v_lshl_add_u64 v[244:245], v[244:245], 0, v[192:193]
	v_lshl_add_u64 v[136:137], v[136:137], 0, v[190:191]
	v_lshl_add_u64 v[146:147], v[146:147], 0, v[192:193]
	v_lshl_add_u64 v[246:247], v[246:247], 0, v[190:191]
	v_lshl_add_u64 v[248:249], v[248:249], 0, v[192:193]
	v_lshl_add_u64 v[250:251], v[250:251], 0, v[190:191]
	v_lshl_add_u64 v[252:253], v[252:253], 0, v[192:193]
	s_mov_b32 s58, s53
	s_add_i32 m0, s58, 0x0
	s_nop 0
	global_load_lds_dwordx4 v[178:179], off
	s_add_i32 m0, s58, 0x400
	v_lshl_add_u64 v[178:179], v[178:179], 0, s[54:55]
	global_load_lds_dwordx4 v[186:187], off
	s_add_i32 m0, s58, 0x2000
	v_lshl_add_u64 v[186:187], v[186:187], 0, s[54:55]
	global_load_lds_dwordx4 v[238:239], off
	s_add_i32 m0, s58, 0x2400
	v_lshl_add_u64 v[238:239], v[238:239], 0, s[54:55]
	global_load_lds_dwordx4 v[240:241], off
	s_add_i32 m0, s58, 0x4000
	v_lshl_add_u64 v[240:241], v[240:241], 0, s[54:55]
	global_load_lds_dwordx4 v[242:243], off
	s_add_i32 m0, s58, 0x4400
	v_lshl_add_u64 v[242:243], v[242:243], 0, s[54:55]
	global_load_lds_dwordx4 v[244:245], off
	s_add_i32 m0, s58, 0x6000
	v_lshl_add_u64 v[244:245], v[244:245], 0, s[54:55]
	global_load_lds_dwordx4 v[136:137], off
	s_add_i32 m0, s58, 0x6400
	v_lshl_add_u64 v[136:137], v[136:137], 0, s[54:55]
	global_load_lds_dwordx4 v[146:147], off
	v_lshl_add_u64 v[146:147], v[146:147], 0, s[54:55]
	s_add_i32 s58, s53, 0x10000
	s_add_i32 m0, s58, 0x0
	s_nop 0
	global_load_lds_dwordx4 v[246:247], off
	s_add_i32 m0, s58, 0x400
	v_lshl_add_u64 v[246:247], v[246:247], 0, s[54:55]
	global_load_lds_dwordx4 v[248:249], off
	s_add_i32 m0, s58, 0x2000
	v_lshl_add_u64 v[248:249], v[248:249], 0, s[54:55]
	global_load_lds_dwordx4 v[250:251], off
	s_add_i32 m0, s58, 0x2400
	v_lshl_add_u64 v[250:251], v[250:251], 0, s[54:55]
	global_load_lds_dwordx4 v[252:253], off
	v_lshl_add_u64 v[252:253], v[252:253], 0, s[54:55]
	s_mov_b32 s16, 0
	s_mov_b32 s17, 0
.Lg_ph9_top:
	s_waitcnt vmcnt(0)
	s_waitcnt lgkmcnt(0)
	s_barrier
	s_cmp_eq_u32 s16, 15
	s_cbranch_scc1 .Lg_ph9_noA
	s_xor_b32 s58, s17, 0x8000
	s_add_i32 s58, s58, s53
	s_add_i32 m0, s58, 0x0
	s_nop 0
	global_load_lds_dwordx4 v[178:179], off
	s_add_i32 m0, s58, 0x400
	v_lshl_add_u64 v[178:179], v[178:179], 0, s[54:55]
	global_load_lds_dwordx4 v[186:187], off
	s_add_i32 m0, s58, 0x2000
	v_lshl_add_u64 v[186:187], v[186:187], 0, s[54:55]
	global_load_lds_dwordx4 v[238:239], off
	s_add_i32 m0, s58, 0x2400
	v_lshl_add_u64 v[238:239], v[238:239], 0, s[54:55]
	global_load_lds_dwordx4 v[240:241], off
	s_add_i32 m0, s58, 0x4000
	v_lshl_add_u64 v[240:241], v[240:241], 0, s[54:55]
	global_load_lds_dwordx4 v[242:243], off
	s_add_i32 m0, s58, 0x4400
	v_lshl_add_u64 v[242:243], v[242:243], 0, s[54:55]
	global_load_lds_dwordx4 v[244:245], off
	s_add_i32 m0, s58, 0x6000
	v_lshl_add_u64 v[244:245], v[244:245], 0, s[54:55]
	global_load_lds_dwordx4 v[136:137], off
	s_add_i32 m0, s58, 0x6400
	v_lshl_add_u64 v[136:137], v[136:137], 0, s[54:55]
	global_load_lds_dwordx4 v[146:147], off
	v_lshl_add_u64 v[146:147], v[146:147], 0, s[54:55]
.Lg_ph9_noA:
	ds_read_b128 v[194:197], v142
	ds_read_b128 v[198:201], v142 offset:4096
	ds_read_b128 v[202:205], v143
	ds_read_b128 v[206:209], v143 offset:4096
	ds_read_b128 v[214:217], v144
	ds_read_b128 v[226:229], v144 offset:4096
	ds_read_b128 v[230:233], v145
	ds_read_b128 v[234:237], v145 offset:4096
	ds_read_b128 v[148:151], v138
	ds_read_b128 v[174:177], v138 offset:4096
	ds_read_b128 v[182:185], v138 offset:8192
	ds_read_b128 v[190:193], v138 offset:12288
	s_waitcnt lgkmcnt(4)
	s_barrier
	s_cmp_eq_u32 s16, 15
	s_cbranch_scc1 .Lg_ph9_noB
	s_add_i32 s58, s53, 0x10000
	s_add_i32 m0, s58, 0x0
	s_nop 0
	global_load_lds_dwordx4 v[246:247], off
	s_add_i32 m0, s58, 0x400
	v_lshl_add_u64 v[246:247], v[246:247], 0, s[54:55]
	global_load_lds_dwordx4 v[248:249], off
	s_add_i32 m0, s58, 0x2000
	v_lshl_add_u64 v[248:249], v[248:249], 0, s[54:55]
	global_load_lds_dwordx4 v[250:251], off
	s_add_i32 m0, s58, 0x2400
	v_lshl_add_u64 v[250:251], v[250:251], 0, s[54:55]
	global_load_lds_dwordx4 v[252:253], off
	v_lshl_add_u64 v[252:253], v[252:253], 0, s[54:55]
.Lg_ph9_noB:
	s_waitcnt lgkmcnt(3)
	v_mfma_f32_32x32x16_bf16 v[0:15], v[148:151], v[194:197], v[0:15]
	v_mfma_f32_32x32x16_bf16 v[16:31], v[148:151], v[198:201], v[16:31]
	ds_read_b128 v[148:151], v139
	s_waitcnt lgkmcnt(3)
	v_mfma_f32_32x32x16_bf16 v[32:47], v[174:177], v[194:197], v[32:47]
	v_mfma_f32_32x32x16_bf16 v[48:63], v[174:177], v[198:201], v[48:63]
	ds_read_b128 v[174:177], v139 offset:4096
	s_waitcnt lgkmcnt(3)
	v_mfma_f32_32x32x16_bf16 v[64:79], v[182:185], v[194:197], v[64:79]
	v_mfma_f32_32x32x16_bf16 v[80:95], v[182:185], v[198:201], v[80:95]
	ds_read_b128 v[182:185], v139 offset:8192
	s_waitcnt lgkmcnt(3)
	v_mfma_f32_32x32x16_bf16 v[96:111], v[190:193], v[194:197], v[96:111]
	v_mfma_f32_32x32x16_bf16 v[112:127], v[190:193], v[198:201], v[112:127]
	ds_read_b128 v[190:193], v139 offset:12288
	s_waitcnt lgkmcnt(3)
	v_mfma_f32_32x32x16_bf16 v[0:15], v[148:151], v[202:205], v[0:15]
	v_mfma_f32_32x32x16_bf16 v[16:31], v[148:151], v[206:209], v[16:31]
	ds_read_b128 v[148:151], v140
	s_waitcnt lgkmcnt(3)
	v_mfma_f32_32x32x16_bf16 v[32:47], v[174:177], v[202:205], v[32:47]
	v_mfma_f32_32x32x16_bf16 v[48:63], v[174:177], v[206:209], v[48:63]
	ds_read_b128 v[174:177], v140 offset:4096
	s_waitcnt lgkmcnt(3)
	v_mfma_f32_32x32x16_bf16 v[64:79], v[182:185], v[202:205], v[64:79]
	v_mfma_f32_32x32x16_bf16 v[80:95], v[182:185], v[206:209], v[80:95]
	ds_read_b128 v[182:185], v140 offset:8192
	s_waitcnt lgkmcnt(3)
	v_mfma_f32_32x32x16_bf16 v[96:111], v[190:193], v[202:205], v[96:111]
	v_mfma_f32_32x32x16_bf16 v[112:127], v[190:193], v[206:209], v[112:127]
	ds_read_b128 v[190:193], v140 offset:12288
	s_waitcnt lgkmcnt(3)
	v_mfma_f32_32x32x16_bf16 v[0:15], v[148:151], v[214:217], v[0:15]
	v_mfma_f32_32x32x16_bf16 v[16:31], v[148:151], v[226:229], v[16:31]
	ds_read_b128 v[148:151], v141
	s_waitcnt lgkmcnt(3)
	v_mfma_f32_32x32x16_bf16 v[32:47], v[174:177], v[214:217], v[32:47]
	v_mfma_f32_32x32x16_bf16 v[48:63], v[174:177], v[226:229], v[48:63]
	ds_read_b128 v[174:177], v141 offset:4096
	s_waitcnt lgkmcnt(3)
	v_mfma_f32_32x32x16_bf16 v[64:79], v[182:185], v[214:217], v[64:79]
	v_mfma_f32_32x32x16_bf16 v[80:95], v[182:185], v[226:229], v[80:95]
	ds_read_b128 v[182:185], v141 offset:8192
	s_waitcnt lgkmcnt(3)
	v_mfma_f32_32x32x16_bf16 v[96:111], v[190:193], v[214:217], v[96:111]
	v_mfma_f32_32x32x16_bf16 v[112:127], v[190:193], v[226:229], v[112:127]
	ds_read_b128 v[190:193], v141 offset:12288
	s_waitcnt lgkmcnt(3)
	v_mfma_f32_32x32x16_bf16 v[0:15], v[148:151], v[230:233], v[0:15]
	v_mfma_f32_32x32x16_bf16 v[16:31], v[148:151], v[234:237], v[16:31]
	s_waitcnt lgkmcnt(2)
	v_mfma_f32_32x32x16_bf16 v[32:47], v[174:177], v[230:233], v[32:47]
	v_mfma_f32_32x32x16_bf16 v[48:63], v[174:177], v[234:237], v[48:63]
	s_waitcnt lgkmcnt(1)
	v_mfma_f32_32x32x16_bf16 v[64:79], v[182:185], v[230:233], v[64:79]
	v_mfma_f32_32x32x16_bf16 v[80:95], v[182:185], v[234:237], v[80:95]
	s_waitcnt lgkmcnt(0)
	v_mfma_f32_32x32x16_bf16 v[96:111], v[190:193], v[230:233], v[96:111]
	v_mfma_f32_32x32x16_bf16 v[112:127], v[190:193], v[234:237], v[112:127]
	v_xor_b32_e32 v138, 0x8000, v138
	v_xor_b32_e32 v139, 0x8000, v139
	v_xor_b32_e32 v140, 0x8000, v140
	v_xor_b32_e32 v141, 0x8000, v141
	s_xor_b32 s17, s17, 0x8000
	s_add_i32 s16, s16, 1
	s_cmp_eq_u32 s16, 16
	s_cbranch_scc0 .Lg_ph9_top
	v_mov_b32_e32 v175, 0x12000
	v_mov_b32_e32 v176, s56
	v_mov_b32_e32 v177, s57
	ds_write_b64 v175, v[176:177]
	s_waitcnt vmcnt(0)
	v_mov_b32_e32 v146, v180
	v_add_u32_e32 v209, 0x400, v157
	v_add_u32_e32 v208, 0x1000, v157
	v_add_u32_e32 v207, 0x1400, v157
	v_add_u32_e32 v206, 0x2000, v157
	v_add_u32_e32 v200, 0x2400, v157
	v_add_u32_e32 v201, 0x3000, v157
	v_add_u32_e32 v202, 0x3200, v157
	v_add_u32_e32 v203, 0x3400, v157
	v_add_u32_e32 v204, 0x3600, v157
	v_add_u32_e32 v205, 0x4000, v157
	v_add_u32_e32 v197, 0x4400, v157
	v_add_u32_e32 v198, 0x4800, v157
	v_add_u32_e32 v199, 0x5000, v157
	v_add_u32_e32 v194, 0x5400, v157
	v_add_u32_e32 v195, 0x5800, v157
	v_add_u32_e32 v196, 0x6000, v157
	v_add_u32_e32 v187, 0x6400, v157
	v_add_u32_e32 v189, 0x6800, v157
	v_add_u32_e32 v190, 0x7200, v157
	v_add_u32_e32 v191, 0x7400, v157
	v_add_u32_e32 v192, 0x7600, v157
	v_add_u32_e32 v193, 0x7800, v157
	v_add_u32_e32 v186, 0x8400, v157
	v_add_u32_e32 v185, 0x8800, v157
	v_add_u32_e32 v184, 0x9400, v157
	v_add_u32_e32 v183, 0x9800, v157
	v_add_u32_e32 v181, 0xa400, v157
	v_add_u32_e32 v174, 0xa800, v157
	v_add_u32_e32 v175, 0xb400, v157
	v_add_u32_e32 v176, 0xb600, v157
	v_add_u32_e32 v177, 0xb800, v157
	v_add_u32_e32 v178, 0xba00, v157
	s_waitcnt vmcnt(0)
	s_barrier
	s_and_saveexec_b64 s[16:17], s[6:7]
	s_cbranch_execz .LBB0_1025
	v_add_u32_e32 v130, 0xc400, v157
	ds_write2_b32 v157, v0, v16 offset1:32
	ds_write2_b32 v157, v1, v17 offset0:132 offset1:164
	ds_write2_b32 v209, v2, v18 offset0:8 offset1:40
	ds_write2_b32 v209, v3, v19 offset0:140 offset1:172
	ds_write2_b32 v208, v4, v20 offset0:32 offset1:64
	ds_write2_b32 v208, v5, v21 offset0:164 offset1:196
	ds_write2_b32 v207, v6, v22 offset0:40 offset1:72
	ds_write2_b32 v207, v7, v23 offset0:172 offset1:204
	ds_write2_b32 v206, v8, v24 offset0:64 offset1:96
	ds_write2_b32 v206, v9, v25 offset0:196 offset1:228
	ds_write2_b32 v200, v10, v26 offset0:72 offset1:104
	ds_write2_b32 v200, v11, v27 offset0:204 offset1:236
	ds_write2_b32 v201, v12, v28 offset0:96 offset1:128
	ds_write2_b32 v202, v13, v29 offset0:100 offset1:132
	ds_write2_b32 v203, v14, v30 offset0:104 offset1:136
	ds_write2_b32 v204, v15, v31 offset0:108 offset1:140
	ds_write2_b32 v205, v32, v48 offset0:128 offset1:160
	ds_write2_b32 v197, v33, v49 offset0:4 offset1:36
	ds_write2_b32 v197, v34, v50 offset0:136 offset1:168
	ds_write2_b32 v198, v35, v51 offset0:12 offset1:44
	ds_write2_b32 v199, v36, v52 offset0:160 offset1:192
	ds_write2_b32 v194, v37, v53 offset0:36 offset1:68
	ds_write2_b32 v194, v38, v54 offset0:168 offset1:200
	ds_write2_b32 v195, v39, v55 offset0:44 offset1:76
	ds_write2_b32 v196, v40, v56 offset0:192 offset1:224
	ds_write2_b32 v187, v41, v57 offset0:68 offset1:100
	ds_write2_b32 v187, v42, v58 offset0:200 offset1:232
	ds_write2_b32 v189, v43, v59 offset0:76 offset1:108
	ds_write2_b32 v190, v44, v60 offset0:96 offset1:128
	ds_write2_b32 v191, v45, v61 offset0:100 offset1:132
	ds_write2_b32 v192, v46, v62 offset0:104 offset1:136
	ds_write2_b32 v193, v47, v63 offset0:108 offset1:140
	ds_write2_b32 v186, v64, v80 offset1:32
	ds_write2_b32 v186, v65, v81 offset0:132 offset1:164
	ds_write2_b32 v185, v66, v82 offset0:8 offset1:40
	ds_write2_b32 v185, v67, v83 offset0:140 offset1:172
	ds_write2_b32 v184, v68, v84 offset0:32 offset1:64
	ds_write2_b32 v184, v69, v85 offset0:164 offset1:196
	ds_write2_b32 v183, v70, v86 offset0:40 offset1:72
	ds_write2_b32 v183, v71, v87 offset0:172 offset1:204
	ds_write2_b32 v181, v72, v88 offset0:64 offset1:96
	ds_write2_b32 v181, v73, v89 offset0:196 offset1:228
	ds_write2_b32 v174, v74, v90 offset0:72 offset1:104
	ds_write2_b32 v174, v75, v91 offset0:204 offset1:236
	ds_write2_b32 v175, v76, v92 offset0:96 offset1:128
	ds_write2_b32 v176, v77, v93 offset0:100 offset1:132
	ds_write2_b32 v177, v78, v94 offset0:104 offset1:136
	ds_write2_b32 v178, v79, v95 offset0:108 offset1:140
	ds_write2_b32 v130, v96, v112 offset0:128 offset1:160
	v_add_u32_e32 v130, 0xc800, v157
	ds_write2_b32 v130, v97, v113 offset0:4 offset1:36
	ds_write2_b32 v130, v98, v114 offset0:136 offset1:168
	v_add_u32_e32 v130, 0xcc00, v157
	ds_write2_b32 v130, v99, v115 offset0:12 offset1:44
	v_add_u32_e32 v130, 0xd400, v157
	ds_write2_b32 v130, v100, v116 offset0:160 offset1:192
	v_add_u32_e32 v130, 0xd800, v157
	ds_write2_b32 v130, v101, v117 offset0:36 offset1:68
	ds_write2_b32 v130, v102, v118 offset0:168 offset1:200
	v_add_u32_e32 v130, 0xdc00, v157
	ds_write2_b32 v130, v103, v119 offset0:44 offset1:76
	v_add_u32_e32 v130, 0xe400, v157
	ds_write2_b32 v130, v104, v120 offset0:192 offset1:224
	v_add_u32_e32 v130, 0xe800, v157
	ds_write2_b32 v130, v105, v121 offset0:68 offset1:100
	ds_write2_b32 v130, v106, v122 offset0:200 offset1:232
	v_add_u32_e32 v130, 0xec00, v157
	ds_write2_b32 v130, v107, v123 offset0:76 offset1:108
	v_add_u32_e32 v130, 0xf600, v157
	ds_write2_b32 v130, v108, v124 offset0:96 offset1:128
	v_add_u32_e32 v130, 0xf800, v157
	ds_write2_b32 v130, v109, v125 offset0:100 offset1:132
	v_add_u32_e32 v130, 0xfa00, v157
	ds_write2_b32 v130, v110, v126 offset0:104 offset1:136
	v_add_u32_e32 v130, 0xfc00, v157
	ds_write2_b32 v130, v111, v127 offset0:108 offset1:140

.LBB0_1176:
	s_mul_i32 s46, s27, 0x6000
	s_min_i32 s48, s26, 29
	s_mul_i32 s4, s45, 0x6000
	v_add_u32_e32 v130, s46, v160
	s_lshl_b32 s46, s48, 6
	s_mov_b32 s47, s5
	s_add_i32 s48, s4, 0
	s_add_i32 s4, s46, 0x80
	v_readfirstlane_b32 s49, v130
	v_add_u32_e32 v133, 0x1000, v130
	s_waitcnt vmcnt(6)
	s_cmp_lt_u32 s26, 31
	s_cbranch_scc1 .Ltw2
	s_waitcnt vmcnt(0)
.Ltw2:
	v_add_u32_e32 v135, 0x2000, v130
	v_lshl_add_u64 v[156:157], v[152:153], 0, s[46:47]
	v_lshl_add_u64 v[158:159], v[154:155], 0, s[46:47]
	v_lshl_add_u64 v[182:183], v[136:137], 0, s[4:5]
	v_readfirstlane_b32 s46, v133
	s_mov_b32 m0, s49
	s_waitcnt lgkmcnt(0)
	s_barrier
	v_add_u32_e32 v179, 0x3000, v130
	v_lshl_add_u64 v[184:185], v[138:139], 0, s[4:5]
	v_readfirstlane_b32 s47, v135
	s_cmp_ge_u32 s26, 30
	s_cbranch_scc1 .Ltd2_0
	global_load_lds_dwordx4 v[182:183], off
.Ltd2_0:
	s_mov_b32 m0, s46
	v_add_u32_e32 v181, 0x4000, v130
	v_lshl_add_u64 v[186:187], v[140:141], 0, s[4:5]
	v_lshl_add_u64 v[190:191], v[142:143], 0, s[4:5]
	v_readfirstlane_b32 s4, v179
	s_cbranch_scc1 .Ltd2_1
	global_load_lds_dwordx4 v[184:185], off
.Ltd2_1:
	s_mov_b32 m0, s47
	v_add_u32_e32 v130, 0x5000, v130
	v_add_u32_e32 v189, s48, v163
	v_add_u32_e32 v210, s48, v164
	v_readfirstlane_b32 s48, v181
	s_cbranch_scc1 .Ltd2_2
	global_load_lds_dwordx4 v[186:187], off
.Ltd2_2:
	s_mov_b32 m0, s4
	v_lshl_add_u64 v[156:157], v[156:157], 0, s[14:15]
	v_readfirstlane_b32 s50, v130
	s_cbranch_scc1 .Ltd2_3
	global_load_lds_dwordx4 v[190:191], off
.Ltd2_3:
	s_mov_b32 m0, s48
	v_lshl_add_u64 v[158:159], v[158:159], 0, s[14:15]
	s_cbranch_scc1 .Ltd2_4
	global_load_lds_dwordx4 v[156:157], off
.Ltd2_4:
	s_mov_b32 m0, s50
	v_add_u32_e32 v130, v189, v161
	s_cbranch_scc1 .Ltd2_5
	global_load_lds_dwordx4 v[158:159], off
.Ltd2_5:
	ds_read_b128 v[156:159], v130
	ds_read_b128 v[190:193], v130 offset:2048
	ds_read_b128 v[194:197], v130 offset:4096
	ds_read_b128 v[198:201], v130 offset:6144
	v_add_u32_e32 v133, v210, v161
	ds_read_b128 v[182:185], v133 offset:16384
	ds_read_b128 v[202:205], v133 offset:18432
	v_add_u32_e32 v130, v189, v162
	s_waitcnt lgkmcnt(0)
	v_mfma_f32_32x32x16_bf16 v[0:15], v[156:159], v[182:185], v[0:15]
	ds_read_b128 v[206:209], v130
	s_add_i32 s4, s45, 1
	s_cmp_lg_u32 s45, 2
	s_cselect_b32 s45, s4, 0
	s_add_i32 s4, s27, 1
	s_cmp_lg_u32 s27, 2
	s_cselect_b32 s27, s4, 0
	v_mfma_f32_32x32x16_bf16 v[48:63], v[156:159], v[202:205], v[48:63]
	ds_read_b128 v[156:159], v130 offset:2048
	s_add_i32 s26, s26, 1
	s_cmp_eq_u32 s26, 32
	v_mfma_f32_32x32x16_bf16 v[16:31], v[190:193], v[182:185], v[16:31]
	ds_read_b128 v[214:217], v130 offset:4096
	v_mfma_f32_32x32x16_bf16 v[64:79], v[190:193], v[202:205], v[64:79]
	ds_read_b128 v[190:193], v130 offset:6144
	v_add_u32_e32 v130, v210, v162
	v_mfma_f32_32x32x16_bf16 v[32:47], v[194:197], v[182:185], v[32:47]
	ds_read_b128 v[218:221], v130 offset:16384
	v_mfma_f32_32x32x16_bf16 v[112:127], v[194:197], v[202:205], v[112:127]
	ds_read_b128 v[194:197], v130 offset:18432
	v_mfma_f32_32x32x16_bf16 v[80:95], v[198:201], v[182:185], v[80:95]
	v_mfma_f32_32x32x16_bf16 v[96:111], v[198:201], v[202:205], v[96:111]
	s_waitcnt lgkmcnt(0)
	v_mfma_f32_32x32x16_bf16 v[0:15], v[206:209], v[218:221], v[0:15]
	v_mfma_f32_32x32x16_bf16 v[48:63], v[206:209], v[194:197], v[48:63]
	v_mfma_f32_32x32x16_bf16 v[16:31], v[156:159], v[218:221], v[16:31]
	v_mfma_f32_32x32x16_bf16 v[64:79], v[156:159], v[194:197], v[64:79]
	v_mfma_f32_32x32x16_bf16 v[32:47], v[214:217], v[218:221], v[32:47]
	v_mfma_f32_32x32x16_bf16 v[112:127], v[214:217], v[194:197], v[112:127]
	v_mfma_f32_32x32x16_bf16 v[80:95], v[190:193], v[218:221], v[80:95]
	v_mfma_f32_32x32x16_bf16 v[96:111], v[190:193], v[194:197], v[96:111]
	s_cbranch_scc0 .LBB0_1176
	s_waitcnt vmcnt(0)
	v_mov_b32_e32 v130, v180
	s_waitcnt vmcnt(0)
	s_barrier
	s_and_saveexec_b64 s[26:27], s[6:7]
	s_cbranch_execz .LBB0_1179
	v_add_u32_e32 v133, 0x400, v166
	ds_write2_b32 v166, v0, v48 offset1:32
	ds_write2_b32 v166, v1, v49 offset0:132 offset1:164
	ds_write2_b32 v133, v2, v50 offset0:8 offset1:40
	ds_write2_b32 v133, v3, v51 offset0:140 offset1:172
	v_add_u32_e32 v133, 0x1000, v166
	ds_write2_b32 v133, v4, v52 offset0:32 offset1:64
	ds_write2_b32 v133, v5, v53 offset0:164 offset1:196
	v_add_u32_e32 v133, 0x1400, v166
	ds_write2_b32 v133, v6, v54 offset0:40 offset1:72
	ds_write2_b32 v133, v7, v55 offset0:172 offset1:204
	v_add_u32_e32 v133, 0x2000, v166
	ds_write2_b32 v133, v8, v56 offset0:64 offset1:96
	ds_write2_b32 v133, v9, v57 offset0:196 offset1:228
	v_add_u32_e32 v133, 0x2400, v166
	ds_write2_b32 v133, v10, v58 offset0:72 offset1:104
	ds_write2_b32 v133, v11, v59 offset0:204 offset1:236
	v_add_u32_e32 v133, 0x3000, v166
	ds_write2_b32 v133, v12, v60 offset0:96 offset1:128
	v_add_u32_e32 v133, 0x3200, v166
	ds_write2_b32 v133, v13, v61 offset0:100 offset1:132
	v_add_u32_e32 v133, 0x3400, v166
	ds_write2_b32 v133, v14, v62 offset0:104 offset1:136
	v_add_u32_e32 v133, 0x3600, v166
	ds_write2_b32 v133, v15, v63 offset0:108 offset1:140
	v_add_u32_e32 v133, 0x4000, v166
	ds_write2_b32 v133, v16, v64 offset0:128 offset1:160
	v_add_u32_e32 v133, 0x4400, v166
	ds_write2_b32 v133, v17, v65 offset0:4 offset1:36
	ds_write2_b32 v133, v18, v66 offset0:136 offset1:168
	v_add_u32_e32 v133, 0x4800, v166
	ds_write2_b32 v133, v19, v67 offset0:12 offset1:44
	v_add_u32_e32 v133, 0x5000, v166
	ds_write2_b32 v133, v20, v68 offset0:160 offset1:192
	v_add_u32_e32 v133, 0x5400, v166
	ds_write2_b32 v133, v21, v69 offset0:36 offset1:68
	ds_write2_b32 v133, v22, v70 offset0:168 offset1:200
	v_add_u32_e32 v133, 0x5800, v166
	ds_write2_b32 v133, v23, v71 offset0:44 offset1:76
	v_add_u32_e32 v133, 0x6000, v166
	ds_write2_b32 v133, v24, v72 offset0:192 offset1:224
	v_add_u32_e32 v133, 0x6400, v166
	ds_write2_b32 v133, v25, v73 offset0:68 offset1:100
	ds_write2_b32 v133, v26, v74 offset0:200 offset1:232
	v_add_u32_e32 v133, 0x6800, v166
	ds_write2_b32 v133, v27, v75 offset0:76 offset1:108
	v_add_u32_e32 v133, 0x7200, v166
	ds_write2_b32 v133, v28, v76 offset0:96 offset1:128
	v_add_u32_e32 v133, 0x7400, v166
	ds_write2_b32 v133, v29, v77 offset0:100 offset1:132
	v_add_u32_e32 v133, 0x7600, v166
	ds_write2_b32 v133, v30, v78 offset0:104 offset1:136
	v_add_u32_e32 v133, 0x7800, v166
	ds_write2_b32 v133, v31, v79 offset0:108 offset1:140
	v_add_u32_e32 v133, 0x8400, v166
	ds_write2_b32 v133, v32, v112 offset1:32
	ds_write2_b32 v133, v33, v113 offset0:132 offset1:164
	v_add_u32_e32 v133, 0x8800, v166
	ds_write2_b32 v133, v34, v114 offset0:8 offset1:40
	ds_write2_b32 v133, v35, v115 offset0:140 offset1:172
	v_add_u32_e32 v133, 0x9400, v166
	ds_write2_b32 v133, v36, v116 offset0:32 offset1:64
	ds_write2_b32 v133, v37, v117 offset0:164 offset1:196
	v_add_u32_e32 v133, 0x9800, v166
	ds_write2_b32 v133, v38, v118 offset0:40 offset1:72
	ds_write2_b32 v133, v39, v119 offset0:172 offset1:204
	v_add_u32_e32 v133, 0xa400, v166
	ds_write2_b32 v133, v40, v120 offset0:64 offset1:96
	ds_write2_b32 v133, v41, v121 offset0:196 offset1:228
	v_add_u32_e32 v133, 0xa800, v166
	ds_write2_b32 v133, v42, v122 offset0:72 offset1:104
	ds_write2_b32 v133, v43, v123 offset0:204 offset1:236
	v_add_u32_e32 v133, 0xb400, v166
	ds_write2_b32 v133, v44, v124 offset0:96 offset1:128
	v_add_u32_e32 v133, 0xb600, v166
	ds_write2_b32 v133, v45, v125 offset0:100 offset1:132
	v_add_u32_e32 v133, 0xb800, v166
	ds_write2_b32 v133, v46, v126 offset0:104 offset1:136
	v_add_u32_e32 v133, 0xba00, v166
	ds_write2_b32 v133, v47, v127 offset0:108 offset1:140
	v_add_u32_e32 v133, 0xc400, v166
	ds_write2_b32 v133, v80, v96 offset0:128 offset1:160
	v_add_u32_e32 v133, 0xc800, v166
	ds_write2_b32 v133, v81, v97 offset0:4 offset1:36
	ds_write2_b32 v133, v82, v98 offset0:136 offset1:168
	v_add_u32_e32 v133, 0xcc00, v166
	ds_write2_b32 v133, v83, v99 offset0:12 offset1:44
	v_add_u32_e32 v133, 0xd400, v166
	ds_write2_b32 v133, v84, v100 offset0:160 offset1:192
	v_add_u32_e32 v133, 0xd800, v166
	ds_write2_b32 v133, v85, v101 offset0:36 offset1:68
	ds_write2_b32 v133, v86, v102 offset0:168 offset1:200
	v_add_u32_e32 v133, 0xdc00, v166
	ds_write2_b32 v133, v87, v103 offset0:44 offset1:76
	v_add_u32_e32 v133, 0xe400, v166
	ds_write2_b32 v133, v88, v104 offset0:192 offset1:224
	v_add_u32_e32 v133, 0xe800, v166
	ds_write2_b32 v133, v89, v105 offset0:68 offset1:100
	ds_write2_b32 v133, v90, v106 offset0:200 offset1:232
	v_add_u32_e32 v133, 0xec00, v166
	ds_write2_b32 v133, v91, v107 offset0:76 offset1:108
	v_add_u32_e32 v133, 0xf600, v166
	ds_write2_b32 v133, v92, v108 offset0:96 offset1:128
	v_add_u32_e32 v133, 0xf800, v166
	ds_write2_b32 v133, v93, v109 offset0:100 offset1:132
	v_add_u32_e32 v133, 0xfa00, v166
	ds_write2_b32 v133, v94, v110 offset0:104 offset1:136
	v_add_u32_e32 v133, 0xfc00, v166
	ds_write2_b32 v133, v95, v111 offset0:108 offset1:140

.LBB0_1184:
	s_mul_i32 s27, s25, 0x6000
	s_min_i32 s45, s24, 29
	s_mul_i32 s4, s26, 0x6000
	v_add_u32_e32 v130, s27, v160
	s_lshl_b32 s46, s45, 6
	s_add_i32 s27, s4, 0
	s_add_i32 s4, s46, 0x80
	v_readfirstlane_b32 s45, v130
	v_add_u32_e32 v133, 0x1000, v130
	s_waitcnt vmcnt(6)
	s_cmp_lt_u32 s24, 31
	s_cbranch_scc1 .Ltw3
	s_waitcnt vmcnt(0)
.Ltw3:
	s_mov_b32 s47, s5
	v_add_u32_e32 v135, 0x2000, v130
	v_add_u32_e32 v186, s27, v163
	v_add_u32_e32 v187, s27, v164
	v_lshl_add_u64 v[148:149], v[136:137], 0, s[4:5]
	v_readfirstlane_b32 s27, v133
	s_mov_b32 m0, s45
	s_waitcnt lgkmcnt(0)
	s_barrier
	v_add_u32_e32 v179, 0x3000, v130
	v_lshl_add_u64 v[144:145], v[152:153], 0, s[46:47]
	v_lshl_add_u64 v[146:147], v[154:155], 0, s[46:47]
	v_lshl_add_u64 v[150:151], v[138:139], 0, s[4:5]
	v_readfirstlane_b32 s46, v135
	s_cmp_ge_u32 s24, 30
	s_cbranch_scc1 .Ltd3_0
	global_load_lds_dwordx4 v[148:149], off
.Ltd3_0:
	s_mov_b32 m0, s27
	v_add_u32_e32 v181, 0x4000, v130
	v_lshl_add_u64 v[156:157], v[140:141], 0, s[4:5]
	v_lshl_add_u64 v[158:159], v[142:143], 0, s[4:5]
	v_readfirstlane_b32 s4, v179
	s_cbranch_scc1 .Ltd3_1
	global_load_lds_dwordx4 v[150:151], off
.Ltd3_1:
	s_mov_b32 m0, s46
	v_add_u32_e32 v130, 0x5000, v130
	v_readfirstlane_b32 s47, v181
	s_cbranch_scc1 .Ltd3_2
	global_load_lds_dwordx4 v[156:157], off
.Ltd3_2:
	s_mov_b32 m0, s4
	v_lshl_add_u64 v[144:145], v[144:145], 0, s[14:15]
	v_readfirstlane_b32 s48, v130
	s_cbranch_scc1 .Ltd3_3
	global_load_lds_dwordx4 v[158:159], off
.Ltd3_3:
	s_mov_b32 m0, s47
	v_lshl_add_u64 v[146:147], v[146:147], 0, s[14:15]
	s_cbranch_scc1 .Ltd3_4
	global_load_lds_dwordx4 v[144:145], off
.Ltd3_4:
	s_mov_b32 m0, s48
	v_add_u32_e32 v130, v186, v161
	s_cbranch_scc1 .Ltd3_5
	global_load_lds_dwordx4 v[146:147], off
.Ltd3_5:
	ds_read_b128 v[144:147], v130
	ds_read_b128 v[156:159], v130 offset:2048
	ds_read_b128 v[182:185], v130 offset:4096
	ds_read_b128 v[190:193], v130 offset:6144
	v_add_u32_e32 v133, v187, v161
	ds_read_b128 v[148:151], v133 offset:16384
	ds_read_b128 v[194:197], v133 offset:18432
	v_add_u32_e32 v130, v186, v162
	s_waitcnt lgkmcnt(0)
	v_mfma_f32_32x32x16_bf16 v[0:15], v[144:147], v[148:151], v[0:15]
	ds_read_b128 v[198:201], v130
	s_add_i32 s4, s26, 1
	s_cmp_lg_u32 s26, 2
	s_cselect_b32 s26, s4, 0
	s_add_i32 s4, s25, 1
	s_cmp_lg_u32 s25, 2
	s_cselect_b32 s25, s4, 0
	v_mfma_f32_32x32x16_bf16 v[16:31], v[144:147], v[194:197], v[16:31]
	ds_read_b128 v[144:147], v130 offset:2048
	s_add_i32 s24, s24, 1
	s_cmp_eq_u32 s24, 32
	v_mfma_f32_32x32x16_bf16 v[32:47], v[156:159], v[148:151], v[32:47]
	ds_read_b128 v[202:205], v130 offset:4096
	v_mfma_f32_32x32x16_bf16 v[48:63], v[156:159], v[194:197], v[48:63]
	ds_read_b128 v[156:159], v130 offset:6144
	v_add_u32_e32 v130, v187, v162
	v_mfma_f32_32x32x16_bf16 v[64:79], v[182:185], v[148:151], v[64:79]
	ds_read_b128 v[206:209], v130 offset:16384
	v_mfma_f32_32x32x16_bf16 v[112:127], v[182:185], v[194:197], v[112:127]
	ds_read_b128 v[182:185], v130 offset:18432
	v_mfma_f32_32x32x16_bf16 v[80:95], v[190:193], v[148:151], v[80:95]
	v_mfma_f32_32x32x16_bf16 v[96:111], v[190:193], v[194:197], v[96:111]
	s_waitcnt lgkmcnt(0)
	v_mfma_f32_32x32x16_bf16 v[0:15], v[198:201], v[206:209], v[0:15]
	v_mfma_f32_32x32x16_bf16 v[16:31], v[198:201], v[182:185], v[16:31]
	v_mfma_f32_32x32x16_bf16 v[32:47], v[144:147], v[206:209], v[32:47]
	v_mfma_f32_32x32x16_bf16 v[48:63], v[144:147], v[182:185], v[48:63]
	v_mfma_f32_32x32x16_bf16 v[64:79], v[202:205], v[206:209], v[64:79]
	v_mfma_f32_32x32x16_bf16 v[112:127], v[202:205], v[182:185], v[112:127]
	v_mfma_f32_32x32x16_bf16 v[80:95], v[156:159], v[206:209], v[80:95]
	v_mfma_f32_32x32x16_bf16 v[96:111], v[156:159], v[182:185], v[96:111]
	s_cbranch_scc0 .LBB0_1184
	s_waitcnt vmcnt(0)
	v_mov_b32_e32 v130, v180
	v_add_u32_e32 v192, 0x400, v166
	v_add_u32_e32 v191, 0x1000, v166
	v_add_u32_e32 v190, 0x1400, v166
	v_add_u32_e32 v189, 0x2000, v166
	v_add_u32_e32 v182, 0x2400, v166
	v_add_u32_e32 v183, 0x3000, v166
	v_add_u32_e32 v184, 0x3200, v166
	v_add_u32_e32 v185, 0x3400, v166
	v_add_u32_e32 v186, 0x3600, v166
	v_add_u32_e32 v187, 0x4000, v166
	v_add_u32_e32 v159, 0x4400, v166
	v_add_u32_e32 v179, 0x4800, v166
	v_add_u32_e32 v181, 0x5000, v166
	v_add_u32_e32 v156, 0x5400, v166
	v_add_u32_e32 v157, 0x5800, v166
	v_add_u32_e32 v158, 0x6000, v166
	v_add_u32_e32 v150, 0x6400, v166
	v_add_u32_e32 v151, 0x6800, v166
	v_add_u32_e32 v152, 0x7200, v166
	v_add_u32_e32 v153, 0x7400, v166
	v_add_u32_e32 v154, 0x7600, v166
	v_add_u32_e32 v155, 0x7800, v166
	v_add_u32_e32 v149, 0x8400, v166
	v_add_u32_e32 v148, 0x8800, v166
	v_add_u32_e32 v147, 0x9400, v166
	v_add_u32_e32 v146, 0x9800, v166
	v_add_u32_e32 v145, 0xa400, v166
	v_add_u32_e32 v140, 0xa800, v166
	v_add_u32_e32 v141, 0xb400, v166
	v_add_u32_e32 v142, 0xb600, v166
	v_add_u32_e32 v143, 0xb800, v166
	v_add_u32_e32 v144, 0xba00, v166
	s_waitcnt vmcnt(0)
	s_barrier
	s_and_saveexec_b64 s[24:25], s[6:7]
	s_cbranch_execz .LBB0_1187
	v_add_u32_e32 v133, 0xc400, v166
	ds_write2_b32 v166, v0, v16 offset1:32
	ds_write2_b32 v166, v1, v17 offset0:132 offset1:164
	ds_write2_b32 v192, v2, v18 offset0:8 offset1:40
	ds_write2_b32 v192, v3, v19 offset0:140 offset1:172
	ds_write2_b32 v191, v4, v20 offset0:32 offset1:64
	ds_write2_b32 v191, v5, v21 offset0:164 offset1:196
	ds_write2_b32 v190, v6, v22 offset0:40 offset1:72
	ds_write2_b32 v190, v7, v23 offset0:172 offset1:204
	ds_write2_b32 v189, v8, v24 offset0:64 offset1:96
	ds_write2_b32 v189, v9, v25 offset0:196 offset1:228
	ds_write2_b32 v182, v10, v26 offset0:72 offset1:104
	ds_write2_b32 v182, v11, v27 offset0:204 offset1:236
	ds_write2_b32 v183, v12, v28 offset0:96 offset1:128
	ds_write2_b32 v184, v13, v29 offset0:100 offset1:132
	ds_write2_b32 v185, v14, v30 offset0:104 offset1:136
	ds_write2_b32 v186, v15, v31 offset0:108 offset1:140
	ds_write2_b32 v187, v32, v48 offset0:128 offset1:160
	ds_write2_b32 v159, v33, v49 offset0:4 offset1:36
	ds_write2_b32 v159, v34, v50 offset0:136 offset1:168
	ds_write2_b32 v179, v35, v51 offset0:12 offset1:44
	ds_write2_b32 v181, v36, v52 offset0:160 offset1:192
	ds_write2_b32 v156, v37, v53 offset0:36 offset1:68
	ds_write2_b32 v156, v38, v54 offset0:168 offset1:200
	ds_write2_b32 v157, v39, v55 offset0:44 offset1:76
	ds_write2_b32 v158, v40, v56 offset0:192 offset1:224
	ds_write2_b32 v150, v41, v57 offset0:68 offset1:100
	ds_write2_b32 v150, v42, v58 offset0:200 offset1:232
	ds_write2_b32 v151, v43, v59 offset0:76 offset1:108
	ds_write2_b32 v152, v44, v60 offset0:96 offset1:128
	ds_write2_b32 v153, v45, v61 offset0:100 offset1:132
	ds_write2_b32 v154, v46, v62 offset0:104 offset1:136
	ds_write2_b32 v155, v47, v63 offset0:108 offset1:140
	ds_write2_b32 v149, v64, v112 offset1:32
	ds_write2_b32 v149, v65, v113 offset0:132 offset1:164
	ds_write2_b32 v148, v66, v114 offset0:8 offset1:40
	ds_write2_b32 v148, v67, v115 offset0:140 offset1:172
	ds_write2_b32 v147, v68, v116 offset0:32 offset1:64
	ds_write2_b32 v147, v69, v117 offset0:164 offset1:196
	ds_write2_b32 v146, v70, v118 offset0:40 offset1:72
	ds_write2_b32 v146, v71, v119 offset0:172 offset1:204
	ds_write2_b32 v145, v72, v120 offset0:64 offset1:96
	ds_write2_b32 v145, v73, v121 offset0:196 offset1:228
	ds_write2_b32 v140, v74, v122 offset0:72 offset1:104
	ds_write2_b32 v140, v75, v123 offset0:204 offset1:236
	ds_write2_b32 v141, v76, v124 offset0:96 offset1:128
	ds_write2_b32 v142, v77, v125 offset0:100 offset1:132
	ds_write2_b32 v143, v78, v126 offset0:104 offset1:136
	ds_write2_b32 v144, v79, v127 offset0:108 offset1:140
	ds_write2_b32 v133, v80, v96 offset0:128 offset1:160
	v_add_u32_e32 v133, 0xc800, v166
	ds_write2_b32 v133, v81, v97 offset0:4 offset1:36
	ds_write2_b32 v133, v82, v98 offset0:136 offset1:168
	v_add_u32_e32 v133, 0xcc00, v166
	ds_write2_b32 v133, v83, v99 offset0:12 offset1:44
	v_add_u32_e32 v133, 0xd400, v166
	ds_write2_b32 v133, v84, v100 offset0:160 offset1:192
	v_add_u32_e32 v133, 0xd800, v166
	ds_write2_b32 v133, v85, v101 offset0:36 offset1:68
	ds_write2_b32 v133, v86, v102 offset0:168 offset1:200
	v_add_u32_e32 v133, 0xdc00, v166
	ds_write2_b32 v133, v87, v103 offset0:44 offset1:76
	v_add_u32_e32 v133, 0xe400, v166
	ds_write2_b32 v133, v88, v104 offset0:192 offset1:224
	v_add_u32_e32 v133, 0xe800, v166
	ds_write2_b32 v133, v89, v105 offset0:68 offset1:100
	ds_write2_b32 v133, v90, v106 offset0:200 offset1:232
	v_add_u32_e32 v133, 0xec00, v166
	ds_write2_b32 v133, v91, v107 offset0:76 offset1:108
	v_add_u32_e32 v133, 0xf600, v166
	ds_write2_b32 v133, v92, v108 offset0:96 offset1:128
	v_add_u32_e32 v133, 0xf800, v166
	ds_write2_b32 v133, v93, v109 offset0:100 offset1:132
	v_add_u32_e32 v133, 0xfa00, v166
	ds_write2_b32 v133, v94, v110 offset0:104 offset1:136
	v_add_u32_e32 v133, 0xfc00, v166
	ds_write2_b32 v133, v95, v111 offset0:108 offset1:140

.LBB0_1316:
	s_mul_i32 s34, s17, 0x6000
	s_min_i32 s36, s16, 29
	s_mul_i32 s4, s31, 0x6000
	v_add_u32_e32 v130, s34, v148
	s_lshl_b32 s34, s36, 6
	s_mov_b32 s35, s5
	s_add_i32 s36, s4, 0
	s_add_i32 s4, s34, 0x80
	v_readfirstlane_b32 s37, v130
	v_add_u32_e32 v169, 0x1000, v130
	s_waitcnt vmcnt(6)
	s_cmp_lt_u32 s16, 31
	s_cbranch_scc1 .Ltw4
	s_waitcnt vmcnt(0)
.Ltw4:
	v_add_u32_e32 v181, 0x2000, v130
	v_lshl_add_u64 v[170:171], v[136:137], 0, s[34:35]
	v_lshl_add_u64 v[172:173], v[146:147], 0, s[34:35]
	v_lshl_add_u64 v[174:175], v[138:139], 0, s[4:5]
	v_readfirstlane_b32 s34, v169
	s_mov_b32 m0, s37
	s_waitcnt lgkmcnt(0)
	s_barrier
	v_add_u32_e32 v184, 0x3000, v130
	v_lshl_add_u64 v[176:177], v[140:141], 0, s[4:5]
	v_readfirstlane_b32 s35, v181
	s_cmp_ge_u32 s16, 30
	s_cbranch_scc1 .Ltd4_0
	global_load_lds_dwordx4 v[174:175], off
.Ltd4_0:
	s_mov_b32 m0, s34
	v_add_u32_e32 v185, 0x4000, v130
	v_lshl_add_u64 v[178:179], v[142:143], 0, s[4:5]
	v_lshl_add_u64 v[182:183], v[144:145], 0, s[4:5]
	v_readfirstlane_b32 s4, v184
	s_cbranch_scc1 .Ltd4_1
	global_load_lds_dwordx4 v[176:177], off
.Ltd4_1:
	s_mov_b32 m0, s35
	v_add_u32_e32 v130, 0x5000, v130
	v_add_u32_e32 v186, s36, v151
	v_add_u32_e32 v187, s36, v152
	v_readfirstlane_b32 s36, v185
	s_cbranch_scc1 .Ltd4_2
	global_load_lds_dwordx4 v[178:179], off
.Ltd4_2:
	s_mov_b32 m0, s4
	v_lshl_add_u64 v[170:171], v[170:171], 0, s[14:15]
	v_readfirstlane_b32 s38, v130
	s_cbranch_scc1 .Ltd4_3
	global_load_lds_dwordx4 v[182:183], off
.Ltd4_3:
	s_mov_b32 m0, s36
	v_lshl_add_u64 v[172:173], v[172:173], 0, s[14:15]
	s_cbranch_scc1 .Ltd4_4
	global_load_lds_dwordx4 v[170:171], off
.Ltd4_4:
	s_mov_b32 m0, s38
	v_add_u32_e32 v130, v186, v149
	s_cbranch_scc1 .Ltd4_5
	global_load_lds_dwordx4 v[172:173], off
.Ltd4_5:
	ds_read_b128 v[170:173], v130
	ds_read_b128 v[182:185], v130 offset:2048
	ds_read_b128 v[190:193], v130 offset:4096
	ds_read_b128 v[194:197], v130 offset:6144
	v_add_u32_e32 v169, v187, v149
	ds_read_b128 v[174:177], v169 offset:16384
	ds_read_b128 v[198:201], v169 offset:18432
	v_add_u32_e32 v130, v186, v150
	s_waitcnt lgkmcnt(0)
	v_mfma_f32_32x32x16_bf16 v[0:15], v[170:173], v[174:177], v[0:15]
	ds_read_b128 v[202:205], v130
	s_add_i32 s4, s31, 1
	s_cmp_lg_u32 s31, 2
	s_cselect_b32 s31, s4, 0
	s_add_i32 s4, s17, 1
	s_cmp_lg_u32 s17, 2
	s_cselect_b32 s17, s4, 0
	v_mfma_f32_32x32x16_bf16 v[16:31], v[170:173], v[198:201], v[16:31]
	ds_read_b128 v[170:173], v130 offset:2048
	s_add_i32 s16, s16, 1
	s_cmp_eq_u32 s16, 32
	v_mfma_f32_32x32x16_bf16 v[32:47], v[182:185], v[174:177], v[32:47]
	ds_read_b128 v[206:209], v130 offset:4096
	v_mfma_f32_32x32x16_bf16 v[48:63], v[182:185], v[198:201], v[48:63]
	ds_read_b128 v[182:185], v130 offset:6144
	v_add_u32_e32 v130, v187, v150
	v_mfma_f32_32x32x16_bf16 v[64:79], v[190:193], v[174:177], v[64:79]
	ds_read_b128 v[214:217], v130 offset:16384
	v_mfma_f32_32x32x16_bf16 v[80:95], v[190:193], v[198:201], v[80:95]
	ds_read_b128 v[190:193], v130 offset:18432
	v_mfma_f32_32x32x16_bf16 v[96:111], v[194:197], v[174:177], v[96:111]
	v_mfma_f32_32x32x16_bf16 v[112:127], v[194:197], v[198:201], v[112:127]
	s_waitcnt lgkmcnt(0)
	v_mfma_f32_32x32x16_bf16 v[0:15], v[202:205], v[214:217], v[0:15]
	v_mfma_f32_32x32x16_bf16 v[16:31], v[202:205], v[190:193], v[16:31]
	v_mfma_f32_32x32x16_bf16 v[32:47], v[170:173], v[214:217], v[32:47]
	v_mfma_f32_32x32x16_bf16 v[48:63], v[170:173], v[190:193], v[48:63]
	v_mfma_f32_32x32x16_bf16 v[64:79], v[206:209], v[214:217], v[64:79]
	v_mfma_f32_32x32x16_bf16 v[80:95], v[206:209], v[190:193], v[80:95]
	v_mfma_f32_32x32x16_bf16 v[96:111], v[182:185], v[214:217], v[96:111]
	v_mfma_f32_32x32x16_bf16 v[112:127], v[182:185], v[190:193], v[112:127]
	s_cbranch_scc0 .LBB0_1316
	s_waitcnt vmcnt(0)
	v_mov_b32_e32 v130, v180
	v_add_u32_e32 v202, 0x400, v153
	v_add_u32_e32 v201, 0x1000, v153
	v_add_u32_e32 v200, 0x1400, v153
	v_add_u32_e32 v199, 0x2000, v153
	v_add_u32_e32 v193, 0x2400, v153
	v_add_u32_e32 v194, 0x3000, v153
	v_add_u32_e32 v195, 0x3200, v153
	v_add_u32_e32 v196, 0x3400, v153
	v_add_u32_e32 v197, 0x3600, v153
	v_add_u32_e32 v198, 0x4000, v153
	v_add_u32_e32 v190, 0x4400, v153
	v_add_u32_e32 v191, 0x4800, v153
	v_add_u32_e32 v192, 0x5000, v153
	v_add_u32_e32 v186, 0x5400, v153
	v_add_u32_e32 v187, 0x5800, v153
	v_add_u32_e32 v189, 0x6000, v153
	v_add_u32_e32 v179, 0x6400, v153
	v_add_u32_e32 v181, 0x6800, v153
	v_add_u32_e32 v182, 0x7200, v153
	v_add_u32_e32 v183, 0x7400, v153
	v_add_u32_e32 v184, 0x7600, v153
	v_add_u32_e32 v185, 0x7800, v153
	v_add_u32_e32 v178, 0x8400, v153
	v_add_u32_e32 v177, 0x8800, v153
	v_add_u32_e32 v176, 0x9400, v153
	v_add_u32_e32 v175, 0x9800, v153
	v_add_u32_e32 v174, 0xa400, v153
	v_add_u32_e32 v147, 0xa800, v153
	v_add_u32_e32 v169, 0xb400, v153
	v_add_u32_e32 v170, 0xb600, v153
	v_add_u32_e32 v171, 0xb800, v153
	v_add_u32_e32 v172, 0xba00, v153
	s_waitcnt vmcnt(0)
	s_barrier
	s_and_saveexec_b64 s[16:17], s[6:7]
	s_cbranch_execz .LBB0_1319
	v_add_u32_e32 v136, 0xc400, v153
	ds_write2_b32 v153, v0, v16 offset1:32
	ds_write2_b32 v153, v1, v17 offset0:132 offset1:164
	ds_write2_b32 v202, v2, v18 offset0:8 offset1:40
	ds_write2_b32 v202, v3, v19 offset0:140 offset1:172
	ds_write2_b32 v201, v4, v20 offset0:32 offset1:64
	ds_write2_b32 v201, v5, v21 offset0:164 offset1:196
	ds_write2_b32 v200, v6, v22 offset0:40 offset1:72
	ds_write2_b32 v200, v7, v23 offset0:172 offset1:204
	ds_write2_b32 v199, v8, v24 offset0:64 offset1:96
	ds_write2_b32 v199, v9, v25 offset0:196 offset1:228
	ds_write2_b32 v193, v10, v26 offset0:72 offset1:104
	ds_write2_b32 v193, v11, v27 offset0:204 offset1:236
	ds_write2_b32 v194, v12, v28 offset0:96 offset1:128
	ds_write2_b32 v195, v13, v29 offset0:100 offset1:132
	ds_write2_b32 v196, v14, v30 offset0:104 offset1:136
	ds_write2_b32 v197, v15, v31 offset0:108 offset1:140
	ds_write2_b32 v198, v32, v48 offset0:128 offset1:160
	ds_write2_b32 v190, v33, v49 offset0:4 offset1:36
	ds_write2_b32 v190, v34, v50 offset0:136 offset1:168
	ds_write2_b32 v191, v35, v51 offset0:12 offset1:44
	ds_write2_b32 v192, v36, v52 offset0:160 offset1:192
	ds_write2_b32 v186, v37, v53 offset0:36 offset1:68
	ds_write2_b32 v186, v38, v54 offset0:168 offset1:200
	ds_write2_b32 v187, v39, v55 offset0:44 offset1:76
	ds_write2_b32 v189, v40, v56 offset0:192 offset1:224
	ds_write2_b32 v179, v41, v57 offset0:68 offset1:100
	ds_write2_b32 v179, v42, v58 offset0:200 offset1:232
	ds_write2_b32 v181, v43, v59 offset0:76 offset1:108
	ds_write2_b32 v182, v44, v60 offset0:96 offset1:128
	ds_write2_b32 v183, v45, v61 offset0:100 offset1:132
	ds_write2_b32 v184, v46, v62 offset0:104 offset1:136
	ds_write2_b32 v185, v47, v63 offset0:108 offset1:140
	ds_write2_b32 v178, v64, v80 offset1:32
	ds_write2_b32 v178, v65, v81 offset0:132 offset1:164
	ds_write2_b32 v177, v66, v82 offset0:8 offset1:40
	ds_write2_b32 v177, v67, v83 offset0:140 offset1:172
	ds_write2_b32 v176, v68, v84 offset0:32 offset1:64
	ds_write2_b32 v176, v69, v85 offset0:164 offset1:196
	ds_write2_b32 v175, v70, v86 offset0:40 offset1:72
	ds_write2_b32 v175, v71, v87 offset0:172 offset1:204
	ds_write2_b32 v174, v72, v88 offset0:64 offset1:96
	ds_write2_b32 v174, v73, v89 offset0:196 offset1:228
	ds_write2_b32 v147, v74, v90 offset0:72 offset1:104
	ds_write2_b32 v147, v75, v91 offset0:204 offset1:236
	ds_write2_b32 v169, v76, v92 offset0:96 offset1:128
	ds_write2_b32 v170, v77, v93 offset0:100 offset1:132
	ds_write2_b32 v171, v78, v94 offset0:104 offset1:136
	ds_write2_b32 v172, v79, v95 offset0:108 offset1:140
	ds_write2_b32 v136, v96, v112 offset0:128 offset1:160
	v_add_u32_e32 v136, 0xc800, v153
	ds_write2_b32 v136, v97, v113 offset0:4 offset1:36
	ds_write2_b32 v136, v98, v114 offset0:136 offset1:168
	v_add_u32_e32 v136, 0xcc00, v153
	ds_write2_b32 v136, v99, v115 offset0:12 offset1:44
	v_add_u32_e32 v136, 0xd400, v153
	ds_write2_b32 v136, v100, v116 offset0:160 offset1:192
	v_add_u32_e32 v136, 0xd800, v153
	ds_write2_b32 v136, v101, v117 offset0:36 offset1:68
	ds_write2_b32 v136, v102, v118 offset0:168 offset1:200
	v_add_u32_e32 v136, 0xdc00, v153
	ds_write2_b32 v136, v103, v119 offset0:44 offset1:76
	v_add_u32_e32 v136, 0xe400, v153
	ds_write2_b32 v136, v104, v120 offset0:192 offset1:224
	v_add_u32_e32 v136, 0xe800, v153
	ds_write2_b32 v136, v105, v121 offset0:68 offset1:100
	ds_write2_b32 v136, v106, v122 offset0:200 offset1:232
	v_add_u32_e32 v136, 0xec00, v153
	ds_write2_b32 v136, v107, v123 offset0:76 offset1:108
	v_add_u32_e32 v136, 0xf600, v153
	ds_write2_b32 v136, v108, v124 offset0:96 offset1:128
	v_add_u32_e32 v136, 0xf800, v153
	ds_write2_b32 v136, v109, v125 offset0:100 offset1:132
	v_add_u32_e32 v136, 0xfa00, v153
	ds_write2_b32 v136, v110, v126 offset0:104 offset1:136
	v_add_u32_e32 v136, 0xfc00, v153
	ds_write2_b32 v136, v111, v127 offset0:108 offset1:140

.LBB0_1670:
	s_lshr_b32 s10, s19, 4
	s_and_b32 s10, s10, 12
	s_bfe_u32 s15, s19, 0x20001
	s_or_b32 s10, s10, s20
	s_lshl_b32 s14, s15, 4
	s_and_b32 s26, s19, 1
	s_or_b32 s27, s14, s10
	s_lshl_b32 s14, s27, 9
	s_lshl_b32 s28, s26, 8
	s_or_b32 s14, s14, s28
	v_or_b32_e32 v0, s14, v146
	v_lshlrev_b32_e32 v0, 2, v0
	global_load_dword v2, v0, s[2:3]
	global_load_dword v4, v0, s[2:3] offset:256
	global_load_dword v10, v0, s[2:3] offset:512
	global_load_dword v11, v0, s[2:3] offset:768
	s_lshl_b32 s15, s15, 22
	s_bfe_u32 s28, s19, 0x30003
	v_readfirstlane_b32 s29, v148
	v_readfirstlane_b32 s30, v154
	s_or_b32 s28, s28, s21
	s_mov_b32 m0, s29
	v_readfirstlane_b32 s31, v155
	s_lshl_b32 s43, s28, 17
	s_lshl_b32 s10, s10, 21
	s_waitcnt vmcnt(0)
	s_barrier
	v_readfirstlane_b32 s34, v156
	s_or_b32 s10, s10, s43
	v_readfirstlane_b32 s35, v157
	s_bitset1_b32 s10, 25
	v_readfirstlane_b32 s36, v158
	v_lshl_add_u64 v[134:135], v[130:131], 0, s[10:11]
	v_mov_b32_e32 v1, v129
	v_readfirstlane_b32 s37, v159
	v_lshl_add_u64 v[136:137], v[132:133], 0, s[10:11]
	v_mov_b32_e32 v3, v129
	v_readfirstlane_b32 s38, v160
	v_mov_b32_e32 v5, v129
	v_readfirstlane_b32 s39, v161
	v_readfirstlane_b32 s40, v162
	v_readfirstlane_b32 s41, v163
	v_readfirstlane_b32 s42, v164
	v_lshl_add_u64 v[6:7], v[134:135], 0, 64
	v_lshl_add_u64 v[8:9], v[136:137], 0, 64
	s_mov_b32 s14, s11
	s_mov_b32 s29, s11
	v_mov_b32_e32 v16, 0
	v_mov_b32_e32 v17, v129
	v_mov_b32_e32 v18, v129
	v_mov_b32_e32 v19, v129
	v_mov_b32_e32 v20, v129
	v_mov_b32_e32 v21, v129
	v_mov_b32_e32 v22, v129
	v_mov_b32_e32 v23, v129
	v_mov_b32_e32 v24, v129
	v_mov_b32_e32 v25, v129
	v_mov_b32_e32 v26, v129
	v_mov_b32_e32 v27, v129
	v_mov_b32_e32 v28, v129
	v_mov_b32_e32 v29, v129
	v_mov_b32_e32 v30, v129
	v_mov_b32_e32 v31, v129
	v_mov_b32_e32 v32, 0
	v_mov_b32_e32 v33, v129
	v_mov_b32_e32 v34, v129
	v_mov_b32_e32 v35, v129
	v_mov_b32_e32 v36, v129
	v_mov_b32_e32 v37, v129
	v_mov_b32_e32 v38, v129
	v_mov_b32_e32 v39, v129
	v_mov_b32_e32 v40, v129
	v_mov_b32_e32 v41, v129
	v_mov_b32_e32 v42, v129
	v_mov_b32_e32 v43, v129
	v_mov_b32_e32 v44, v129
	v_mov_b32_e32 v45, v129
	v_mov_b32_e32 v46, v129
	v_mov_b32_e32 v47, v129
	v_mov_b32_e32 v48, 0
	v_mov_b32_e32 v49, v129
	v_mov_b32_e32 v50, v129
	v_mov_b32_e32 v51, v129
	v_mov_b32_e32 v52, v129
	v_mov_b32_e32 v53, v129
	v_mov_b32_e32 v54, v129
	v_mov_b32_e32 v55, v129
	v_mov_b32_e32 v56, v129
	v_mov_b32_e32 v57, v129
	v_mov_b32_e32 v58, v129
	s_waitcnt vmcnt(3)
	v_lshl_add_u32 v0, v2, 10, s15
	s_waitcnt vmcnt(2)
	v_lshl_add_u32 v2, v4, 10, s15
	v_or_b32_e32 v0, v0, v147
	s_waitcnt vmcnt(1)
	v_lshl_add_u32 v4, v10, 10, s15
	v_or_b32_e32 v2, v2, v147
	v_lshlrev_b32_e32 v128, 1, v0
	s_waitcnt vmcnt(0)
	v_lshl_add_u32 v10, v11, 10, s15
	v_or_b32_e32 v4, v4, v147
	v_lshlrev_b32_e32 v0, 1, v2
	s_nop 0
	s_mov_b32 m0, s30
	v_or_b32_e32 v10, v10, v147
	v_lshlrev_b32_e32 v2, 1, v4
	s_nop 0
	s_mov_b32 m0, s31
	v_lshlrev_b32_e32 v4, 1, v10
	s_nop 0
	s_mov_b32 m0, s34
	v_lshl_add_u64 v[138:139], s[4:5], 0, v[128:129]
	s_nop 0
	s_mov_b32 m0, s35
	v_lshl_add_u64 v[140:141], s[4:5], 0, v[0:1]
	s_nop 0
	s_mov_b32 m0, s36
	v_lshl_add_u64 v[0:1], v[138:139], 0, 64
	s_nop 0
	s_mov_b32 m0, s37
	v_lshl_add_u64 v[142:143], s[4:5], 0, v[2:3]
	v_lshl_add_u64 v[10:11], v[140:141], 0, 64
	s_nop 0
	s_mov_b32 m0, s38
	v_lshl_add_u64 v[144:145], s[4:5], 0, v[4:5]
	v_lshl_add_u64 v[12:13], v[142:143], 0, 64
	s_nop 0
	s_mov_b32 m0, s39
	v_lshl_add_u64 v[14:15], v[144:145], 0, 64
	s_nop 0
	s_mov_b32 m0, s40
	s_mov_b32 s15, 2
	s_nop 0
	s_mov_b32 m0, s41
	v_mov_b32_e32 v0, 0
	s_nop 0
	s_mov_b32 m0, s42
	v_mov_b32_e32 v1, v129
	s_nop 0
	v_mov_b32_e32 v2, v129
	v_mov_b32_e32 v4, v129
	v_mov_b32_e32 v6, v129
	v_mov_b32_e32 v7, v129
	v_mov_b32_e32 v8, v129
	v_mov_b32_e32 v9, v129
	v_mov_b32_e32 v10, v129
	v_mov_b32_e32 v11, v129
	v_mov_b32_e32 v12, v129
	v_mov_b32_e32 v13, v129
	v_mov_b32_e32 v14, v129
	v_mov_b32_e32 v15, v129
	v_mov_b32_e32 v59, v129
	v_mov_b32_e32 v60, v129
	v_mov_b32_e32 v61, v129
	v_mov_b32_e32 v62, v129
	v_mov_b32_e32 v63, v129
	v_mov_b32_e32 v64, 0
	v_mov_b32_e32 v65, v129
	v_mov_b32_e32 v66, v129
	v_mov_b32_e32 v67, v129
	v_mov_b32_e32 v68, v129
	v_mov_b32_e32 v69, v129
	v_mov_b32_e32 v70, v129
	v_mov_b32_e32 v71, v129
	v_mov_b32_e32 v72, v129
	v_mov_b32_e32 v73, v129
	v_mov_b32_e32 v74, v129
	v_mov_b32_e32 v75, v129
	v_mov_b32_e32 v76, v129
	v_mov_b32_e32 v77, v129
	v_mov_b32_e32 v78, v129
	v_mov_b32_e32 v79, v129
	v_mov_b32_e32 v80, 0
	v_mov_b32_e32 v81, v129
	v_mov_b32_e32 v82, v129
	v_mov_b32_e32 v83, v129
	v_mov_b32_e32 v84, v129
	v_mov_b32_e32 v85, v129
	v_mov_b32_e32 v86, v129
	v_mov_b32_e32 v87, v129
	v_mov_b32_e32 v88, v129
	v_mov_b32_e32 v89, v129
	v_mov_b32_e32 v90, v129
	v_mov_b32_e32 v91, v129
	v_mov_b32_e32 v92, v129
	v_mov_b32_e32 v93, v129
	v_mov_b32_e32 v94, v129
	v_mov_b32_e32 v95, v129
	v_mov_b32_e32 v96, 0
	v_mov_b32_e32 v97, v129
	v_mov_b32_e32 v98, v129
	v_mov_b32_e32 v99, v129
	v_mov_b32_e32 v100, v129
	v_mov_b32_e32 v101, v129
	v_mov_b32_e32 v102, v129
	v_mov_b32_e32 v103, v129
	v_mov_b32_e32 v104, v129
	v_mov_b32_e32 v105, v129
	v_mov_b32_e32 v106, v129
	v_mov_b32_e32 v107, v129
	v_mov_b32_e32 v108, v129
	v_mov_b32_e32 v109, v129
	v_mov_b32_e32 v110, v129
	v_mov_b32_e32 v111, v129
	v_mov_b32_e32 v112, 0
	v_mov_b32_e32 v113, v129
	v_mov_b32_e32 v114, v129
	v_mov_b32_e32 v115, v129
	v_mov_b32_e32 v116, v129
	v_mov_b32_e32 v117, v129
	v_mov_b32_e32 v118, v129
	v_mov_b32_e32 v119, v129
	v_mov_b32_e32 v120, v129
	v_mov_b32_e32 v121, v129
	v_mov_b32_e32 v122, v129
	v_mov_b32_e32 v123, v129
	v_mov_b32_e32 v124, v129
	v_mov_b32_e32 v125, v129
	v_mov_b32_e32 v126, v129
	v_mov_b32_e32 v127, v129
	s_mov_b64 s[54:55], 0x80
	v_lshrrev_b32_e32 v170, 6, v180
	v_lshlrev_b32_e32 v176, 11, v170
	v_mov_b32_e32 v171, 0x12000
	ds_read_b64 v[172:173], v171
	v_and_b32_e32 v166, 63, v180
	v_readfirstlane_b32 s53, v176
	v_lshrrev_b32_e32 v167, 5, v166
	v_bfe_u32 v168, v166, 1, 3
	v_xor_b32_e32 v168, v167, v168
	v_and_b32_e32 v169, 31, v166
	v_lshlrev_b32_e32 v169, 7, v169
	v_lshrrev_b32_e32 v169, 3, v166
	v_lshlrev_b32_e32 v176, 4, v169
	v_add_u32_e32 v177, 0x80, v176
	v_and_b32_e32 v169, 7, v166
	v_lshrrev_b32_e32 v167, 4, v166
	v_xor_b32_e32 v167, v169, v167
	v_lshrrev_b32_e32 v169, 5, v166
	v_sub_u32_e32 v182, v167, v169
	v_xor_b32_e32 v167, 4, v167
	v_add_u32_e32 v169, 2, v169
	v_sub_u32_e32 v184, v167, v169
	v_lshlrev_b32_e32 v182, 4, v182
	v_ashrrev_i32_e32 v183, 31, v182
	v_lshlrev_b32_e32 v184, 4, v184
	v_ashrrev_i32_e32 v185, 31, v184
	ds_bpermute_b32 v240, v176, v134
	ds_bpermute_b32 v241, v176, v135
	ds_bpermute_b32 v242, v177, v134
	ds_bpermute_b32 v243, v177, v135
	ds_bpermute_b32 v244, v176, v136
	ds_bpermute_b32 v245, v176, v137
	ds_bpermute_b32 v246, v177, v136
	ds_bpermute_b32 v247, v177, v137
	s_waitcnt lgkmcnt(0)
	ds_bpermute_b32 v178, v176, v138
	ds_bpermute_b32 v179, v176, v139
	ds_bpermute_b32 v230, v177, v138
	ds_bpermute_b32 v231, v177, v139
	ds_bpermute_b32 v232, v176, v140
	ds_bpermute_b32 v233, v176, v141
	ds_bpermute_b32 v234, v177, v140
	ds_bpermute_b32 v235, v177, v141
	ds_bpermute_b32 v236, v176, v142
	ds_bpermute_b32 v237, v176, v143
	ds_bpermute_b32 v238, v177, v142
	ds_bpermute_b32 v239, v177, v143
	ds_bpermute_b32 v134, v176, v144
	ds_bpermute_b32 v135, v176, v145
	ds_bpermute_b32 v136, v177, v144
	ds_bpermute_b32 v137, v177, v145
	s_waitcnt lgkmcnt(0)
	v_readfirstlane_b32 s56, v172
	v_readfirstlane_b32 s57, v173
	v_and_b32_e32 v169, 31, v166
	v_lshlrev_b32_e32 v169, 7, v169
	v_lshrrev_b32_e32 v167, 1, v170
	v_lshl_add_u32 v138, v167, 14, v169
	v_and_b32_e32 v167, 1, v170
	v_lshl_add_u32 v142, v167, 13, v169
	v_add_u32_e32 v142, 0x10000, v142
	v_xor_b32_e32 v169, 6, v168
	v_lshl_add_u32 v141, v169, 4, v138
	v_lshl_add_u32 v145, v169, 4, v142
	v_xor_b32_e32 v169, 4, v168
	v_lshl_add_u32 v140, v169, 4, v138
	v_lshl_add_u32 v144, v169, 4, v142
	v_xor_b32_e32 v169, 2, v168
	v_lshl_add_u32 v139, v169, 4, v138
	v_lshl_add_u32 v143, v169, 4, v142
	v_xor_b32_e32 v169, 0, v168
	v_lshl_add_u32 v138, v169, 4, v138
	v_lshl_add_u32 v142, v169, 4, v142
	v_lshl_add_u64 v[178:179], v[178:179], 0, v[182:183]
	v_lshl_add_u64 v[230:231], v[230:231], 0, v[184:185]
	v_lshl_add_u64 v[232:233], v[232:233], 0, v[182:183]
	v_lshl_add_u64 v[234:235], v[234:235], 0, v[184:185]
	v_lshl_add_u64 v[236:237], v[236:237], 0, v[182:183]
	v_lshl_add_u64 v[238:239], v[238:239], 0, v[184:185]
	v_lshl_add_u64 v[134:135], v[134:135], 0, v[182:183]
	v_lshl_add_u64 v[136:137], v[136:137], 0, v[184:185]
	v_lshl_add_u64 v[240:241], v[240:241], 0, v[182:183]
	v_lshl_add_u64 v[242:243], v[242:243], 0, v[184:185]
	v_lshl_add_u64 v[244:245], v[244:245], 0, v[182:183]
	v_lshl_add_u64 v[246:247], v[246:247], 0, v[184:185]
	s_mov_b32 s58, s53
	s_add_i32 m0, s58, 0x0
	s_nop 0
	global_load_lds_dwordx4 v[178:179], off
	s_add_i32 m0, s58, 0x400
	v_lshl_add_u64 v[178:179], v[178:179], 0, s[54:55]
	global_load_lds_dwordx4 v[230:231], off
	s_add_i32 m0, s58, 0x2000
	v_lshl_add_u64 v[230:231], v[230:231], 0, s[54:55]
	global_load_lds_dwordx4 v[232:233], off
	s_add_i32 m0, s58, 0x2400
	v_lshl_add_u64 v[232:233], v[232:233], 0, s[54:55]
	global_load_lds_dwordx4 v[234:235], off
	s_add_i32 m0, s58, 0x4000
	v_lshl_add_u64 v[234:235], v[234:235], 0, s[54:55]
	global_load_lds_dwordx4 v[236:237], off
	s_add_i32 m0, s58, 0x4400
	v_lshl_add_u64 v[236:237], v[236:237], 0, s[54:55]
	global_load_lds_dwordx4 v[238:239], off
	s_add_i32 m0, s58, 0x6000
	v_lshl_add_u64 v[238:239], v[238:239], 0, s[54:55]
	global_load_lds_dwordx4 v[134:135], off
	s_add_i32 m0, s58, 0x6400
	v_lshl_add_u64 v[134:135], v[134:135], 0, s[54:55]
	global_load_lds_dwordx4 v[136:137], off
	v_lshl_add_u64 v[136:137], v[136:137], 0, s[54:55]
	s_add_i32 s58, s53, 0x10000
	s_add_i32 m0, s58, 0x0
	s_nop 0
	global_load_lds_dwordx4 v[240:241], off
	s_add_i32 m0, s58, 0x400
	v_lshl_add_u64 v[240:241], v[240:241], 0, s[54:55]
	global_load_lds_dwordx4 v[242:243], off
	s_add_i32 m0, s58, 0x2000
	v_lshl_add_u64 v[242:243], v[242:243], 0, s[54:55]
	global_load_lds_dwordx4 v[244:245], off
	s_add_i32 m0, s58, 0x2400
	v_lshl_add_u64 v[244:245], v[244:245], 0, s[54:55]
	global_load_lds_dwordx4 v[246:247], off
	v_lshl_add_u64 v[246:247], v[246:247], 0, s[54:55]
	s_mov_b32 s14, 0
	s_mov_b32 s15, 0
.Lg_ph16_top:
	s_waitcnt vmcnt(0)
	s_waitcnt lgkmcnt(0)
	s_barrier
	s_cmp_eq_u32 s14, 15
	s_cbranch_scc1 .Lg_ph16_noA
	s_xor_b32 s58, s15, 0x8000
	s_add_i32 s58, s58, s53
	s_add_i32 m0, s58, 0x0
	s_nop 0
	global_load_lds_dwordx4 v[178:179], off
	s_add_i32 m0, s58, 0x400
	v_lshl_add_u64 v[178:179], v[178:179], 0, s[54:55]
	global_load_lds_dwordx4 v[230:231], off
	s_add_i32 m0, s58, 0x2000
	v_lshl_add_u64 v[230:231], v[230:231], 0, s[54:55]
	global_load_lds_dwordx4 v[232:233], off
	s_add_i32 m0, s58, 0x2400
	v_lshl_add_u64 v[232:233], v[232:233], 0, s[54:55]
	global_load_lds_dwordx4 v[234:235], off
	s_add_i32 m0, s58, 0x4000
	v_lshl_add_u64 v[234:235], v[234:235], 0, s[54:55]
	global_load_lds_dwordx4 v[236:237], off
	s_add_i32 m0, s58, 0x4400
	v_lshl_add_u64 v[236:237], v[236:237], 0, s[54:55]
	global_load_lds_dwordx4 v[238:239], off
	s_add_i32 m0, s58, 0x6000
	v_lshl_add_u64 v[238:239], v[238:239], 0, s[54:55]
	global_load_lds_dwordx4 v[134:135], off
	s_add_i32 m0, s58, 0x6400
	v_lshl_add_u64 v[134:135], v[134:135], 0, s[54:55]
	global_load_lds_dwordx4 v[136:137], off
	v_lshl_add_u64 v[136:137], v[136:137], 0, s[54:55]
.Lg_ph16_noA:
	ds_read_b128 v[186:189], v142
	ds_read_b128 v[190:193], v142 offset:4096
	ds_read_b128 v[194:197], v143
	ds_read_b128 v[198:201], v143 offset:4096
	ds_read_b128 v[202:205], v144
	ds_read_b128 v[218:221], v144 offset:4096
	ds_read_b128 v[222:225], v145
	ds_read_b128 v[226:229], v145 offset:4096
	ds_read_b128 v[166:169], v138
	ds_read_b128 v[170:173], v138 offset:4096
	ds_read_b128 v[174:177], v138 offset:8192
	ds_read_b128 v[182:185], v138 offset:12288
	s_waitcnt lgkmcnt(4)
	s_barrier
	s_cmp_eq_u32 s14, 15
	s_cbranch_scc1 .Lg_ph16_noB
	s_add_i32 s58, s53, 0x10000
	s_add_i32 m0, s58, 0x0
	s_nop 0
	global_load_lds_dwordx4 v[240:241], off
	s_add_i32 m0, s58, 0x400
	v_lshl_add_u64 v[240:241], v[240:241], 0, s[54:55]
	global_load_lds_dwordx4 v[242:243], off
	s_add_i32 m0, s58, 0x2000
	v_lshl_add_u64 v[242:243], v[242:243], 0, s[54:55]
	global_load_lds_dwordx4 v[244:245], off
	s_add_i32 m0, s58, 0x2400
	v_lshl_add_u64 v[244:245], v[244:245], 0, s[54:55]
	global_load_lds_dwordx4 v[246:247], off
	v_lshl_add_u64 v[246:247], v[246:247], 0, s[54:55]
.Lg_ph16_noB:
	s_waitcnt lgkmcnt(3)
	v_mfma_f32_32x32x16_bf16 v[0:15], v[166:169], v[186:189], v[0:15]
	v_mfma_f32_32x32x16_bf16 v[16:31], v[166:169], v[190:193], v[16:31]
	ds_read_b128 v[166:169], v139
	s_waitcnt lgkmcnt(3)
	v_mfma_f32_32x32x16_bf16 v[32:47], v[170:173], v[186:189], v[32:47]
	v_mfma_f32_32x32x16_bf16 v[48:63], v[170:173], v[190:193], v[48:63]
	ds_read_b128 v[170:173], v139 offset:4096
	s_waitcnt lgkmcnt(3)
	v_mfma_f32_32x32x16_bf16 v[64:79], v[174:177], v[186:189], v[64:79]
	v_mfma_f32_32x32x16_bf16 v[80:95], v[174:177], v[190:193], v[80:95]
	ds_read_b128 v[174:177], v139 offset:8192
	s_waitcnt lgkmcnt(3)
	v_mfma_f32_32x32x16_bf16 v[96:111], v[182:185], v[186:189], v[96:111]
	v_mfma_f32_32x32x16_bf16 v[112:127], v[182:185], v[190:193], v[112:127]
	ds_read_b128 v[182:185], v139 offset:12288
	s_waitcnt lgkmcnt(3)
	v_mfma_f32_32x32x16_bf16 v[0:15], v[166:169], v[194:197], v[0:15]
	v_mfma_f32_32x32x16_bf16 v[16:31], v[166:169], v[198:201], v[16:31]
	ds_read_b128 v[166:169], v140
	s_waitcnt lgkmcnt(3)
	v_mfma_f32_32x32x16_bf16 v[32:47], v[170:173], v[194:197], v[32:47]
	v_mfma_f32_32x32x16_bf16 v[48:63], v[170:173], v[198:201], v[48:63]
	ds_read_b128 v[170:173], v140 offset:4096
	s_waitcnt lgkmcnt(3)
	v_mfma_f32_32x32x16_bf16 v[64:79], v[174:177], v[194:197], v[64:79]
	v_mfma_f32_32x32x16_bf16 v[80:95], v[174:177], v[198:201], v[80:95]
	ds_read_b128 v[174:177], v140 offset:8192
	s_waitcnt lgkmcnt(3)
	v_mfma_f32_32x32x16_bf16 v[96:111], v[182:185], v[194:197], v[96:111]
	v_mfma_f32_32x32x16_bf16 v[112:127], v[182:185], v[198:201], v[112:127]
	ds_read_b128 v[182:185], v140 offset:12288
	s_waitcnt lgkmcnt(3)
	v_mfma_f32_32x32x16_bf16 v[0:15], v[166:169], v[202:205], v[0:15]
	v_mfma_f32_32x32x16_bf16 v[16:31], v[166:169], v[218:221], v[16:31]
	ds_read_b128 v[166:169], v141
	s_waitcnt lgkmcnt(3)
	v_mfma_f32_32x32x16_bf16 v[32:47], v[170:173], v[202:205], v[32:47]
	v_mfma_f32_32x32x16_bf16 v[48:63], v[170:173], v[218:221], v[48:63]
	ds_read_b128 v[170:173], v141 offset:4096
	s_waitcnt lgkmcnt(3)
	v_mfma_f32_32x32x16_bf16 v[64:79], v[174:177], v[202:205], v[64:79]
	v_mfma_f32_32x32x16_bf16 v[80:95], v[174:177], v[218:221], v[80:95]
	ds_read_b128 v[174:177], v141 offset:8192
	s_waitcnt lgkmcnt(3)
	v_mfma_f32_32x32x16_bf16 v[96:111], v[182:185], v[202:205], v[96:111]
	v_mfma_f32_32x32x16_bf16 v[112:127], v[182:185], v[218:221], v[112:127]
	ds_read_b128 v[182:185], v141 offset:12288
	s_waitcnt lgkmcnt(3)
	v_mfma_f32_32x32x16_bf16 v[0:15], v[166:169], v[222:225], v[0:15]
	v_mfma_f32_32x32x16_bf16 v[16:31], v[166:169], v[226:229], v[16:31]
	s_waitcnt lgkmcnt(2)
	v_mfma_f32_32x32x16_bf16 v[32:47], v[170:173], v[222:225], v[32:47]
	v_mfma_f32_32x32x16_bf16 v[48:63], v[170:173], v[226:229], v[48:63]
	s_waitcnt lgkmcnt(1)
	v_mfma_f32_32x32x16_bf16 v[64:79], v[174:177], v[222:225], v[64:79]
	v_mfma_f32_32x32x16_bf16 v[80:95], v[174:177], v[226:229], v[80:95]
	s_waitcnt lgkmcnt(0)
	v_mfma_f32_32x32x16_bf16 v[96:111], v[182:185], v[222:225], v[96:111]
	v_mfma_f32_32x32x16_bf16 v[112:127], v[182:185], v[226:229], v[112:127]
	v_xor_b32_e32 v138, 0x8000, v138
	v_xor_b32_e32 v139, 0x8000, v139
	v_xor_b32_e32 v140, 0x8000, v140
	v_xor_b32_e32 v141, 0x8000, v141
	s_xor_b32 s15, s15, 0x8000
	s_add_i32 s14, s14, 1
	s_cmp_eq_u32 s14, 16
	s_cbranch_scc0 .Lg_ph16_top
	v_mov_b32_e32 v171, 0x12000
	v_mov_b32_e32 v172, s56
	v_mov_b32_e32 v173, s57
	ds_write_b64 v171, v[172:173]
	s_waitcnt vmcnt(0)
	v_mov_b32_e32 v128, v180
	v_add_u32_e32 v192, 0x400, v153
	v_add_u32_e32 v191, 0x1000, v153
	v_add_u32_e32 v190, 0x1400, v153
	v_add_u32_e32 v189, 0x2000, v153
	v_add_u32_e32 v183, 0x2400, v153
	v_add_u32_e32 v184, 0x3000, v153
	v_add_u32_e32 v185, 0x3200, v153
	v_add_u32_e32 v186, 0x3400, v153
	v_add_u32_e32 v187, 0x3600, v153
	v_add_u32_e32 v188, 0x4000, v153
	v_add_u32_e32 v179, 0x4400, v153
	v_add_u32_e32 v181, 0x4800, v153
	v_add_u32_e32 v182, 0x5000, v153
	v_add_u32_e32 v176, 0x5400, v153
	v_add_u32_e32 v177, 0x5800, v153
	v_add_u32_e32 v178, 0x6000, v153
	v_add_u32_e32 v170, 0x6400, v153
	v_add_u32_e32 v171, 0x6800, v153
	v_add_u32_e32 v172, 0x7200, v153
	v_add_u32_e32 v173, 0x7400, v153
	v_add_u32_e32 v174, 0x7600, v153
	v_add_u32_e32 v175, 0x7800, v153
	v_add_u32_e32 v169, 0x8400, v153
	v_add_u32_e32 v168, 0x8800, v153
	v_add_u32_e32 v167, 0x9400, v153
	v_add_u32_e32 v166, 0x9800, v153
	v_add_u32_e32 v145, 0xa400, v153
	v_add_u32_e32 v140, 0xa800, v153
	v_add_u32_e32 v141, 0xb400, v153
	v_add_u32_e32 v142, 0xb600, v153
	v_add_u32_e32 v143, 0xb800, v153
	v_add_u32_e32 v144, 0xba00, v153
	s_waitcnt vmcnt(0)
	s_barrier
	s_and_saveexec_b64 s[14:15], s[6:7]
	s_cbranch_execz .LBB0_1674
	v_add_u32_e32 v134, 0xc400, v153
	ds_write2_b32 v153, v0, v16 offset1:32
	ds_write2_b32 v153, v1, v17 offset0:132 offset1:164
	ds_write2_b32 v192, v2, v18 offset0:8 offset1:40
	ds_write2_b32 v192, v3, v19 offset0:140 offset1:172
	ds_write2_b32 v191, v4, v20 offset0:32 offset1:64
	ds_write2_b32 v191, v5, v21 offset0:164 offset1:196
	ds_write2_b32 v190, v6, v22 offset0:40 offset1:72
	ds_write2_b32 v190, v7, v23 offset0:172 offset1:204
	ds_write2_b32 v189, v8, v24 offset0:64 offset1:96
	ds_write2_b32 v189, v9, v25 offset0:196 offset1:228
	ds_write2_b32 v183, v10, v26 offset0:72 offset1:104
	ds_write2_b32 v183, v11, v27 offset0:204 offset1:236
	ds_write2_b32 v184, v12, v28 offset0:96 offset1:128
	ds_write2_b32 v185, v13, v29 offset0:100 offset1:132
	ds_write2_b32 v186, v14, v30 offset0:104 offset1:136
	ds_write2_b32 v187, v15, v31 offset0:108 offset1:140
	ds_write2_b32 v188, v32, v48 offset0:128 offset1:160
	ds_write2_b32 v179, v33, v49 offset0:4 offset1:36
	ds_write2_b32 v179, v34, v50 offset0:136 offset1:168
	ds_write2_b32 v181, v35, v51 offset0:12 offset1:44
	ds_write2_b32 v182, v36, v52 offset0:160 offset1:192
	ds_write2_b32 v176, v37, v53 offset0:36 offset1:68
	ds_write2_b32 v176, v38, v54 offset0:168 offset1:200
	ds_write2_b32 v177, v39, v55 offset0:44 offset1:76
	ds_write2_b32 v178, v40, v56 offset0:192 offset1:224
	ds_write2_b32 v170, v41, v57 offset0:68 offset1:100
	ds_write2_b32 v170, v42, v58 offset0:200 offset1:232
	ds_write2_b32 v171, v43, v59 offset0:76 offset1:108
	ds_write2_b32 v172, v44, v60 offset0:96 offset1:128
	ds_write2_b32 v173, v45, v61 offset0:100 offset1:132
	ds_write2_b32 v174, v46, v62 offset0:104 offset1:136
	ds_write2_b32 v175, v47, v63 offset0:108 offset1:140
	ds_write2_b32 v169, v64, v80 offset1:32
	ds_write2_b32 v169, v65, v81 offset0:132 offset1:164
	ds_write2_b32 v168, v66, v82 offset0:8 offset1:40
	ds_write2_b32 v168, v67, v83 offset0:140 offset1:172
	ds_write2_b32 v167, v68, v84 offset0:32 offset1:64
	ds_write2_b32 v167, v69, v85 offset0:164 offset1:196
	ds_write2_b32 v166, v70, v86 offset0:40 offset1:72
	ds_write2_b32 v166, v71, v87 offset0:172 offset1:204
	ds_write2_b32 v145, v72, v88 offset0:64 offset1:96
	ds_write2_b32 v145, v73, v89 offset0:196 offset1:228
	ds_write2_b32 v140, v74, v90 offset0:72 offset1:104
	ds_write2_b32 v140, v75, v91 offset0:204 offset1:236
	ds_write2_b32 v141, v76, v92 offset0:96 offset1:128
	ds_write2_b32 v142, v77, v93 offset0:100 offset1:132
	ds_write2_b32 v143, v78, v94 offset0:104 offset1:136
	ds_write2_b32 v144, v79, v95 offset0:108 offset1:140
	ds_write2_b32 v134, v96, v112 offset0:128 offset1:160
	v_add_u32_e32 v134, 0xc800, v153
	ds_write2_b32 v134, v97, v113 offset0:4 offset1:36
	ds_write2_b32 v134, v98, v114 offset0:136 offset1:168
	v_add_u32_e32 v134, 0xcc00, v153
	ds_write2_b32 v134, v99, v115 offset0:12 offset1:44
	v_add_u32_e32 v134, 0xd400, v153
	ds_write2_b32 v134, v100, v116 offset0:160 offset1:192
	v_add_u32_e32 v134, 0xd800, v153
	ds_write2_b32 v134, v101, v117 offset0:36 offset1:68
	ds_write2_b32 v134, v102, v118 offset0:168 offset1:200
	v_add_u32_e32 v134, 0xdc00, v153
	ds_write2_b32 v134, v103, v119 offset0:44 offset1:76
	v_add_u32_e32 v134, 0xe400, v153
	ds_write2_b32 v134, v104, v120 offset0:192 offset1:224
	v_add_u32_e32 v134, 0xe800, v153
	ds_write2_b32 v134, v105, v121 offset0:68 offset1:100
	ds_write2_b32 v134, v106, v122 offset0:200 offset1:232
	v_add_u32_e32 v134, 0xec00, v153
	ds_write2_b32 v134, v107, v123 offset0:76 offset1:108
	v_add_u32_e32 v134, 0xf600, v153
	ds_write2_b32 v134, v108, v124 offset0:96 offset1:128
	v_add_u32_e32 v134, 0xf800, v153
	ds_write2_b32 v134, v109, v125 offset0:100 offset1:132
	v_add_u32_e32 v134, 0xfa00, v153
	ds_write2_b32 v134, v110, v126 offset0:104 offset1:136
	v_add_u32_e32 v134, 0xfc00, v153
	ds_write2_b32 v134, v111, v127 offset0:108 offset1:140

.LBB0_1736:
	s_lshr_b32 s4, s30, 3
	s_and_b32 s4, s4, 8
	s_lshl_b32 s20, s30, 3
	s_or_b32 s4, s4, s28
	s_and_b32 s37, s30, 1
	s_and_b32 s20, s20, 48
	s_or_b32 s38, s4, s20
	s_lshl_b32 s22, s37, 8
	s_lshl_b32 s20, s30, 4
	s_lshl_b32 s23, s38, 9
	v_or_b32_e32 v0, s22, v129
	s_and_b32 s39, s20, 0x380
	v_or_b32_e32 v0, s23, v0
	s_lshl_b32 s20, s39, 11
	s_lshl_b32 s4, s4, 21
	v_lshlrev_b32_e32 v1, 10, v0
	s_or_b32 s4, s4, s20
	s_add_u32 s20, s94, s4
	v_or_b32_e32 v0, v1, v128
	v_readfirstlane_b32 s4, v152
	v_lshlrev_b32_e32 v130, 1, v0
	s_mov_b32 m0, s4
	v_readfirstlane_b32 s4, v161
	s_addc_u32 s21, s95, 0
	v_add_lshl_u32 v0, v1, v158, 1
	s_waitcnt vmcnt(0)
	s_barrier
	s_nop 0
	s_mov_b32 m0, s4
	v_readfirstlane_b32 s4, v162
	v_add_lshl_u32 v2, v1, v159, 1
	v_lshl_add_u64 v[6:7], s[20:21], 0, v[132:133]
	s_nop 0
	s_mov_b32 m0, s4
	v_readfirstlane_b32 s4, v163
	v_add_lshl_u32 v4, v1, v160, 1
	v_lshl_add_u64 v[6:7], v[6:7], 0, v[134:135]
	s_nop 0
	s_mov_b32 m0, s4
	v_readfirstlane_b32 s4, v164
	v_lshl_add_u64 v[136:137], v[6:7], 0, s[10:11]
	s_nop 0
	s_mov_b32 m0, s4
	v_readfirstlane_b32 s4, v165
	v_lshl_add_u64 v[138:139], s[2:3], 0, v[130:131]
	v_mov_b32_e32 v1, v131
	v_lshl_add_u64 v[146:147], v[6:7], 0, s[12:13]
	s_nop 0
	s_mov_b32 m0, s4
	v_readfirstlane_b32 s4, v166
	v_lshl_add_u64 v[140:141], s[2:3], 0, v[0:1]
	v_mov_b32_e32 v3, v131
	s_nop 0
	v_lshl_add_u64 v[0:1], v[138:139], 0, 64
	s_mov_b32 m0, s4
	v_readfirstlane_b32 s4, v167
	v_lshl_add_u64 v[142:143], s[2:3], 0, v[2:3]
	v_mov_b32_e32 v5, v131
	s_nop 0
	v_lshl_add_u64 v[0:1], v[140:141], 0, 64
	s_mov_b32 m0, s4
	v_readfirstlane_b32 s4, v168
	v_lshl_add_u64 v[144:145], s[2:3], 0, v[4:5]
	s_nop 0
	v_lshl_add_u64 v[0:1], v[142:143], 0, 64
	s_mov_b32 m0, s4
	v_readfirstlane_b32 s4, v169
	s_nop 0
	v_lshl_add_u64 v[0:1], v[144:145], 0, 64
	s_mov_b32 m0, s4
	v_readfirstlane_b32 s4, v170
	s_nop 0
	v_lshl_add_u64 v[0:1], v[6:7], 0, s[14:15]
	s_mov_b32 m0, s4
	v_readfirstlane_b32 s4, v171
	s_nop 0
	v_lshl_add_u64 v[0:1], v[6:7], 0, s[16:17]
	s_mov_b32 m0, s4
	s_mov_b32 s20, s5
	s_nop 0
	s_mov_b32 s21, 2
	s_mov_b32 s40, s5
	v_mov_b32_e32 v0, 0
	v_mov_b32_e32 v1, v131
	v_mov_b32_e32 v2, v131
	v_mov_b32_e32 v4, v131
	v_mov_b32_e32 v6, v131
	v_mov_b32_e32 v7, v131
	v_mov_b32_e32 v8, v131
	v_mov_b32_e32 v9, v131
	v_mov_b32_e32 v10, v131
	v_mov_b32_e32 v11, v131
	v_mov_b32_e32 v12, v131
	v_mov_b32_e32 v13, v131
	v_mov_b32_e32 v14, v131
	v_mov_b32_e32 v15, v131
	v_mov_b32_e32 v16, 0
	v_mov_b32_e32 v17, v131
	v_mov_b32_e32 v18, v131
	v_mov_b32_e32 v19, v131
	v_mov_b32_e32 v20, v131
	v_mov_b32_e32 v21, v131
	v_mov_b32_e32 v22, v131
	v_mov_b32_e32 v23, v131
	v_mov_b32_e32 v24, v131
	v_mov_b32_e32 v25, v131
	v_mov_b32_e32 v26, v131
	v_mov_b32_e32 v27, v131
	v_mov_b32_e32 v28, v131
	v_mov_b32_e32 v29, v131
	v_mov_b32_e32 v30, v131
	v_mov_b32_e32 v31, v131
	v_mov_b32_e32 v32, 0
	v_mov_b32_e32 v33, v131
	v_mov_b32_e32 v34, v131
	v_mov_b32_e32 v35, v131
	v_mov_b32_e32 v36, v131
	v_mov_b32_e32 v37, v131
	v_mov_b32_e32 v38, v131
	v_mov_b32_e32 v39, v131
	v_mov_b32_e32 v40, v131
	v_mov_b32_e32 v41, v131
	v_mov_b32_e32 v42, v131
	v_mov_b32_e32 v43, v131
	v_mov_b32_e32 v44, v131
	v_mov_b32_e32 v45, v131
	v_mov_b32_e32 v46, v131
	v_mov_b32_e32 v47, v131
	v_mov_b32_e32 v48, 0
	v_mov_b32_e32 v49, v131
	v_mov_b32_e32 v50, v131
	v_mov_b32_e32 v51, v131
	v_mov_b32_e32 v52, v131
	v_mov_b32_e32 v53, v131
	v_mov_b32_e32 v54, v131
	v_mov_b32_e32 v55, v131
	v_mov_b32_e32 v56, v131
	v_mov_b32_e32 v57, v131
	v_mov_b32_e32 v58, v131
	v_mov_b32_e32 v59, v131
	v_mov_b32_e32 v60, v131
	v_mov_b32_e32 v61, v131
	v_mov_b32_e32 v62, v131
	v_mov_b32_e32 v63, v131
	v_mov_b32_e32 v64, 0
	v_mov_b32_e32 v65, v131
	v_mov_b32_e32 v66, v131
	v_mov_b32_e32 v67, v131
	v_mov_b32_e32 v68, v131
	v_mov_b32_e32 v69, v131
	v_mov_b32_e32 v70, v131
	v_mov_b32_e32 v71, v131
	v_mov_b32_e32 v72, v131
	v_mov_b32_e32 v73, v131
	v_mov_b32_e32 v74, v131
	v_mov_b32_e32 v75, v131
	v_mov_b32_e32 v76, v131
	v_mov_b32_e32 v77, v131
	v_mov_b32_e32 v78, v131
	v_mov_b32_e32 v79, v131
	v_mov_b32_e32 v80, 0
	v_mov_b32_e32 v81, v131
	v_mov_b32_e32 v82, v131
	v_mov_b32_e32 v83, v131
	v_mov_b32_e32 v84, v131
	v_mov_b32_e32 v85, v131
	v_mov_b32_e32 v86, v131
	v_mov_b32_e32 v87, v131
	v_mov_b32_e32 v88, v131
	v_mov_b32_e32 v89, v131
	v_mov_b32_e32 v90, v131
	v_mov_b32_e32 v91, v131
	v_mov_b32_e32 v92, v131
	v_mov_b32_e32 v93, v131
	v_mov_b32_e32 v94, v131
	v_mov_b32_e32 v95, v131
	v_mov_b32_e32 v96, 0
	v_mov_b32_e32 v97, v131
	v_mov_b32_e32 v98, v131
	v_mov_b32_e32 v99, v131
	v_mov_b32_e32 v100, v131
	v_mov_b32_e32 v101, v131
	v_mov_b32_e32 v102, v131
	v_mov_b32_e32 v103, v131
	v_mov_b32_e32 v104, v131
	v_mov_b32_e32 v105, v131
	v_mov_b32_e32 v106, v131
	v_mov_b32_e32 v107, v131
	v_mov_b32_e32 v108, v131
	v_mov_b32_e32 v109, v131
	v_mov_b32_e32 v110, v131
	v_mov_b32_e32 v111, v131
	v_mov_b32_e32 v112, 0
	v_mov_b32_e32 v113, v131
	v_mov_b32_e32 v114, v131
	v_mov_b32_e32 v115, v131
	v_mov_b32_e32 v116, v131
	v_mov_b32_e32 v117, v131
	v_mov_b32_e32 v118, v131
	v_mov_b32_e32 v119, v131
	v_mov_b32_e32 v120, v131
	v_mov_b32_e32 v121, v131
	v_mov_b32_e32 v122, v131
	v_mov_b32_e32 v123, v131
	v_mov_b32_e32 v124, v131
	v_mov_b32_e32 v125, v131
	v_mov_b32_e32 v126, v131
	v_mov_b32_e32 v127, v131
	s_mov_b64 s[54:55], 0x80
	v_lshrrev_b32_e32 v174, 6, v180
	v_lshlrev_b32_e32 v184, 11, v174
	v_mov_b32_e32 v175, 0x12000
	ds_read_b64 v[176:177], v175
	v_and_b32_e32 v148, 63, v180
	v_readfirstlane_b32 s53, v184
	v_lshrrev_b32_e32 v149, 5, v148
	v_bfe_u32 v150, v148, 1, 3
	v_xor_b32_e32 v150, v149, v150
	v_and_b32_e32 v151, 31, v148
	v_lshlrev_b32_e32 v151, 7, v151
	v_lshrrev_b32_e32 v151, 3, v148
	v_lshlrev_b32_e32 v184, 4, v151
	v_add_u32_e32 v185, 0x80, v184
	v_and_b32_e32 v151, 7, v148
	v_lshrrev_b32_e32 v149, 4, v148
	v_xor_b32_e32 v149, v151, v149
	v_lshrrev_b32_e32 v151, 5, v148
	v_sub_u32_e32 v186, v149, v151
	v_xor_b32_e32 v149, 4, v149
	v_add_u32_e32 v151, 2, v151
	v_sub_u32_e32 v188, v149, v151
	v_lshlrev_b32_e32 v186, 4, v186
	v_ashrrev_i32_e32 v187, 31, v186
	v_lshlrev_b32_e32 v188, 4, v188
	v_ashrrev_i32_e32 v189, 31, v188
	ds_bpermute_b32 v246, v184, v136
	ds_bpermute_b32 v247, v184, v137
	ds_bpermute_b32 v248, v185, v136
	ds_bpermute_b32 v249, v185, v137
	ds_bpermute_b32 v250, v184, v146
	ds_bpermute_b32 v251, v184, v147
	ds_bpermute_b32 v252, v185, v146
	ds_bpermute_b32 v253, v185, v147
	s_waitcnt lgkmcnt(0)
	ds_bpermute_b32 v178, v184, v138
	ds_bpermute_b32 v179, v184, v139
	ds_bpermute_b32 v236, v185, v138
	ds_bpermute_b32 v237, v185, v139
	ds_bpermute_b32 v238, v184, v140
	ds_bpermute_b32 v239, v184, v141
	ds_bpermute_b32 v240, v185, v140
	ds_bpermute_b32 v241, v185, v141
	ds_bpermute_b32 v242, v184, v142
	ds_bpermute_b32 v243, v184, v143
	ds_bpermute_b32 v244, v185, v142
	ds_bpermute_b32 v245, v185, v143
	ds_bpermute_b32 v136, v184, v144
	ds_bpermute_b32 v137, v184, v145
	ds_bpermute_b32 v146, v185, v144
	ds_bpermute_b32 v147, v185, v145
	s_waitcnt lgkmcnt(0)
	v_readfirstlane_b32 s56, v176
	v_readfirstlane_b32 s57, v177
	v_and_b32_e32 v151, 31, v148
	v_lshlrev_b32_e32 v151, 7, v151
	v_lshrrev_b32_e32 v149, 1, v174
	v_lshl_add_u32 v138, v149, 14, v151
	v_and_b32_e32 v149, 1, v174
	v_lshl_add_u32 v142, v149, 13, v151
	v_add_u32_e32 v142, 0x10000, v142
	v_xor_b32_e32 v151, 6, v150
	v_lshl_add_u32 v141, v151, 4, v138
	v_lshl_add_u32 v145, v151, 4, v142
	v_xor_b32_e32 v151, 4, v150
	v_lshl_add_u32 v140, v151, 4, v138
	v_lshl_add_u32 v144, v151, 4, v142
	v_xor_b32_e32 v151, 2, v150
	v_lshl_add_u32 v139, v151, 4, v138
	v_lshl_add_u32 v143, v151, 4, v142
	v_xor_b32_e32 v151, 0, v150
	v_lshl_add_u32 v138, v151, 4, v138
	v_lshl_add_u32 v142, v151, 4, v142
	v_lshl_add_u64 v[178:179], v[178:179], 0, v[186:187]
	v_lshl_add_u64 v[236:237], v[236:237], 0, v[188:189]
	v_lshl_add_u64 v[238:239], v[238:239], 0, v[186:187]
	v_lshl_add_u64 v[240:241], v[240:241], 0, v[188:189]
	v_lshl_add_u64 v[242:243], v[242:243], 0, v[186:187]
	v_lshl_add_u64 v[244:245], v[244:245], 0, v[188:189]
	v_lshl_add_u64 v[136:137], v[136:137], 0, v[186:187]
	v_lshl_add_u64 v[146:147], v[146:147], 0, v[188:189]
	v_lshl_add_u64 v[246:247], v[246:247], 0, v[186:187]
	v_lshl_add_u64 v[248:249], v[248:249], 0, v[188:189]
	v_lshl_add_u64 v[250:251], v[250:251], 0, v[186:187]
	v_lshl_add_u64 v[252:253], v[252:253], 0, v[188:189]
	s_mov_b32 s58, s53
	s_add_i32 m0, s58, 0x0
	s_nop 0
	global_load_lds_dwordx4 v[178:179], off
	s_add_i32 m0, s58, 0x400
	v_lshl_add_u64 v[178:179], v[178:179], 0, s[54:55]
	global_load_lds_dwordx4 v[236:237], off
	s_add_i32 m0, s58, 0x2000
	v_lshl_add_u64 v[236:237], v[236:237], 0, s[54:55]
	global_load_lds_dwordx4 v[238:239], off
	s_add_i32 m0, s58, 0x2400
	v_lshl_add_u64 v[238:239], v[238:239], 0, s[54:55]
	global_load_lds_dwordx4 v[240:241], off
	s_add_i32 m0, s58, 0x4000
	v_lshl_add_u64 v[240:241], v[240:241], 0, s[54:55]
	global_load_lds_dwordx4 v[242:243], off
	s_add_i32 m0, s58, 0x4400
	v_lshl_add_u64 v[242:243], v[242:243], 0, s[54:55]
	global_load_lds_dwordx4 v[244:245], off
	s_add_i32 m0, s58, 0x6000
	v_lshl_add_u64 v[244:245], v[244:245], 0, s[54:55]
	global_load_lds_dwordx4 v[136:137], off
	s_add_i32 m0, s58, 0x6400
	v_lshl_add_u64 v[136:137], v[136:137], 0, s[54:55]
	global_load_lds_dwordx4 v[146:147], off
	v_lshl_add_u64 v[146:147], v[146:147], 0, s[54:55]
	s_add_i32 s58, s53, 0x10000
	s_add_i32 m0, s58, 0x0
	s_nop 0
	global_load_lds_dwordx4 v[246:247], off
	s_add_i32 m0, s58, 0x400
	v_lshl_add_u64 v[246:247], v[246:247], 0, s[54:55]
	global_load_lds_dwordx4 v[248:249], off
	s_add_i32 m0, s58, 0x2000
	v_lshl_add_u64 v[248:249], v[248:249], 0, s[54:55]
	global_load_lds_dwordx4 v[250:251], off
	s_add_i32 m0, s58, 0x2400
	v_lshl_add_u64 v[250:251], v[250:251], 0, s[54:55]
	global_load_lds_dwordx4 v[252:253], off
	v_lshl_add_u64 v[252:253], v[252:253], 0, s[54:55]
	s_mov_b32 s20, 0
	s_mov_b32 s21, 0
.Lg_ph17_top:
	s_waitcnt vmcnt(0)
	s_waitcnt lgkmcnt(0)
	s_barrier
	s_cmp_eq_u32 s20, 15
	s_cbranch_scc1 .Lg_ph17_noA
	s_xor_b32 s58, s21, 0x8000
	s_add_i32 s58, s58, s53
	s_add_i32 m0, s58, 0x0
	s_nop 0
	global_load_lds_dwordx4 v[178:179], off
	s_add_i32 m0, s58, 0x400
	v_lshl_add_u64 v[178:179], v[178:179], 0, s[54:55]
	global_load_lds_dwordx4 v[236:237], off
	s_add_i32 m0, s58, 0x2000
	v_lshl_add_u64 v[236:237], v[236:237], 0, s[54:55]
	global_load_lds_dwordx4 v[238:239], off
	s_add_i32 m0, s58, 0x2400
	v_lshl_add_u64 v[238:239], v[238:239], 0, s[54:55]
	global_load_lds_dwordx4 v[240:241], off
	s_add_i32 m0, s58, 0x4000
	v_lshl_add_u64 v[240:241], v[240:241], 0, s[54:55]
	global_load_lds_dwordx4 v[242:243], off
	s_add_i32 m0, s58, 0x4400
	v_lshl_add_u64 v[242:243], v[242:243], 0, s[54:55]
	global_load_lds_dwordx4 v[244:245], off
	s_add_i32 m0, s58, 0x6000
	v_lshl_add_u64 v[244:245], v[244:245], 0, s[54:55]
	global_load_lds_dwordx4 v[136:137], off
	s_add_i32 m0, s58, 0x6400
	v_lshl_add_u64 v[136:137], v[136:137], 0, s[54:55]
	global_load_lds_dwordx4 v[146:147], off
	v_lshl_add_u64 v[146:147], v[146:147], 0, s[54:55]
.Lg_ph17_noA:
	ds_read_b128 v[190:193], v142
	ds_read_b128 v[194:197], v142 offset:4096
	ds_read_b128 v[198:201], v143
	ds_read_b128 v[202:205], v143 offset:4096
	ds_read_b128 v[206:209], v144
	ds_read_b128 v[224:227], v144 offset:4096
	ds_read_b128 v[228:231], v145
	ds_read_b128 v[232:235], v145 offset:4096
	ds_read_b128 v[148:151], v138
	ds_read_b128 v[174:177], v138 offset:4096
	ds_read_b128 v[182:185], v138 offset:8192
	ds_read_b128 v[186:189], v138 offset:12288
	s_waitcnt lgkmcnt(4)
	s_barrier
	s_cmp_eq_u32 s20, 15
	s_cbranch_scc1 .Lg_ph17_noB
	s_add_i32 s58, s53, 0x10000
	s_add_i32 m0, s58, 0x0
	s_nop 0
	global_load_lds_dwordx4 v[246:247], off
	s_add_i32 m0, s58, 0x400
	v_lshl_add_u64 v[246:247], v[246:247], 0, s[54:55]
	global_load_lds_dwordx4 v[248:249], off
	s_add_i32 m0, s58, 0x2000
	v_lshl_add_u64 v[248:249], v[248:249], 0, s[54:55]
	global_load_lds_dwordx4 v[250:251], off
	s_add_i32 m0, s58, 0x2400
	v_lshl_add_u64 v[250:251], v[250:251], 0, s[54:55]
	global_load_lds_dwordx4 v[252:253], off
	v_lshl_add_u64 v[252:253], v[252:253], 0, s[54:55]
.Lg_ph17_noB:
	s_waitcnt lgkmcnt(3)
	v_mfma_f32_32x32x16_bf16 v[0:15], v[148:151], v[190:193], v[0:15]
	v_mfma_f32_32x32x16_bf16 v[16:31], v[148:151], v[194:197], v[16:31]
	ds_read_b128 v[148:151], v139
	s_waitcnt lgkmcnt(3)
	v_mfma_f32_32x32x16_bf16 v[32:47], v[174:177], v[190:193], v[32:47]
	v_mfma_f32_32x32x16_bf16 v[48:63], v[174:177], v[194:197], v[48:63]
	ds_read_b128 v[174:177], v139 offset:4096
	s_waitcnt lgkmcnt(3)
	v_mfma_f32_32x32x16_bf16 v[64:79], v[182:185], v[190:193], v[64:79]
	v_mfma_f32_32x32x16_bf16 v[80:95], v[182:185], v[194:197], v[80:95]
	ds_read_b128 v[182:185], v139 offset:8192
	s_waitcnt lgkmcnt(3)
	v_mfma_f32_32x32x16_bf16 v[96:111], v[186:189], v[190:193], v[96:111]
	v_mfma_f32_32x32x16_bf16 v[112:127], v[186:189], v[194:197], v[112:127]
	ds_read_b128 v[186:189], v139 offset:12288
	s_waitcnt lgkmcnt(3)
	v_mfma_f32_32x32x16_bf16 v[0:15], v[148:151], v[198:201], v[0:15]
	v_mfma_f32_32x32x16_bf16 v[16:31], v[148:151], v[202:205], v[16:31]
	ds_read_b128 v[148:151], v140
	s_waitcnt lgkmcnt(3)
	v_mfma_f32_32x32x16_bf16 v[32:47], v[174:177], v[198:201], v[32:47]
	v_mfma_f32_32x32x16_bf16 v[48:63], v[174:177], v[202:205], v[48:63]
	ds_read_b128 v[174:177], v140 offset:4096
	s_waitcnt lgkmcnt(3)
	v_mfma_f32_32x32x16_bf16 v[64:79], v[182:185], v[198:201], v[64:79]
	v_mfma_f32_32x32x16_bf16 v[80:95], v[182:185], v[202:205], v[80:95]
	ds_read_b128 v[182:185], v140 offset:8192
	s_waitcnt lgkmcnt(3)
	v_mfma_f32_32x32x16_bf16 v[96:111], v[186:189], v[198:201], v[96:111]
	v_mfma_f32_32x32x16_bf16 v[112:127], v[186:189], v[202:205], v[112:127]
	ds_read_b128 v[186:189], v140 offset:12288
	s_waitcnt lgkmcnt(3)
	v_mfma_f32_32x32x16_bf16 v[0:15], v[148:151], v[206:209], v[0:15]
	v_mfma_f32_32x32x16_bf16 v[16:31], v[148:151], v[224:227], v[16:31]
	ds_read_b128 v[148:151], v141
	s_waitcnt lgkmcnt(3)
	v_mfma_f32_32x32x16_bf16 v[32:47], v[174:177], v[206:209], v[32:47]
	v_mfma_f32_32x32x16_bf16 v[48:63], v[174:177], v[224:227], v[48:63]
	ds_read_b128 v[174:177], v141 offset:4096
	s_waitcnt lgkmcnt(3)
	v_mfma_f32_32x32x16_bf16 v[64:79], v[182:185], v[206:209], v[64:79]
	v_mfma_f32_32x32x16_bf16 v[80:95], v[182:185], v[224:227], v[80:95]
	ds_read_b128 v[182:185], v141 offset:8192
	s_waitcnt lgkmcnt(3)
	v_mfma_f32_32x32x16_bf16 v[96:111], v[186:189], v[206:209], v[96:111]
	v_mfma_f32_32x32x16_bf16 v[112:127], v[186:189], v[224:227], v[112:127]
	ds_read_b128 v[186:189], v141 offset:12288
	s_waitcnt lgkmcnt(3)
	v_mfma_f32_32x32x16_bf16 v[0:15], v[148:151], v[228:231], v[0:15]
	v_mfma_f32_32x32x16_bf16 v[16:31], v[148:151], v[232:235], v[16:31]
	s_waitcnt lgkmcnt(2)
	v_mfma_f32_32x32x16_bf16 v[32:47], v[174:177], v[228:231], v[32:47]
	v_mfma_f32_32x32x16_bf16 v[48:63], v[174:177], v[232:235], v[48:63]
	s_waitcnt lgkmcnt(1)
	v_mfma_f32_32x32x16_bf16 v[64:79], v[182:185], v[228:231], v[64:79]
	v_mfma_f32_32x32x16_bf16 v[80:95], v[182:185], v[232:235], v[80:95]
	s_waitcnt lgkmcnt(0)
	v_mfma_f32_32x32x16_bf16 v[96:111], v[186:189], v[228:231], v[96:111]
	v_mfma_f32_32x32x16_bf16 v[112:127], v[186:189], v[232:235], v[112:127]
	v_xor_b32_e32 v138, 0x8000, v138
	v_xor_b32_e32 v139, 0x8000, v139
	v_xor_b32_e32 v140, 0x8000, v140
	v_xor_b32_e32 v141, 0x8000, v141
	s_xor_b32 s21, s21, 0x8000
	s_add_i32 s20, s20, 1
	s_cmp_eq_u32 s20, 16
	s_cbranch_scc0 .Lg_ph17_top
	v_mov_b32_e32 v175, 0x12000
	v_mov_b32_e32 v176, s56
	v_mov_b32_e32 v177, s57
	ds_write_b64 v175, v[176:177]
	s_waitcnt vmcnt(0)
	v_mov_b32_e32 v146, v180
	v_add_u32_e32 v208, 0x400, v157
	v_add_u32_e32 v207, 0x1000, v157
	v_add_u32_e32 v206, 0x1400, v157
	v_add_u32_e32 v205, 0x2000, v157
	v_add_u32_e32 v199, 0x2400, v157
	v_add_u32_e32 v200, 0x3000, v157
	v_add_u32_e32 v201, 0x3200, v157
	v_add_u32_e32 v202, 0x3400, v157
	v_add_u32_e32 v203, 0x3600, v157
	v_add_u32_e32 v204, 0x4000, v157
	v_add_u32_e32 v196, 0x4400, v157
	v_add_u32_e32 v197, 0x4800, v157
	v_add_u32_e32 v198, 0x5000, v157
	v_add_u32_e32 v193, 0x5400, v157
	v_add_u32_e32 v194, 0x5800, v157
	v_add_u32_e32 v195, 0x6000, v157
	v_add_u32_e32 v187, 0x6400, v157
	v_add_u32_e32 v188, 0x6800, v157
	v_add_u32_e32 v189, 0x7200, v157
	v_add_u32_e32 v190, 0x7400, v157
	v_add_u32_e32 v191, 0x7600, v157
	v_add_u32_e32 v192, 0x7800, v157
	v_add_u32_e32 v186, 0x8400, v157
	v_add_u32_e32 v185, 0x8800, v157
	v_add_u32_e32 v184, 0x9400, v157
	v_add_u32_e32 v183, 0x9800, v157
	v_add_u32_e32 v181, 0xa400, v157
	v_add_u32_e32 v174, 0xa800, v157
	v_add_u32_e32 v175, 0xb400, v157
	v_add_u32_e32 v176, 0xb600, v157
	v_add_u32_e32 v177, 0xb800, v157
	v_add_u32_e32 v178, 0xba00, v157
	s_waitcnt vmcnt(0)
	s_barrier
	s_and_saveexec_b64 s[20:21], s[6:7]
	s_cbranch_execz .LBB0_1740
	v_add_u32_e32 v130, 0xc400, v157
	ds_write2_b32 v157, v0, v16 offset1:32
	ds_write2_b32 v157, v1, v17 offset0:132 offset1:164
	ds_write2_b32 v208, v2, v18 offset0:8 offset1:40
	ds_write2_b32 v208, v3, v19 offset0:140 offset1:172
	ds_write2_b32 v207, v4, v20 offset0:32 offset1:64
	ds_write2_b32 v207, v5, v21 offset0:164 offset1:196
	ds_write2_b32 v206, v6, v22 offset0:40 offset1:72
	ds_write2_b32 v206, v7, v23 offset0:172 offset1:204
	ds_write2_b32 v205, v8, v24 offset0:64 offset1:96
	ds_write2_b32 v205, v9, v25 offset0:196 offset1:228
	ds_write2_b32 v199, v10, v26 offset0:72 offset1:104
	ds_write2_b32 v199, v11, v27 offset0:204 offset1:236
	ds_write2_b32 v200, v12, v28 offset0:96 offset1:128
	ds_write2_b32 v201, v13, v29 offset0:100 offset1:132
	ds_write2_b32 v202, v14, v30 offset0:104 offset1:136
	ds_write2_b32 v203, v15, v31 offset0:108 offset1:140
	ds_write2_b32 v204, v32, v48 offset0:128 offset1:160
	ds_write2_b32 v196, v33, v49 offset0:4 offset1:36
	ds_write2_b32 v196, v34, v50 offset0:136 offset1:168
	ds_write2_b32 v197, v35, v51 offset0:12 offset1:44
	ds_write2_b32 v198, v36, v52 offset0:160 offset1:192
	ds_write2_b32 v193, v37, v53 offset0:36 offset1:68
	ds_write2_b32 v193, v38, v54 offset0:168 offset1:200
	ds_write2_b32 v194, v39, v55 offset0:44 offset1:76
	ds_write2_b32 v195, v40, v56 offset0:192 offset1:224
	ds_write2_b32 v187, v41, v57 offset0:68 offset1:100
	ds_write2_b32 v187, v42, v58 offset0:200 offset1:232
	ds_write2_b32 v188, v43, v59 offset0:76 offset1:108
	ds_write2_b32 v189, v44, v60 offset0:96 offset1:128
	ds_write2_b32 v190, v45, v61 offset0:100 offset1:132
	ds_write2_b32 v191, v46, v62 offset0:104 offset1:136
	ds_write2_b32 v192, v47, v63 offset0:108 offset1:140
	ds_write2_b32 v186, v64, v80 offset1:32
	ds_write2_b32 v186, v65, v81 offset0:132 offset1:164
	ds_write2_b32 v185, v66, v82 offset0:8 offset1:40
	ds_write2_b32 v185, v67, v83 offset0:140 offset1:172
	ds_write2_b32 v184, v68, v84 offset0:32 offset1:64
	ds_write2_b32 v184, v69, v85 offset0:164 offset1:196
	ds_write2_b32 v183, v70, v86 offset0:40 offset1:72
	ds_write2_b32 v183, v71, v87 offset0:172 offset1:204
	ds_write2_b32 v181, v72, v88 offset0:64 offset1:96
	ds_write2_b32 v181, v73, v89 offset0:196 offset1:228
	ds_write2_b32 v174, v74, v90 offset0:72 offset1:104
	ds_write2_b32 v174, v75, v91 offset0:204 offset1:236
	ds_write2_b32 v175, v76, v92 offset0:96 offset1:128
	ds_write2_b32 v176, v77, v93 offset0:100 offset1:132
	ds_write2_b32 v177, v78, v94 offset0:104 offset1:136
	ds_write2_b32 v178, v79, v95 offset0:108 offset1:140
	ds_write2_b32 v130, v96, v112 offset0:128 offset1:160
	v_add_u32_e32 v130, 0xc800, v157
	ds_write2_b32 v130, v97, v113 offset0:4 offset1:36
	ds_write2_b32 v130, v98, v114 offset0:136 offset1:168
	v_add_u32_e32 v130, 0xcc00, v157
	ds_write2_b32 v130, v99, v115 offset0:12 offset1:44
	v_add_u32_e32 v130, 0xd400, v157
	ds_write2_b32 v130, v100, v116 offset0:160 offset1:192
	v_add_u32_e32 v130, 0xd800, v157
	ds_write2_b32 v130, v101, v117 offset0:36 offset1:68
	ds_write2_b32 v130, v102, v118 offset0:168 offset1:200
	v_add_u32_e32 v130, 0xdc00, v157
	ds_write2_b32 v130, v103, v119 offset0:44 offset1:76
	v_add_u32_e32 v130, 0xe400, v157
	ds_write2_b32 v130, v104, v120 offset0:192 offset1:224
	v_add_u32_e32 v130, 0xe800, v157
	ds_write2_b32 v130, v105, v121 offset0:68 offset1:100
	ds_write2_b32 v130, v106, v122 offset0:200 offset1:232
	v_add_u32_e32 v130, 0xec00, v157
	ds_write2_b32 v130, v107, v123 offset0:76 offset1:108
	v_add_u32_e32 v130, 0xf600, v157
	ds_write2_b32 v130, v108, v124 offset0:96 offset1:128
	v_add_u32_e32 v130, 0xf800, v157
	ds_write2_b32 v130, v109, v125 offset0:100 offset1:132
	v_add_u32_e32 v130, 0xfa00, v157
	ds_write2_b32 v130, v110, v126 offset0:104 offset1:136
	v_add_u32_e32 v130, 0xfc00, v157
	ds_write2_b32 v130, v111, v127 offset0:108 offset1:140

	.amdhsa_kernel _Z14fwd_megakernel6Params
		.amdhsa_group_segment_fixed_size 8176
		.amdhsa_private_segment_fixed_size 0
		.amdhsa_kernarg_size 464
		.amdhsa_user_sgpr_count 2
		.amdhsa_user_sgpr_dispatch_ptr 0
		.amdhsa_user_sgpr_queue_ptr 0
		.amdhsa_user_sgpr_kernarg_segment_ptr 1
		.amdhsa_user_sgpr_dispatch_id 0
		.amdhsa_user_sgpr_kernarg_preload_length 0
		.amdhsa_user_sgpr_kernarg_preload_offset 0
		.amdhsa_user_sgpr_private_segment_size 0
		.amdhsa_uses_dynamic_stack 0
		.amdhsa_enable_private_segment 0
		.amdhsa_system_sgpr_workgroup_id_x 1
		.amdhsa_system_sgpr_workgroup_id_y 0
		.amdhsa_system_sgpr_workgroup_id_z 0
		.amdhsa_system_sgpr_workgroup_info 0
		.amdhsa_system_vgpr_workitem_id 2
		.amdhsa_next_free_vgpr 256
		.amdhsa_next_free_sgpr 98
		.amdhsa_accum_offset 256
		.amdhsa_reserve_vcc 1
		.amdhsa_float_round_mode_32 0
		.amdhsa_float_round_mode_16_64 0
		.amdhsa_float_denorm_mode_32 3
		.amdhsa_float_denorm_mode_16_64 3
		.amdhsa_dx10_clamp 1
		.amdhsa_ieee_mode 1
		.amdhsa_fp16_overflow 0
		.amdhsa_tg_split 0
		.amdhsa_exception_fp_ieee_invalid_op 0
		.amdhsa_exception_fp_denorm_src 0
		.amdhsa_exception_fp_ieee_div_zero 0
		.amdhsa_exception_fp_ieee_overflow 0
		.amdhsa_exception_fp_ieee_underflow 0
		.amdhsa_exception_fp_ieee_inexact 0
		.amdhsa_exception_int_div_zero 0
	.end_amdhsa_kernel

amdhsa.kernels:
  - .agpr_count:     0
    .args:
      - .offset:         0
        .size:           208
        .value_kind:     by_value
      - .offset:         208
        .size:           4
        .value_kind:     hidden_block_count_x
      - .offset:         212
        .size:           4
        .value_kind:     hidden_block_count_y
      - .offset:         216
        .size:           4
        .value_kind:     hidden_block_count_z
      - .offset:         220
        .size:           2
        .value_kind:     hidden_group_size_x
      - .offset:         222
        .size:           2
        .value_kind:     hidden_group_size_y
      - .offset:         224
        .size:           2
        .value_kind:     hidden_group_size_z
      - .offset:         226
        .size:           2
        .value_kind:     hidden_remainder_x
      - .offset:         228
        .size:           2
        .value_kind:     hidden_remainder_y
      - .offset:         230
        .size:           2
        .value_kind:     hidden_remainder_z
      - .offset:         248
        .size:           8
        .value_kind:     hidden_global_offset_x
      - .offset:         256
        .size:           8
        .value_kind:     hidden_global_offset_y
      - .offset:         264
        .size:           8
        .value_kind:     hidden_global_offset_z
      - .offset:         272
        .size:           2
        .value_kind:     hidden_grid_dims
      - .offset:         296
        .size:           8
        .value_kind:     hidden_multigrid_sync_arg
      - .offset:         328
        .size:           4
        .value_kind:     hidden_dynamic_lds_size
    .group_segment_fixed_size: 8176
    .kernarg_segment_align: 8
    .kernarg_segment_size: 464
    .language:       OpenCL C
    .language_version:
      - 2
      - 0
    .max_flat_workgroup_size: 256
    .name:           _Z14fwd_megakernel6Params
    .private_segment_fixed_size: 0
    .sgpr_count:     104
    .sgpr_spill_count: 48
    .symbol:         _Z14fwd_megakernel6Params.kd
    .uniform_work_group_size: 1
    .uses_dynamic_stack: false
    .vgpr_count:     256
    .vgpr_spill_count: 0
    .wavefront_size: 64
